# RWKV scan phase with specialised waves: waves 0-3 scan, waves 4-7 prepare the next half-chunk tables concurrently into a second LDS buffer; table row pitch padded to 272 B (conflict-free writes)
# speedup vs baseline: 1.0886x; 1.0510x over previous
; __device__ __forceinline__ void phase_rwkv_scan(const Fr& F, int jr) {
;     ...
;     const int lane = F.lane, wave = F.wave, tid = F.tid, l15 = lane & 15, lq = lane >> 4;
;     const int bxs = (int)blockIdx.x, bxcd = (gridDim.x == 256) ? (bxs & 7) * 32 + (bxs >> 3) : bxs;
;     for (int task = bxcd; task < 256; task += gridDim.x) {
;         const int half = task & 1, h = (task >> 1) & 15, b = (task >> 5) & 3, s = task >> 7;
;         bf16* Yb = F.R(s);
;         const float* w0 = F.a->in[9] + (size_t)(jr * 2 + s) * D + h * 64; const float* a0 = F.a->in[12] + (size_t)(jr * 2 + s) * D + h * 64;
;         const float* kkw = F.a->in[15] + (size_t)jr * D + h * 64; const float* kaw = F.a->in[16] + (size_t)jr * D + h * 64;
;         f32x2 S01 = {0.f, 0.f}, S23 = {0.f, 0.f};
;         const int ks = 4 * l15, rloc = 4 * wave + lq;
;     ...
;             {
;                 float* Ypw = Yp + wave * 1024;
;                 unsigned a1 = (unsigned)(size_t)(__attribute__((address_space(3))) float*)(Wv + ks), a2 = (unsigned)(size_t)(__attribute__((address_space(3))) float*)(Rr + ks),
;                          a3 = (unsigned)(size_t)(__attribute__((address_space(3))) float*)(Vv + rloc), a4 = (unsigned)(size_t)(__attribute__((address_space(3))) float*)(Ypw + lane);
;                 asm volatile("" : "+v"(a1), "+v"(a2), "+v"(a3), "+v"(a4));
;                 typedef const __attribute__((address_space(3))) f32x4* lp4; typedef const __attribute__((address_space(3))) float* lp1; typedef __attribute__((address_space(3))) float* lw1;
;                 const lp4 PW = (lp4)a1, PR = (lp4)a2; const lp1 PV = (lp1)a3; const lw1 PY = (lw1)a4;
;                 f32x4 w4 = PW[0], k4 = PW[1024], b4 = PW[2048], d4 = PW[3072], r4 = PR[0];
;                 float vv = PV[0];
;                 for (int pg = 0; pg < 64; pg += 16) {
; #pragma unroll
;                     for (int pi = 0; pi < 16; ++pi) {
;                         const int p = pg + pi, pn = p < 63 ? p + 1 : 63;
;                         const f32x4 w4n = PW[pn * 16], k4n = PW[1024 + pn * 16], b4n = PW[2048 + pn * 16], d4n = PW[3072 + pn * 16], r4n = PR[pn * 16];
;                         const float vvn = PV[pn * 32];
;                         f32x2 t = S01 * k4.xy; t = S23 * k4.zw + t; float sa = t.x + t.y;
;                         sa += dppf<0x128>(sa);
;                         const f32x2 dv01 = d4.xy * vv, dv23 = d4.zw * vv;
.LBB0_552:
	s_or_b64 exec, exec, s[6:7]
	v_cmp_gt_i32_e32 vcc, 6, v1
	v_cmp_lt_i32_e64 s[6:7], 5, v2
	s_and_b64 s[6:7], vcc, s[6:7]
	s_and_saveexec_b64 s[12:13], s[6:7]
	s_cbranch_execz .LBB0_565
	s_and_b32 s3, s2, 7
	s_lshl_b32 s3, s3, 5
	s_lshr_b32 s6, s2, 3
	s_add_i32 s3, s3, s6
	s_lshr_b32 s6, s3, 7
	s_bfe_u32 s7, s3, 0x20005
	s_bfe_u32 s8, s3, 0x40001
	s_and_b32 s9, s3, 1
	s_cmp_gt_u32 s68, 3
	s_cbranch_scc1 .Lrw0_helper
	s_setprio 3
	v_mov_b32_e32 v206, 0
	v_mov_b32_e32 v207, 0
	v_mov_b32_e32 v208, 0
	v_mov_b32_e32 v209, 0
	v_mov_b32_e32 v210, 0
	v_mov_b32_e32 v211, 0
	v_mov_b32_e32 v212, 0
	v_mov_b32_e32 v213, 0
	v_and_b32_e32 v243, 15, v130
	v_lshlrev_b32_e32 v214, 4, v243
	v_lshrrev_b32_e32 v244, 4, v130
	v_lshrrev_b32_e32 v245, 3, v243
	v_lshl_add_u32 v245, v244, 1, v245
	s_lshl_b32 s16, s68, 3
	v_add_u32_e32 v245, s16, v245
	v_lshlrev_b32_e32 v216, 3, v245
	s_mul_i32 s16, s68, 0x2400
	s_add_i32 s16, s16, 0x19800
	s_cmp_eq_u32 s68, 3
	s_cselect_b32 s16, 0x20800, s16
	v_mul_u32_u24_e32 v218, 0x90, v130
	v_add_u32_e32 v218, s16, v218
	v_mul_u32_u24_e32 v244, 0x90, v244
	v_lshl_add_u32 v244, v243, 3, v244
	v_add_u32_e32 v217, s16, v244
	v_lshrrev_b32_e32 v219, 2, v130
	s_cmp_eq_u32 s6, 0
	s_cbranch_scc1 .Lrw0_sdir0
	v_sub_u32_e32 v219, 0, v219
.Lrw0_sdir0:
	v_and_b32_e32 v243, 3, v130
	s_lshl_b32 s16, s68, 4
	v_lshl_add_u32 v220, v243, 2, s16
	s_mul_i32 s16, s6, 0x2200000
	s_add_u32 s20, s26, s16
	s_addc_u32 s21, s27, 0
	s_add_u32 s20, s20, 0x1200000
	s_addc_u32 s21, s21, 0
	s_mul_i32 s16, s7, 0x880000
	s_add_u32 s20, s20, s16
	s_addc_u32 s21, s21, 0
	s_and_b32 s16, s3, 31
	s_lshl_b32 s16, s16, 6
	s_add_u32 s20, s20, s16
	s_addc_u32 s21, s21, 0
	s_mov_b32 s10, 0
	s_mov_b32 s11, 0
	s_waitcnt lgkmcnt(0)
	s_barrier
.Lrw0_shc:
	v_add_u32_e32 v240, s11, v214
	v_add_u32_e32 v242, s11, v216
	ds_read_b128 v[84:87], v240 offset:8704
	ds_read_b64 v[100:101], v242 offset:43520
	ds_read_b128 v[92:95], v240 offset:26112
	ds_read_b128 v[80:83], v240 offset:0
	ds_read_b128 v[88:91], v240 offset:17408
	ds_read_b128 v[96:99], v240 offset:34816
	s_lshl_b32 s17, s10, 5
	s_cmp_lt_u32 s10, 8
	s_movk_i32 s18, 0x11ff
	s_cselect_b32 s18, 0xff, s18
	s_sub_i32 s18, s18, s17
	s_cmp_eq_u32 s6, 0
	s_cselect_b32 s15, s17, s18
	s_cselect_b32 s19, 16, -16
	s_waitcnt lgkmcnt(0)
	ds_read_b128 v[106:109], v240 offset:8976
	ds_read_b64 v[118:119], v242 offset:43792
	ds_read_b128 v[114:117], v240 offset:26384
	ds_read_b128 v[102:105], v240 offset:272
	ds_read_b128 v[110:113], v240 offset:17680
	v_pk_mul_f32 v[226:227], v[206:207], v[84:85] op_sel_hi:[1,0]
	v_pk_mul_f32 v[232:233], v[100:101], v[92:93] op_sel_hi:[1,0]
	v_pk_fma_f32 v[226:227], v[208:209], v[84:85], v[226:227] op_sel:[0,1,0]
	v_pk_mul_f32 v[234:235], v[100:101], v[92:93] op_sel:[0,1]
	v_pk_fma_f32 v[226:227], v[210:211], v[86:87], v[226:227] op_sel_hi:[1,0,1]
	v_pk_mul_f32 v[236:237], v[100:101], v[94:95] op_sel_hi:[1,0]
	v_pk_fma_f32 v[226:227], v[212:213], v[86:87], v[226:227] op_sel:[0,1,0]
	v_pk_mul_f32 v[238:239], v[100:101], v[94:95] op_sel:[0,1]
	s_nop 0
	v_add_f32_dpp v230, v227, v226 row_ror:8 row_mask:0xf bank_mask:0xf
	v_pk_fma_f32 v[232:233], v[206:207], v[80:81], v[232:233] op_sel_hi:[1,0,1]
	v_pk_fma_f32 v[234:235], v[208:209], v[80:81], v[234:235] op_sel:[0,1,0]
	v_add_f32_dpp v230, v230, v230 quad_perm:[1,0,3,2] row_mask:0xf bank_mask:0xf
	v_pk_fma_f32 v[236:237], v[210:211], v[82:83], v[236:237] op_sel_hi:[1,0,1]
	v_pk_fma_f32 v[238:239], v[212:213], v[82:83], v[238:239] op_sel:[0,1,0]
	v_add_f32_dpp v230, v230, v230 quad_perm:[2,3,0,1] row_mask:0xf bank_mask:0xf
	ds_read_b128 v[222:225], v240 offset:35088
	s_nop 0
	v_add_f32_dpp v230, v230, v230 row_half_mirror row_mask:0xf bank_mask:0xf
	s_nop 1
	v_mov_b32_dpp v231, v230 row_ror:8 row_mask:0xf bank_mask:0xf
	s_nop 0
	v_pk_fma_f32 v[206:207], v[88:89], v[230:231], v[232:233] op_sel_hi:[0,1,1] neg_lo:[1,0,0] neg_hi:[1,0,0]
	v_pk_fma_f32 v[208:209], v[88:89], v[230:231], v[234:235] op_sel:[1,0,0] neg_lo:[1,0,0] neg_hi:[1,0,0]
	v_pk_fma_f32 v[210:211], v[90:91], v[230:231], v[236:237] op_sel_hi:[0,1,1] neg_lo:[1,0,0] neg_hi:[1,0,0]
	v_pk_fma_f32 v[212:213], v[90:91], v[230:231], v[238:239] op_sel:[1,0,0] neg_lo:[1,0,0] neg_hi:[1,0,0]
	ds_read_b128 v[84:87], v240 offset:9248
	ds_read_b64 v[100:101], v242 offset:44064
	ds_read_b128 v[92:95], v240 offset:26656
	ds_read_b128 v[80:83], v240 offset:544
	ds_read_b128 v[88:91], v240 offset:17952
	s_waitcnt lgkmcnt(6)
	v_pk_mul_f32 v[226:227], v[206:207], v[106:107] op_sel_hi:[1,0]
	v_pk_mul_f32 v[228:229], v[206:207], v[96:97] op_sel_hi:[1,0]
	v_pk_fma_f32 v[226:227], v[208:209], v[106:107], v[226:227] op_sel:[0,1,0]
	v_pk_fma_f32 v[228:229], v[208:209], v[96:97], v[228:229] op_sel:[0,1,0]
	v_pk_fma_f32 v[226:227], v[210:211], v[108:109], v[226:227] op_sel_hi:[1,0,1]
	v_pk_fma_f32 v[228:229], v[210:211], v[98:99], v[228:229] op_sel_hi:[1,0,1]
	v_pk_fma_f32 v[226:227], v[212:213], v[108:109], v[226:227] op_sel:[0,1,0]
	v_pk_fma_f32 v[228:229], v[212:213], v[98:99], v[228:229] op_sel:[0,1,0]
	v_pk_mul_f32 v[232:233], v[118:119], v[114:115] op_sel_hi:[1,0]
	v_add_f32_dpp v230, v227, v226 row_ror:8 row_mask:0xf bank_mask:0xf
	v_pk_mul_f32 v[234:235], v[118:119], v[114:115] op_sel:[0,1]
	v_pk_mul_f32 v[236:237], v[118:119], v[116:117] op_sel_hi:[1,0]
	v_add_f32_dpp v230, v230, v230 quad_perm:[1,0,3,2] row_mask:0xf bank_mask:0xf
	v_pk_mul_f32 v[238:239], v[118:119], v[116:117] op_sel:[0,1]
	ds_read_b128 v[96:99], v240 offset:35360
	v_add_f32_dpp v230, v230, v230 quad_perm:[2,3,0,1] row_mask:0xf bank_mask:0xf
	v_pk_fma_f32 v[232:233], v[206:207], v[102:103], v[232:233] op_sel_hi:[1,0,1]
	v_pk_fma_f32 v[234:235], v[208:209], v[102:103], v[234:235] op_sel:[0,1,0]
	v_add_f32_dpp v230, v230, v230 row_half_mirror row_mask:0xf bank_mask:0xf
	v_pk_fma_f32 v[236:237], v[210:211], v[104:105], v[236:237] op_sel_hi:[1,0,1]
	v_pk_fma_f32 v[238:239], v[212:213], v[104:105], v[238:239] op_sel:[0,1,0]
	v_mov_b32_dpp v231, v230 row_ror:8 row_mask:0xf bank_mask:0xf
	ds_write_b64 v217, v[228:229] offset:0
	v_pk_fma_f32 v[206:207], v[110:111], v[230:231], v[232:233] op_sel_hi:[0,1,1] neg_lo:[1,0,0] neg_hi:[1,0,0]
	v_pk_fma_f32 v[208:209], v[110:111], v[230:231], v[234:235] op_sel:[1,0,0] neg_lo:[1,0,0] neg_hi:[1,0,0]
	v_pk_fma_f32 v[210:211], v[112:113], v[230:231], v[236:237] op_sel_hi:[0,1,1] neg_lo:[1,0,0] neg_hi:[1,0,0]
	v_pk_fma_f32 v[212:213], v[112:113], v[230:231], v[238:239] op_sel:[1,0,0] neg_lo:[1,0,0] neg_hi:[1,0,0]
	ds_read_b128 v[106:109], v240 offset:9520
	ds_read_b64 v[118:119], v242 offset:44336
	ds_read_b128 v[114:117], v240 offset:26928
	ds_read_b128 v[102:105], v240 offset:816
	ds_read_b128 v[110:113], v240 offset:18224
	s_waitcnt lgkmcnt(7)
; template <int CTRL> __device__ __forceinline__ float dppf(float x) { return __builtin_bit_cast(float, __builtin_amdgcn_update_dpp(0, __builtin_bit_cast(int, x), CTRL, 0xF, 0xF, false)); }
; __device__ __forceinline__ void phase_rwkv_scan(const Fr& F, int jr) {
;     ...
;                 for (int pg = 0; pg < 64; pg += 16) {
; #pragma unroll
;                     for (int pi = 0; pi < 16; ++pi) {
;                         const int p = pg + pi, pn = p < 63 ? p + 1 : 63;
;                         const f32x4 w4n = PW[pn * 16], k4n = PW[1024 + pn * 16], b4n = PW[2048 + pn * 16], d4n = PW[3072 + pn * 16], r4n = PR[pn * 16];
;                         const float vvn = PV[pn * 32];
;                         f32x2 t = S01 * k4.xy; t = S23 * k4.zw + t; float sa = t.x + t.y;
;                         sa += dppf<0x128>(sa);
;                         const f32x2 dv01 = d4.xy * vv, dv23 = d4.zw * vv;
;                         sa += dppf<0x124>(sa);
;                         const f32x2 e01 = S01 * w4.xy + dv01;
;                         sa += dppf<0x122>(sa);
;                         const f32x2 e23 = S23 * w4.zw + dv23;
;                         sa += dppf<0x121>(sa);
;                         S01 = e01 - b4.xy * sa; S23 = e23 - b4.zw * sa;
;                         f32x2 u = S01 * r4.xy; u = S23 * r4.zw + u;
;                         PY[pi * 64] = u.x + u.y;
;                         w4 = w4n; k4 = k4n; b4 = b4n; d4 = d4n; r4 = r4n; vv = vvn;
	v_pk_mul_f32 v[226:227], v[206:207], v[84:85] op_sel_hi:[1,0]
	v_pk_mul_f32 v[228:229], v[206:207], v[222:223] op_sel_hi:[1,0]
	v_pk_fma_f32 v[226:227], v[208:209], v[84:85], v[226:227] op_sel:[0,1,0]
	v_pk_fma_f32 v[228:229], v[208:209], v[222:223], v[228:229] op_sel:[0,1,0]
	v_pk_fma_f32 v[226:227], v[210:211], v[86:87], v[226:227] op_sel_hi:[1,0,1]
	v_pk_fma_f32 v[228:229], v[210:211], v[224:225], v[228:229] op_sel_hi:[1,0,1]
	v_pk_fma_f32 v[226:227], v[212:213], v[86:87], v[226:227] op_sel:[0,1,0]
	v_pk_fma_f32 v[228:229], v[212:213], v[224:225], v[228:229] op_sel:[0,1,0]
	v_pk_mul_f32 v[232:233], v[100:101], v[92:93] op_sel_hi:[1,0]
	v_add_f32_dpp v230, v227, v226 row_ror:8 row_mask:0xf bank_mask:0xf
	v_pk_mul_f32 v[234:235], v[100:101], v[92:93] op_sel:[0,1]
	v_pk_mul_f32 v[236:237], v[100:101], v[94:95] op_sel_hi:[1,0]
	v_add_f32_dpp v230, v230, v230 quad_perm:[1,0,3,2] row_mask:0xf bank_mask:0xf
	v_pk_mul_f32 v[238:239], v[100:101], v[94:95] op_sel:[0,1]
	ds_read_b128 v[222:225], v240 offset:35632
	v_add_f32_dpp v230, v230, v230 quad_perm:[2,3,0,1] row_mask:0xf bank_mask:0xf
	v_pk_fma_f32 v[232:233], v[206:207], v[80:81], v[232:233] op_sel_hi:[1,0,1]
	v_pk_fma_f32 v[234:235], v[208:209], v[80:81], v[234:235] op_sel:[0,1,0]
	v_add_f32_dpp v230, v230, v230 row_half_mirror row_mask:0xf bank_mask:0xf
	v_pk_fma_f32 v[236:237], v[210:211], v[82:83], v[236:237] op_sel_hi:[1,0,1]
	v_pk_fma_f32 v[238:239], v[212:213], v[82:83], v[238:239] op_sel:[0,1,0]
	v_mov_b32_dpp v231, v230 row_ror:8 row_mask:0xf bank_mask:0xf
	ds_write_b64 v217, v[228:229] offset:576
	v_pk_fma_f32 v[206:207], v[88:89], v[230:231], v[232:233] op_sel_hi:[0,1,1] neg_lo:[1,0,0] neg_hi:[1,0,0]
	v_pk_fma_f32 v[208:209], v[88:89], v[230:231], v[234:235] op_sel:[1,0,0] neg_lo:[1,0,0] neg_hi:[1,0,0]
	v_pk_fma_f32 v[210:211], v[90:91], v[230:231], v[236:237] op_sel_hi:[0,1,1] neg_lo:[1,0,0] neg_hi:[1,0,0]
	v_pk_fma_f32 v[212:213], v[90:91], v[230:231], v[238:239] op_sel:[1,0,0] neg_lo:[1,0,0] neg_hi:[1,0,0]
	ds_read_b128 v[84:87], v240 offset:9792
	ds_read_b64 v[100:101], v242 offset:44608
	ds_read_b128 v[92:95], v240 offset:27200
	ds_read_b128 v[80:83], v240 offset:1088
	ds_read_b128 v[88:91], v240 offset:18496
	s_waitcnt lgkmcnt(7)
	v_pk_mul_f32 v[226:227], v[206:207], v[106:107] op_sel_hi:[1,0]
	v_pk_mul_f32 v[228:229], v[206:207], v[96:97] op_sel_hi:[1,0]
	v_pk_fma_f32 v[226:227], v[208:209], v[106:107], v[226:227] op_sel:[0,1,0]
	v_pk_fma_f32 v[228:229], v[208:209], v[96:97], v[228:229] op_sel:[0,1,0]
	v_pk_fma_f32 v[226:227], v[210:211], v[108:109], v[226:227] op_sel_hi:[1,0,1]
	v_pk_fma_f32 v[228:229], v[210:211], v[98:99], v[228:229] op_sel_hi:[1,0,1]
	v_pk_fma_f32 v[226:227], v[212:213], v[108:109], v[226:227] op_sel:[0,1,0]
	v_pk_fma_f32 v[228:229], v[212:213], v[98:99], v[228:229] op_sel:[0,1,0]
	v_pk_mul_f32 v[232:233], v[118:119], v[114:115] op_sel_hi:[1,0]
	v_add_f32_dpp v230, v227, v226 row_ror:8 row_mask:0xf bank_mask:0xf
	v_pk_mul_f32 v[234:235], v[118:119], v[114:115] op_sel:[0,1]
	v_pk_mul_f32 v[236:237], v[118:119], v[116:117] op_sel_hi:[1,0]
	v_add_f32_dpp v230, v230, v230 quad_perm:[1,0,3,2] row_mask:0xf bank_mask:0xf
	v_pk_mul_f32 v[238:239], v[118:119], v[116:117] op_sel:[0,1]
	ds_read_b128 v[96:99], v240 offset:35904
	v_add_f32_dpp v230, v230, v230 quad_perm:[2,3,0,1] row_mask:0xf bank_mask:0xf
	v_pk_fma_f32 v[232:233], v[206:207], v[102:103], v[232:233] op_sel_hi:[1,0,1]
	v_pk_fma_f32 v[234:235], v[208:209], v[102:103], v[234:235] op_sel:[0,1,0]
	v_add_f32_dpp v230, v230, v230 row_half_mirror row_mask:0xf bank_mask:0xf
	v_pk_fma_f32 v[236:237], v[210:211], v[104:105], v[236:237] op_sel_hi:[1,0,1]
	v_pk_fma_f32 v[238:239], v[212:213], v[104:105], v[238:239] op_sel:[0,1,0]
	v_mov_b32_dpp v231, v230 row_ror:8 row_mask:0xf bank_mask:0xf
	ds_write_b64 v217, v[228:229] offset:1152
	v_pk_fma_f32 v[206:207], v[110:111], v[230:231], v[232:233] op_sel_hi:[0,1,1] neg_lo:[1,0,0] neg_hi:[1,0,0]
	v_pk_fma_f32 v[208:209], v[110:111], v[230:231], v[234:235] op_sel:[1,0,0] neg_lo:[1,0,0] neg_hi:[1,0,0]
	v_pk_fma_f32 v[210:211], v[112:113], v[230:231], v[236:237] op_sel_hi:[0,1,1] neg_lo:[1,0,0] neg_hi:[1,0,0]
	v_pk_fma_f32 v[212:213], v[112:113], v[230:231], v[238:239] op_sel:[1,0,0] neg_lo:[1,0,0] neg_hi:[1,0,0]
	ds_read_b128 v[106:109], v240 offset:10064
	ds_read_b64 v[118:119], v242 offset:44880
	ds_read_b128 v[114:117], v240 offset:27472
	ds_read_b128 v[102:105], v240 offset:1360
	ds_read_b128 v[110:113], v240 offset:18768
	s_waitcnt lgkmcnt(7)
	v_pk_mul_f32 v[226:227], v[206:207], v[84:85] op_sel_hi:[1,0]
	v_pk_mul_f32 v[228:229], v[206:207], v[222:223] op_sel_hi:[1,0]
	v_pk_fma_f32 v[226:227], v[208:209], v[84:85], v[226:227] op_sel:[0,1,0]
	v_pk_fma_f32 v[228:229], v[208:209], v[222:223], v[228:229] op_sel:[0,1,0]
	v_pk_fma_f32 v[226:227], v[210:211], v[86:87], v[226:227] op_sel_hi:[1,0,1]
	v_pk_fma_f32 v[228:229], v[210:211], v[224:225], v[228:229] op_sel_hi:[1,0,1]
	v_pk_fma_f32 v[226:227], v[212:213], v[86:87], v[226:227] op_sel:[0,1,0]
	v_pk_fma_f32 v[228:229], v[212:213], v[224:225], v[228:229] op_sel:[0,1,0]
	v_pk_mul_f32 v[232:233], v[100:101], v[92:93] op_sel_hi:[1,0]
	v_add_f32_dpp v230, v227, v226 row_ror:8 row_mask:0xf bank_mask:0xf
	v_pk_mul_f32 v[234:235], v[100:101], v[92:93] op_sel:[0,1]
	v_pk_mul_f32 v[236:237], v[100:101], v[94:95] op_sel_hi:[1,0]
	v_add_f32_dpp v230, v230, v230 quad_perm:[1,0,3,2] row_mask:0xf bank_mask:0xf
	v_pk_mul_f32 v[238:239], v[100:101], v[94:95] op_sel:[0,1]
	ds_read_b128 v[222:225], v240 offset:36176
	v_add_f32_dpp v230, v230, v230 quad_perm:[2,3,0,1] row_mask:0xf bank_mask:0xf
	v_pk_fma_f32 v[232:233], v[206:207], v[80:81], v[232:233] op_sel_hi:[1,0,1]
	v_pk_fma_f32 v[234:235], v[208:209], v[80:81], v[234:235] op_sel:[0,1,0]
	v_add_f32_dpp v230, v230, v230 row_half_mirror row_mask:0xf bank_mask:0xf
	v_pk_fma_f32 v[236:237], v[210:211], v[82:83], v[236:237] op_sel_hi:[1,0,1]
	v_pk_fma_f32 v[238:239], v[212:213], v[82:83], v[238:239] op_sel:[0,1,0]
	v_mov_b32_dpp v231, v230 row_ror:8 row_mask:0xf bank_mask:0xf
	ds_write_b64 v217, v[228:229] offset:1728
	v_pk_fma_f32 v[206:207], v[88:89], v[230:231], v[232:233] op_sel_hi:[0,1,1] neg_lo:[1,0,0] neg_hi:[1,0,0]
	v_pk_fma_f32 v[208:209], v[88:89], v[230:231], v[234:235] op_sel:[1,0,0] neg_lo:[1,0,0] neg_hi:[1,0,0]
	v_pk_fma_f32 v[210:211], v[90:91], v[230:231], v[236:237] op_sel_hi:[0,1,1] neg_lo:[1,0,0] neg_hi:[1,0,0]
	v_pk_fma_f32 v[212:213], v[90:91], v[230:231], v[238:239] op_sel:[1,0,0] neg_lo:[1,0,0] neg_hi:[1,0,0]
	ds_read_b128 v[84:87], v240 offset:10336
	ds_read_b64 v[100:101], v242 offset:45152
	ds_read_b128 v[92:95], v240 offset:27744
	ds_read_b128 v[80:83], v240 offset:1632
	ds_read_b128 v[88:91], v240 offset:19040
	s_waitcnt lgkmcnt(7)
; template <int CTRL> __device__ __forceinline__ float dppf(float x) { return __builtin_bit_cast(float, __builtin_amdgcn_update_dpp(0, __builtin_bit_cast(int, x), CTRL, 0xF, 0xF, false)); }
; __device__ __forceinline__ void phase_rwkv_scan(const Fr& F, int jr) {
;     ...
;                 for (int pg = 0; pg < 64; pg += 16) {
; #pragma unroll
;                     for (int pi = 0; pi < 16; ++pi) {
;                         const int p = pg + pi, pn = p < 63 ? p + 1 : 63;
;                         const f32x4 w4n = PW[pn * 16], k4n = PW[1024 + pn * 16], b4n = PW[2048 + pn * 16], d4n = PW[3072 + pn * 16], r4n = PR[pn * 16];
;                         const float vvn = PV[pn * 32];
;                         f32x2 t = S01 * k4.xy; t = S23 * k4.zw + t; float sa = t.x + t.y;
;                         sa += dppf<0x128>(sa);
;                         const f32x2 dv01 = d4.xy * vv, dv23 = d4.zw * vv;
;                         sa += dppf<0x124>(sa);
;                         const f32x2 e01 = S01 * w4.xy + dv01;
;                         sa += dppf<0x122>(sa);
;                         const f32x2 e23 = S23 * w4.zw + dv23;
;                         sa += dppf<0x121>(sa);
;                         S01 = e01 - b4.xy * sa; S23 = e23 - b4.zw * sa;
;                         f32x2 u = S01 * r4.xy; u = S23 * r4.zw + u;
;                         PY[pi * 64] = u.x + u.y;
;                         w4 = w4n; k4 = k4n; b4 = b4n; d4 = d4n; r4 = r4n; vv = vvn;
	v_pk_mul_f32 v[226:227], v[206:207], v[106:107] op_sel_hi:[1,0]
	v_pk_mul_f32 v[228:229], v[206:207], v[96:97] op_sel_hi:[1,0]
	v_pk_fma_f32 v[226:227], v[208:209], v[106:107], v[226:227] op_sel:[0,1,0]
	v_pk_fma_f32 v[228:229], v[208:209], v[96:97], v[228:229] op_sel:[0,1,0]
	v_pk_fma_f32 v[226:227], v[210:211], v[108:109], v[226:227] op_sel_hi:[1,0,1]
	v_pk_fma_f32 v[228:229], v[210:211], v[98:99], v[228:229] op_sel_hi:[1,0,1]
	v_pk_fma_f32 v[226:227], v[212:213], v[108:109], v[226:227] op_sel:[0,1,0]
	v_pk_fma_f32 v[228:229], v[212:213], v[98:99], v[228:229] op_sel:[0,1,0]
	v_pk_mul_f32 v[232:233], v[118:119], v[114:115] op_sel_hi:[1,0]
	v_add_f32_dpp v230, v227, v226 row_ror:8 row_mask:0xf bank_mask:0xf
	v_pk_mul_f32 v[234:235], v[118:119], v[114:115] op_sel:[0,1]
	v_pk_mul_f32 v[236:237], v[118:119], v[116:117] op_sel_hi:[1,0]
	v_add_f32_dpp v230, v230, v230 quad_perm:[1,0,3,2] row_mask:0xf bank_mask:0xf
	v_pk_mul_f32 v[238:239], v[118:119], v[116:117] op_sel:[0,1]
	ds_read_b128 v[96:99], v240 offset:36448
	v_add_f32_dpp v230, v230, v230 quad_perm:[2,3,0,1] row_mask:0xf bank_mask:0xf
	v_pk_fma_f32 v[232:233], v[206:207], v[102:103], v[232:233] op_sel_hi:[1,0,1]
	v_pk_fma_f32 v[234:235], v[208:209], v[102:103], v[234:235] op_sel:[0,1,0]
	v_add_f32_dpp v230, v230, v230 row_half_mirror row_mask:0xf bank_mask:0xf
	v_pk_fma_f32 v[236:237], v[210:211], v[104:105], v[236:237] op_sel_hi:[1,0,1]
	v_pk_fma_f32 v[238:239], v[212:213], v[104:105], v[238:239] op_sel:[0,1,0]
	v_mov_b32_dpp v231, v230 row_ror:8 row_mask:0xf bank_mask:0xf
	ds_write_b64 v217, v[228:229] offset:2304
	v_pk_fma_f32 v[206:207], v[110:111], v[230:231], v[232:233] op_sel_hi:[0,1,1] neg_lo:[1,0,0] neg_hi:[1,0,0]
	v_pk_fma_f32 v[208:209], v[110:111], v[230:231], v[234:235] op_sel:[1,0,0] neg_lo:[1,0,0] neg_hi:[1,0,0]
	v_pk_fma_f32 v[210:211], v[112:113], v[230:231], v[236:237] op_sel_hi:[0,1,1] neg_lo:[1,0,0] neg_hi:[1,0,0]
	v_pk_fma_f32 v[212:213], v[112:113], v[230:231], v[238:239] op_sel:[1,0,0] neg_lo:[1,0,0] neg_hi:[1,0,0]
	ds_read_b128 v[106:109], v240 offset:10608
	ds_read_b64 v[118:119], v242 offset:45424
	ds_read_b128 v[114:117], v240 offset:28016
	ds_read_b128 v[102:105], v240 offset:1904
	ds_read_b128 v[110:113], v240 offset:19312
	s_waitcnt lgkmcnt(7)
	v_pk_mul_f32 v[226:227], v[206:207], v[84:85] op_sel_hi:[1,0]
	v_pk_mul_f32 v[228:229], v[206:207], v[222:223] op_sel_hi:[1,0]
	v_pk_fma_f32 v[226:227], v[208:209], v[84:85], v[226:227] op_sel:[0,1,0]
	v_pk_fma_f32 v[228:229], v[208:209], v[222:223], v[228:229] op_sel:[0,1,0]
	v_pk_fma_f32 v[226:227], v[210:211], v[86:87], v[226:227] op_sel_hi:[1,0,1]
	v_pk_fma_f32 v[228:229], v[210:211], v[224:225], v[228:229] op_sel_hi:[1,0,1]
	v_pk_fma_f32 v[226:227], v[212:213], v[86:87], v[226:227] op_sel:[0,1,0]
	v_pk_fma_f32 v[228:229], v[212:213], v[224:225], v[228:229] op_sel:[0,1,0]
	v_pk_mul_f32 v[232:233], v[100:101], v[92:93] op_sel_hi:[1,0]
	v_add_f32_dpp v230, v227, v226 row_ror:8 row_mask:0xf bank_mask:0xf
	v_pk_mul_f32 v[234:235], v[100:101], v[92:93] op_sel:[0,1]
	v_pk_mul_f32 v[236:237], v[100:101], v[94:95] op_sel_hi:[1,0]
	v_add_f32_dpp v230, v230, v230 quad_perm:[1,0,3,2] row_mask:0xf bank_mask:0xf
	v_pk_mul_f32 v[238:239], v[100:101], v[94:95] op_sel:[0,1]
	ds_read_b128 v[222:225], v240 offset:36720
	v_add_f32_dpp v230, v230, v230 quad_perm:[2,3,0,1] row_mask:0xf bank_mask:0xf
	v_pk_fma_f32 v[232:233], v[206:207], v[80:81], v[232:233] op_sel_hi:[1,0,1]
	v_pk_fma_f32 v[234:235], v[208:209], v[80:81], v[234:235] op_sel:[0,1,0]
	v_add_f32_dpp v230, v230, v230 row_half_mirror row_mask:0xf bank_mask:0xf
	v_pk_fma_f32 v[236:237], v[210:211], v[82:83], v[236:237] op_sel_hi:[1,0,1]
	v_pk_fma_f32 v[238:239], v[212:213], v[82:83], v[238:239] op_sel:[0,1,0]
	v_mov_b32_dpp v231, v230 row_ror:8 row_mask:0xf bank_mask:0xf
	ds_write_b64 v217, v[228:229] offset:2880
	v_pk_fma_f32 v[206:207], v[88:89], v[230:231], v[232:233] op_sel_hi:[0,1,1] neg_lo:[1,0,0] neg_hi:[1,0,0]
	v_pk_fma_f32 v[208:209], v[88:89], v[230:231], v[234:235] op_sel:[1,0,0] neg_lo:[1,0,0] neg_hi:[1,0,0]
	v_pk_fma_f32 v[210:211], v[90:91], v[230:231], v[236:237] op_sel_hi:[0,1,1] neg_lo:[1,0,0] neg_hi:[1,0,0]
	v_pk_fma_f32 v[212:213], v[90:91], v[230:231], v[238:239] op_sel:[1,0,0] neg_lo:[1,0,0] neg_hi:[1,0,0]
	ds_read_b128 v[84:87], v240 offset:10880
	ds_read_b64 v[100:101], v242 offset:45696
	ds_read_b128 v[92:95], v240 offset:28288
	ds_read_b128 v[80:83], v240 offset:2176
	ds_read_b128 v[88:91], v240 offset:19584
	s_waitcnt lgkmcnt(7)
; template <int CTRL> __device__ __forceinline__ float dppf(float x) { return __builtin_bit_cast(float, __builtin_amdgcn_update_dpp(0, __builtin_bit_cast(int, x), CTRL, 0xF, 0xF, false)); }
; __device__ __forceinline__ void phase_rwkv_scan(const Fr& F, int jr) {
;     ...
;                 for (int pg = 0; pg < 64; pg += 16) {
; #pragma unroll
;                     for (int pi = 0; pi < 16; ++pi) {
;                         const int p = pg + pi, pn = p < 63 ? p + 1 : 63;
;                         const f32x4 w4n = PW[pn * 16], k4n = PW[1024 + pn * 16], b4n = PW[2048 + pn * 16], d4n = PW[3072 + pn * 16], r4n = PR[pn * 16];
;                         const float vvn = PV[pn * 32];
;                         f32x2 t = S01 * k4.xy; t = S23 * k4.zw + t; float sa = t.x + t.y;
;                         sa += dppf<0x128>(sa);
;                         const f32x2 dv01 = d4.xy * vv, dv23 = d4.zw * vv;
;                         sa += dppf<0x124>(sa);
;                         const f32x2 e01 = S01 * w4.xy + dv01;
;                         sa += dppf<0x122>(sa);
;                         const f32x2 e23 = S23 * w4.zw + dv23;
;                         sa += dppf<0x121>(sa);
;                         S01 = e01 - b4.xy * sa; S23 = e23 - b4.zw * sa;
;                         f32x2 u = S01 * r4.xy; u = S23 * r4.zw + u;
;                         PY[pi * 64] = u.x + u.y;
;                         w4 = w4n; k4 = k4n; b4 = b4n; d4 = d4n; r4 = r4n; vv = vvn;
	v_pk_mul_f32 v[226:227], v[206:207], v[106:107] op_sel_hi:[1,0]
	v_pk_mul_f32 v[228:229], v[206:207], v[96:97] op_sel_hi:[1,0]
	v_pk_fma_f32 v[226:227], v[208:209], v[106:107], v[226:227] op_sel:[0,1,0]
	v_pk_fma_f32 v[228:229], v[208:209], v[96:97], v[228:229] op_sel:[0,1,0]
	v_pk_fma_f32 v[226:227], v[210:211], v[108:109], v[226:227] op_sel_hi:[1,0,1]
	v_pk_fma_f32 v[228:229], v[210:211], v[98:99], v[228:229] op_sel_hi:[1,0,1]
	v_pk_fma_f32 v[226:227], v[212:213], v[108:109], v[226:227] op_sel:[0,1,0]
	v_pk_fma_f32 v[228:229], v[212:213], v[98:99], v[228:229] op_sel:[0,1,0]
	v_pk_mul_f32 v[232:233], v[118:119], v[114:115] op_sel_hi:[1,0]
	v_add_f32_dpp v230, v227, v226 row_ror:8 row_mask:0xf bank_mask:0xf
	v_pk_mul_f32 v[234:235], v[118:119], v[114:115] op_sel:[0,1]
	v_pk_mul_f32 v[236:237], v[118:119], v[116:117] op_sel_hi:[1,0]
	v_add_f32_dpp v230, v230, v230 quad_perm:[1,0,3,2] row_mask:0xf bank_mask:0xf
	v_pk_mul_f32 v[238:239], v[118:119], v[116:117] op_sel:[0,1]
	ds_read_b128 v[96:99], v240 offset:36992
	v_add_f32_dpp v230, v230, v230 quad_perm:[2,3,0,1] row_mask:0xf bank_mask:0xf
	v_pk_fma_f32 v[232:233], v[206:207], v[102:103], v[232:233] op_sel_hi:[1,0,1]
	v_pk_fma_f32 v[234:235], v[208:209], v[102:103], v[234:235] op_sel:[0,1,0]
	v_add_f32_dpp v230, v230, v230 row_half_mirror row_mask:0xf bank_mask:0xf
	v_pk_fma_f32 v[236:237], v[210:211], v[104:105], v[236:237] op_sel_hi:[1,0,1]
	v_pk_fma_f32 v[238:239], v[212:213], v[104:105], v[238:239] op_sel:[0,1,0]
	v_mov_b32_dpp v231, v230 row_ror:8 row_mask:0xf bank_mask:0xf
	ds_write_b64 v217, v[228:229] offset:3456
	v_pk_fma_f32 v[206:207], v[110:111], v[230:231], v[232:233] op_sel_hi:[0,1,1] neg_lo:[1,0,0] neg_hi:[1,0,0]
	v_pk_fma_f32 v[208:209], v[110:111], v[230:231], v[234:235] op_sel:[1,0,0] neg_lo:[1,0,0] neg_hi:[1,0,0]
	v_pk_fma_f32 v[210:211], v[112:113], v[230:231], v[236:237] op_sel_hi:[0,1,1] neg_lo:[1,0,0] neg_hi:[1,0,0]
	v_pk_fma_f32 v[212:213], v[112:113], v[230:231], v[238:239] op_sel:[1,0,0] neg_lo:[1,0,0] neg_hi:[1,0,0]
	ds_read_b128 v[106:109], v240 offset:11152
	ds_read_b64 v[118:119], v242 offset:45968
	ds_read_b128 v[114:117], v240 offset:28560
	ds_read_b128 v[102:105], v240 offset:2448
	ds_read_b128 v[110:113], v240 offset:19856
	s_waitcnt lgkmcnt(7)
	v_pk_mul_f32 v[226:227], v[206:207], v[84:85] op_sel_hi:[1,0]
	v_pk_mul_f32 v[228:229], v[206:207], v[222:223] op_sel_hi:[1,0]
	v_pk_fma_f32 v[226:227], v[208:209], v[84:85], v[226:227] op_sel:[0,1,0]
	v_pk_fma_f32 v[228:229], v[208:209], v[222:223], v[228:229] op_sel:[0,1,0]
	v_pk_fma_f32 v[226:227], v[210:211], v[86:87], v[226:227] op_sel_hi:[1,0,1]
	v_pk_fma_f32 v[228:229], v[210:211], v[224:225], v[228:229] op_sel_hi:[1,0,1]
	v_pk_fma_f32 v[226:227], v[212:213], v[86:87], v[226:227] op_sel:[0,1,0]
	v_pk_fma_f32 v[228:229], v[212:213], v[224:225], v[228:229] op_sel:[0,1,0]
	v_pk_mul_f32 v[232:233], v[100:101], v[92:93] op_sel_hi:[1,0]
	v_add_f32_dpp v230, v227, v226 row_ror:8 row_mask:0xf bank_mask:0xf
	v_pk_mul_f32 v[234:235], v[100:101], v[92:93] op_sel:[0,1]
	v_pk_mul_f32 v[236:237], v[100:101], v[94:95] op_sel_hi:[1,0]
	v_add_f32_dpp v230, v230, v230 quad_perm:[1,0,3,2] row_mask:0xf bank_mask:0xf
	v_pk_mul_f32 v[238:239], v[100:101], v[94:95] op_sel:[0,1]
	ds_read_b128 v[222:225], v240 offset:37264
	v_add_f32_dpp v230, v230, v230 quad_perm:[2,3,0,1] row_mask:0xf bank_mask:0xf
	v_pk_fma_f32 v[232:233], v[206:207], v[80:81], v[232:233] op_sel_hi:[1,0,1]
	v_pk_fma_f32 v[234:235], v[208:209], v[80:81], v[234:235] op_sel:[0,1,0]
	v_add_f32_dpp v230, v230, v230 row_half_mirror row_mask:0xf bank_mask:0xf
	v_pk_fma_f32 v[236:237], v[210:211], v[82:83], v[236:237] op_sel_hi:[1,0,1]
	v_pk_fma_f32 v[238:239], v[212:213], v[82:83], v[238:239] op_sel:[0,1,0]
	v_mov_b32_dpp v231, v230 row_ror:8 row_mask:0xf bank_mask:0xf
	ds_write_b64 v217, v[228:229] offset:4032
	v_pk_fma_f32 v[206:207], v[88:89], v[230:231], v[232:233] op_sel_hi:[0,1,1] neg_lo:[1,0,0] neg_hi:[1,0,0]
	v_pk_fma_f32 v[208:209], v[88:89], v[230:231], v[234:235] op_sel:[1,0,0] neg_lo:[1,0,0] neg_hi:[1,0,0]
	v_pk_fma_f32 v[210:211], v[90:91], v[230:231], v[236:237] op_sel_hi:[0,1,1] neg_lo:[1,0,0] neg_hi:[1,0,0]
	v_pk_fma_f32 v[212:213], v[90:91], v[230:231], v[238:239] op_sel:[1,0,0] neg_lo:[1,0,0] neg_hi:[1,0,0]
	ds_read_b128 v[84:87], v240 offset:11424
	ds_read_b64 v[100:101], v242 offset:46240
	ds_read_b128 v[92:95], v240 offset:28832
	ds_read_b128 v[80:83], v240 offset:2720
	ds_read_b128 v[88:91], v240 offset:20128
	s_waitcnt lgkmcnt(7)
; template <int CTRL> __device__ __forceinline__ float dppf(float x) { return __builtin_bit_cast(float, __builtin_amdgcn_update_dpp(0, __builtin_bit_cast(int, x), CTRL, 0xF, 0xF, false)); }
; __device__ __forceinline__ void phase_rwkv_scan(const Fr& F, int jr) {
;     ...
;                 for (int pg = 0; pg < 64; pg += 16) {
; #pragma unroll
;                     for (int pi = 0; pi < 16; ++pi) {
;                         const int p = pg + pi, pn = p < 63 ? p + 1 : 63;
;                         const f32x4 w4n = PW[pn * 16], k4n = PW[1024 + pn * 16], b4n = PW[2048 + pn * 16], d4n = PW[3072 + pn * 16], r4n = PR[pn * 16];
;                         const float vvn = PV[pn * 32];
;                         f32x2 t = S01 * k4.xy; t = S23 * k4.zw + t; float sa = t.x + t.y;
;                         sa += dppf<0x128>(sa);
;                         const f32x2 dv01 = d4.xy * vv, dv23 = d4.zw * vv;
;                         sa += dppf<0x124>(sa);
;                         const f32x2 e01 = S01 * w4.xy + dv01;
;                         sa += dppf<0x122>(sa);
;                         const f32x2 e23 = S23 * w4.zw + dv23;
;                         sa += dppf<0x121>(sa);
;                         S01 = e01 - b4.xy * sa; S23 = e23 - b4.zw * sa;
;                         f32x2 u = S01 * r4.xy; u = S23 * r4.zw + u;
;                         PY[pi * 64] = u.x + u.y;
;                         w4 = w4n; k4 = k4n; b4 = b4n; d4 = d4n; r4 = r4n; vv = vvn;
	v_pk_mul_f32 v[226:227], v[206:207], v[106:107] op_sel_hi:[1,0]
	v_pk_mul_f32 v[228:229], v[206:207], v[96:97] op_sel_hi:[1,0]
	v_pk_fma_f32 v[226:227], v[208:209], v[106:107], v[226:227] op_sel:[0,1,0]
	v_pk_fma_f32 v[228:229], v[208:209], v[96:97], v[228:229] op_sel:[0,1,0]
	v_pk_fma_f32 v[226:227], v[210:211], v[108:109], v[226:227] op_sel_hi:[1,0,1]
	v_pk_fma_f32 v[228:229], v[210:211], v[98:99], v[228:229] op_sel_hi:[1,0,1]
	v_pk_fma_f32 v[226:227], v[212:213], v[108:109], v[226:227] op_sel:[0,1,0]
	v_pk_fma_f32 v[228:229], v[212:213], v[98:99], v[228:229] op_sel:[0,1,0]
	v_pk_mul_f32 v[232:233], v[118:119], v[114:115] op_sel_hi:[1,0]
	v_add_f32_dpp v230, v227, v226 row_ror:8 row_mask:0xf bank_mask:0xf
	v_pk_mul_f32 v[234:235], v[118:119], v[114:115] op_sel:[0,1]
	v_pk_mul_f32 v[236:237], v[118:119], v[116:117] op_sel_hi:[1,0]
	v_add_f32_dpp v230, v230, v230 quad_perm:[1,0,3,2] row_mask:0xf bank_mask:0xf
	v_pk_mul_f32 v[238:239], v[118:119], v[116:117] op_sel:[0,1]
	ds_read_b128 v[96:99], v240 offset:37536
	v_add_f32_dpp v230, v230, v230 quad_perm:[2,3,0,1] row_mask:0xf bank_mask:0xf
	v_pk_fma_f32 v[232:233], v[206:207], v[102:103], v[232:233] op_sel_hi:[1,0,1]
	v_pk_fma_f32 v[234:235], v[208:209], v[102:103], v[234:235] op_sel:[0,1,0]
	v_add_f32_dpp v230, v230, v230 row_half_mirror row_mask:0xf bank_mask:0xf
	v_pk_fma_f32 v[236:237], v[210:211], v[104:105], v[236:237] op_sel_hi:[1,0,1]
	v_pk_fma_f32 v[238:239], v[212:213], v[104:105], v[238:239] op_sel:[0,1,0]
	v_mov_b32_dpp v231, v230 row_ror:8 row_mask:0xf bank_mask:0xf
	ds_write_b64 v217, v[228:229] offset:4608
	v_pk_fma_f32 v[206:207], v[110:111], v[230:231], v[232:233] op_sel_hi:[0,1,1] neg_lo:[1,0,0] neg_hi:[1,0,0]
	v_pk_fma_f32 v[208:209], v[110:111], v[230:231], v[234:235] op_sel:[1,0,0] neg_lo:[1,0,0] neg_hi:[1,0,0]
	v_pk_fma_f32 v[210:211], v[112:113], v[230:231], v[236:237] op_sel_hi:[0,1,1] neg_lo:[1,0,0] neg_hi:[1,0,0]
	v_pk_fma_f32 v[212:213], v[112:113], v[230:231], v[238:239] op_sel:[1,0,0] neg_lo:[1,0,0] neg_hi:[1,0,0]
	ds_read_b128 v[106:109], v240 offset:11696
	ds_read_b64 v[118:119], v242 offset:46512
	ds_read_b128 v[114:117], v240 offset:29104
	ds_read_b128 v[102:105], v240 offset:2992
	ds_read_b128 v[110:113], v240 offset:20400
	s_waitcnt lgkmcnt(7)
	v_pk_mul_f32 v[226:227], v[206:207], v[84:85] op_sel_hi:[1,0]
	v_pk_mul_f32 v[228:229], v[206:207], v[222:223] op_sel_hi:[1,0]
	v_pk_fma_f32 v[226:227], v[208:209], v[84:85], v[226:227] op_sel:[0,1,0]
	v_pk_fma_f32 v[228:229], v[208:209], v[222:223], v[228:229] op_sel:[0,1,0]
	v_pk_fma_f32 v[226:227], v[210:211], v[86:87], v[226:227] op_sel_hi:[1,0,1]
	v_pk_fma_f32 v[228:229], v[210:211], v[224:225], v[228:229] op_sel_hi:[1,0,1]
	v_pk_fma_f32 v[226:227], v[212:213], v[86:87], v[226:227] op_sel:[0,1,0]
	v_pk_fma_f32 v[228:229], v[212:213], v[224:225], v[228:229] op_sel:[0,1,0]
	v_pk_mul_f32 v[232:233], v[100:101], v[92:93] op_sel_hi:[1,0]
	v_add_f32_dpp v230, v227, v226 row_ror:8 row_mask:0xf bank_mask:0xf
	v_pk_mul_f32 v[234:235], v[100:101], v[92:93] op_sel:[0,1]
	v_pk_mul_f32 v[236:237], v[100:101], v[94:95] op_sel_hi:[1,0]
	v_add_f32_dpp v230, v230, v230 quad_perm:[1,0,3,2] row_mask:0xf bank_mask:0xf
	v_pk_mul_f32 v[238:239], v[100:101], v[94:95] op_sel:[0,1]
	ds_read_b128 v[222:225], v240 offset:37808
	v_add_f32_dpp v230, v230, v230 quad_perm:[2,3,0,1] row_mask:0xf bank_mask:0xf
	v_pk_fma_f32 v[232:233], v[206:207], v[80:81], v[232:233] op_sel_hi:[1,0,1]
	v_pk_fma_f32 v[234:235], v[208:209], v[80:81], v[234:235] op_sel:[0,1,0]
	v_add_f32_dpp v230, v230, v230 row_half_mirror row_mask:0xf bank_mask:0xf
	v_pk_fma_f32 v[236:237], v[210:211], v[82:83], v[236:237] op_sel_hi:[1,0,1]
	v_pk_fma_f32 v[238:239], v[212:213], v[82:83], v[238:239] op_sel:[0,1,0]
	v_mov_b32_dpp v231, v230 row_ror:8 row_mask:0xf bank_mask:0xf
	ds_write_b64 v217, v[228:229] offset:5184
	v_pk_fma_f32 v[206:207], v[88:89], v[230:231], v[232:233] op_sel_hi:[0,1,1] neg_lo:[1,0,0] neg_hi:[1,0,0]
	v_pk_fma_f32 v[208:209], v[88:89], v[230:231], v[234:235] op_sel:[1,0,0] neg_lo:[1,0,0] neg_hi:[1,0,0]
	v_pk_fma_f32 v[210:211], v[90:91], v[230:231], v[236:237] op_sel_hi:[0,1,1] neg_lo:[1,0,0] neg_hi:[1,0,0]
	v_pk_fma_f32 v[212:213], v[90:91], v[230:231], v[238:239] op_sel:[1,0,0] neg_lo:[1,0,0] neg_hi:[1,0,0]
	ds_read_b128 v[84:87], v240 offset:11968
	ds_read_b64 v[100:101], v242 offset:46784
	ds_read_b128 v[92:95], v240 offset:29376
	ds_read_b128 v[80:83], v240 offset:3264
	ds_read_b128 v[88:91], v240 offset:20672
	s_waitcnt lgkmcnt(7)
; template <int CTRL> __device__ __forceinline__ float dppf(float x) { return __builtin_bit_cast(float, __builtin_amdgcn_update_dpp(0, __builtin_bit_cast(int, x), CTRL, 0xF, 0xF, false)); }
; __device__ __forceinline__ void phase_rwkv_scan(const Fr& F, int jr) {
;     ...
;                 for (int pg = 0; pg < 64; pg += 16) {
; #pragma unroll
;                     for (int pi = 0; pi < 16; ++pi) {
;                         const int p = pg + pi, pn = p < 63 ? p + 1 : 63;
;                         const f32x4 w4n = PW[pn * 16], k4n = PW[1024 + pn * 16], b4n = PW[2048 + pn * 16], d4n = PW[3072 + pn * 16], r4n = PR[pn * 16];
;                         const float vvn = PV[pn * 32];
;                         f32x2 t = S01 * k4.xy; t = S23 * k4.zw + t; float sa = t.x + t.y;
;                         sa += dppf<0x128>(sa);
;                         const f32x2 dv01 = d4.xy * vv, dv23 = d4.zw * vv;
;                         sa += dppf<0x124>(sa);
;                         const f32x2 e01 = S01 * w4.xy + dv01;
;                         sa += dppf<0x122>(sa);
;                         const f32x2 e23 = S23 * w4.zw + dv23;
;                         sa += dppf<0x121>(sa);
;                         S01 = e01 - b4.xy * sa; S23 = e23 - b4.zw * sa;
;                         f32x2 u = S01 * r4.xy; u = S23 * r4.zw + u;
;                         PY[pi * 64] = u.x + u.y;
;                         w4 = w4n; k4 = k4n; b4 = b4n; d4 = d4n; r4 = r4n; vv = vvn;
	v_pk_mul_f32 v[226:227], v[206:207], v[106:107] op_sel_hi:[1,0]
	v_pk_mul_f32 v[228:229], v[206:207], v[96:97] op_sel_hi:[1,0]
	v_pk_fma_f32 v[226:227], v[208:209], v[106:107], v[226:227] op_sel:[0,1,0]
	v_pk_fma_f32 v[228:229], v[208:209], v[96:97], v[228:229] op_sel:[0,1,0]
	v_pk_fma_f32 v[226:227], v[210:211], v[108:109], v[226:227] op_sel_hi:[1,0,1]
	v_pk_fma_f32 v[228:229], v[210:211], v[98:99], v[228:229] op_sel_hi:[1,0,1]
	v_pk_fma_f32 v[226:227], v[212:213], v[108:109], v[226:227] op_sel:[0,1,0]
	v_pk_fma_f32 v[228:229], v[212:213], v[98:99], v[228:229] op_sel:[0,1,0]
	v_pk_mul_f32 v[232:233], v[118:119], v[114:115] op_sel_hi:[1,0]
	v_add_f32_dpp v230, v227, v226 row_ror:8 row_mask:0xf bank_mask:0xf
	v_pk_mul_f32 v[234:235], v[118:119], v[114:115] op_sel:[0,1]
	v_pk_mul_f32 v[236:237], v[118:119], v[116:117] op_sel_hi:[1,0]
	v_add_f32_dpp v230, v230, v230 quad_perm:[1,0,3,2] row_mask:0xf bank_mask:0xf
	v_pk_mul_f32 v[238:239], v[118:119], v[116:117] op_sel:[0,1]
	ds_read_b128 v[96:99], v240 offset:38080
	v_add_f32_dpp v230, v230, v230 quad_perm:[2,3,0,1] row_mask:0xf bank_mask:0xf
	v_pk_fma_f32 v[232:233], v[206:207], v[102:103], v[232:233] op_sel_hi:[1,0,1]
	v_pk_fma_f32 v[234:235], v[208:209], v[102:103], v[234:235] op_sel:[0,1,0]
	v_add_f32_dpp v230, v230, v230 row_half_mirror row_mask:0xf bank_mask:0xf
	v_pk_fma_f32 v[236:237], v[210:211], v[104:105], v[236:237] op_sel_hi:[1,0,1]
	v_pk_fma_f32 v[238:239], v[212:213], v[104:105], v[238:239] op_sel:[0,1,0]
	v_mov_b32_dpp v231, v230 row_ror:8 row_mask:0xf bank_mask:0xf
	ds_write_b64 v217, v[228:229] offset:5760
	v_pk_fma_f32 v[206:207], v[110:111], v[230:231], v[232:233] op_sel_hi:[0,1,1] neg_lo:[1,0,0] neg_hi:[1,0,0]
	v_pk_fma_f32 v[208:209], v[110:111], v[230:231], v[234:235] op_sel:[1,0,0] neg_lo:[1,0,0] neg_hi:[1,0,0]
	v_pk_fma_f32 v[210:211], v[112:113], v[230:231], v[236:237] op_sel_hi:[0,1,1] neg_lo:[1,0,0] neg_hi:[1,0,0]
	v_pk_fma_f32 v[212:213], v[112:113], v[230:231], v[238:239] op_sel:[1,0,0] neg_lo:[1,0,0] neg_hi:[1,0,0]
	ds_read_b128 v[106:109], v240 offset:12240
	ds_read_b64 v[118:119], v242 offset:47056
	ds_read_b128 v[114:117], v240 offset:29648
	ds_read_b128 v[102:105], v240 offset:3536
	ds_read_b128 v[110:113], v240 offset:20944
	s_waitcnt lgkmcnt(7)
	v_pk_mul_f32 v[226:227], v[206:207], v[84:85] op_sel_hi:[1,0]
	v_pk_mul_f32 v[228:229], v[206:207], v[222:223] op_sel_hi:[1,0]
	v_pk_fma_f32 v[226:227], v[208:209], v[84:85], v[226:227] op_sel:[0,1,0]
	v_pk_fma_f32 v[228:229], v[208:209], v[222:223], v[228:229] op_sel:[0,1,0]
	v_pk_fma_f32 v[226:227], v[210:211], v[86:87], v[226:227] op_sel_hi:[1,0,1]
	v_pk_fma_f32 v[228:229], v[210:211], v[224:225], v[228:229] op_sel_hi:[1,0,1]
	v_pk_fma_f32 v[226:227], v[212:213], v[86:87], v[226:227] op_sel:[0,1,0]
	v_pk_fma_f32 v[228:229], v[212:213], v[224:225], v[228:229] op_sel:[0,1,0]
	v_pk_mul_f32 v[232:233], v[100:101], v[92:93] op_sel_hi:[1,0]
	v_add_f32_dpp v230, v227, v226 row_ror:8 row_mask:0xf bank_mask:0xf
	v_pk_mul_f32 v[234:235], v[100:101], v[92:93] op_sel:[0,1]
	v_pk_mul_f32 v[236:237], v[100:101], v[94:95] op_sel_hi:[1,0]
	v_add_f32_dpp v230, v230, v230 quad_perm:[1,0,3,2] row_mask:0xf bank_mask:0xf
	v_pk_mul_f32 v[238:239], v[100:101], v[94:95] op_sel:[0,1]
	ds_read_b128 v[222:225], v240 offset:38352
	v_add_f32_dpp v230, v230, v230 quad_perm:[2,3,0,1] row_mask:0xf bank_mask:0xf
	v_pk_fma_f32 v[232:233], v[206:207], v[80:81], v[232:233] op_sel_hi:[1,0,1]
	v_pk_fma_f32 v[234:235], v[208:209], v[80:81], v[234:235] op_sel:[0,1,0]
	v_add_f32_dpp v230, v230, v230 row_half_mirror row_mask:0xf bank_mask:0xf
	v_pk_fma_f32 v[236:237], v[210:211], v[82:83], v[236:237] op_sel_hi:[1,0,1]
	v_pk_fma_f32 v[238:239], v[212:213], v[82:83], v[238:239] op_sel:[0,1,0]
	v_mov_b32_dpp v231, v230 row_ror:8 row_mask:0xf bank_mask:0xf
	ds_write_b64 v217, v[228:229] offset:6336
	v_pk_fma_f32 v[206:207], v[88:89], v[230:231], v[232:233] op_sel_hi:[0,1,1] neg_lo:[1,0,0] neg_hi:[1,0,0]
	v_pk_fma_f32 v[208:209], v[88:89], v[230:231], v[234:235] op_sel:[1,0,0] neg_lo:[1,0,0] neg_hi:[1,0,0]
	v_pk_fma_f32 v[210:211], v[90:91], v[230:231], v[236:237] op_sel_hi:[0,1,1] neg_lo:[1,0,0] neg_hi:[1,0,0]
	v_pk_fma_f32 v[212:213], v[90:91], v[230:231], v[238:239] op_sel:[1,0,0] neg_lo:[1,0,0] neg_hi:[1,0,0]
	ds_read_b128 v[84:87], v240 offset:12512
	ds_read_b64 v[100:101], v242 offset:47328
	ds_read_b128 v[92:95], v240 offset:29920
	ds_read_b128 v[80:83], v240 offset:3808
	ds_read_b128 v[88:91], v240 offset:21216
	s_waitcnt lgkmcnt(7)
; template <int CTRL> __device__ __forceinline__ float dppf(float x) { return __builtin_bit_cast(float, __builtin_amdgcn_update_dpp(0, __builtin_bit_cast(int, x), CTRL, 0xF, 0xF, false)); }
; __device__ __forceinline__ void phase_rwkv_scan(const Fr& F, int jr) {
;     ...
;                 for (int pg = 0; pg < 64; pg += 16) {
; #pragma unroll
;                     for (int pi = 0; pi < 16; ++pi) {
;                         const int p = pg + pi, pn = p < 63 ? p + 1 : 63;
;                         const f32x4 w4n = PW[pn * 16], k4n = PW[1024 + pn * 16], b4n = PW[2048 + pn * 16], d4n = PW[3072 + pn * 16], r4n = PR[pn * 16];
;                         const float vvn = PV[pn * 32];
;                         f32x2 t = S01 * k4.xy; t = S23 * k4.zw + t; float sa = t.x + t.y;
;                         sa += dppf<0x128>(sa);
;                         const f32x2 dv01 = d4.xy * vv, dv23 = d4.zw * vv;
;                         sa += dppf<0x124>(sa);
;                         const f32x2 e01 = S01 * w4.xy + dv01;
;                         sa += dppf<0x122>(sa);
;                         const f32x2 e23 = S23 * w4.zw + dv23;
;                         sa += dppf<0x121>(sa);
;                         S01 = e01 - b4.xy * sa; S23 = e23 - b4.zw * sa;
;                         f32x2 u = S01 * r4.xy; u = S23 * r4.zw + u;
;                         PY[pi * 64] = u.x + u.y;
;                         w4 = w4n; k4 = k4n; b4 = b4n; d4 = d4n; r4 = r4n; vv = vvn;
	v_pk_mul_f32 v[226:227], v[206:207], v[106:107] op_sel_hi:[1,0]
	v_pk_mul_f32 v[228:229], v[206:207], v[96:97] op_sel_hi:[1,0]
	v_pk_fma_f32 v[226:227], v[208:209], v[106:107], v[226:227] op_sel:[0,1,0]
	v_pk_fma_f32 v[228:229], v[208:209], v[96:97], v[228:229] op_sel:[0,1,0]
	v_pk_fma_f32 v[226:227], v[210:211], v[108:109], v[226:227] op_sel_hi:[1,0,1]
	v_pk_fma_f32 v[228:229], v[210:211], v[98:99], v[228:229] op_sel_hi:[1,0,1]
	v_pk_fma_f32 v[226:227], v[212:213], v[108:109], v[226:227] op_sel:[0,1,0]
	v_pk_fma_f32 v[228:229], v[212:213], v[98:99], v[228:229] op_sel:[0,1,0]
	v_pk_mul_f32 v[232:233], v[118:119], v[114:115] op_sel_hi:[1,0]
	v_add_f32_dpp v230, v227, v226 row_ror:8 row_mask:0xf bank_mask:0xf
	v_pk_mul_f32 v[234:235], v[118:119], v[114:115] op_sel:[0,1]
	v_pk_mul_f32 v[236:237], v[118:119], v[116:117] op_sel_hi:[1,0]
	v_add_f32_dpp v230, v230, v230 quad_perm:[1,0,3,2] row_mask:0xf bank_mask:0xf
	v_pk_mul_f32 v[238:239], v[118:119], v[116:117] op_sel:[0,1]
	ds_read_b128 v[96:99], v240 offset:38624
	v_add_f32_dpp v230, v230, v230 quad_perm:[2,3,0,1] row_mask:0xf bank_mask:0xf
	v_pk_fma_f32 v[232:233], v[206:207], v[102:103], v[232:233] op_sel_hi:[1,0,1]
	v_pk_fma_f32 v[234:235], v[208:209], v[102:103], v[234:235] op_sel:[0,1,0]
	v_add_f32_dpp v230, v230, v230 row_half_mirror row_mask:0xf bank_mask:0xf
	v_pk_fma_f32 v[236:237], v[210:211], v[104:105], v[236:237] op_sel_hi:[1,0,1]
	v_pk_fma_f32 v[238:239], v[212:213], v[104:105], v[238:239] op_sel:[0,1,0]
	v_mov_b32_dpp v231, v230 row_ror:8 row_mask:0xf bank_mask:0xf
	ds_write_b64 v217, v[228:229] offset:6912
	v_pk_fma_f32 v[206:207], v[110:111], v[230:231], v[232:233] op_sel_hi:[0,1,1] neg_lo:[1,0,0] neg_hi:[1,0,0]
	v_pk_fma_f32 v[208:209], v[110:111], v[230:231], v[234:235] op_sel:[1,0,0] neg_lo:[1,0,0] neg_hi:[1,0,0]
	v_pk_fma_f32 v[210:211], v[112:113], v[230:231], v[236:237] op_sel_hi:[0,1,1] neg_lo:[1,0,0] neg_hi:[1,0,0]
	v_pk_fma_f32 v[212:213], v[112:113], v[230:231], v[238:239] op_sel:[1,0,0] neg_lo:[1,0,0] neg_hi:[1,0,0]
	ds_read_b128 v[106:109], v240 offset:12784
	ds_read_b64 v[118:119], v242 offset:47600
	ds_read_b128 v[114:117], v240 offset:30192
	ds_read_b128 v[102:105], v240 offset:4080
	ds_read_b128 v[110:113], v240 offset:21488
	s_waitcnt lgkmcnt(7)
	v_pk_mul_f32 v[226:227], v[206:207], v[84:85] op_sel_hi:[1,0]
	v_pk_mul_f32 v[228:229], v[206:207], v[222:223] op_sel_hi:[1,0]
	v_pk_fma_f32 v[226:227], v[208:209], v[84:85], v[226:227] op_sel:[0,1,0]
	v_pk_fma_f32 v[228:229], v[208:209], v[222:223], v[228:229] op_sel:[0,1,0]
	v_pk_fma_f32 v[226:227], v[210:211], v[86:87], v[226:227] op_sel_hi:[1,0,1]
	v_pk_fma_f32 v[228:229], v[210:211], v[224:225], v[228:229] op_sel_hi:[1,0,1]
	v_pk_fma_f32 v[226:227], v[212:213], v[86:87], v[226:227] op_sel:[0,1,0]
	v_pk_fma_f32 v[228:229], v[212:213], v[224:225], v[228:229] op_sel:[0,1,0]
	v_pk_mul_f32 v[232:233], v[100:101], v[92:93] op_sel_hi:[1,0]
	v_add_f32_dpp v230, v227, v226 row_ror:8 row_mask:0xf bank_mask:0xf
	v_pk_mul_f32 v[234:235], v[100:101], v[92:93] op_sel:[0,1]
	v_pk_mul_f32 v[236:237], v[100:101], v[94:95] op_sel_hi:[1,0]
	v_add_f32_dpp v230, v230, v230 quad_perm:[1,0,3,2] row_mask:0xf bank_mask:0xf
	v_pk_mul_f32 v[238:239], v[100:101], v[94:95] op_sel:[0,1]
	ds_read_b128 v[222:225], v240 offset:38896
	v_add_f32_dpp v230, v230, v230 quad_perm:[2,3,0,1] row_mask:0xf bank_mask:0xf
	v_pk_fma_f32 v[232:233], v[206:207], v[80:81], v[232:233] op_sel_hi:[1,0,1]
	v_pk_fma_f32 v[234:235], v[208:209], v[80:81], v[234:235] op_sel:[0,1,0]
	v_add_f32_dpp v230, v230, v230 row_half_mirror row_mask:0xf bank_mask:0xf
	v_pk_fma_f32 v[236:237], v[210:211], v[82:83], v[236:237] op_sel_hi:[1,0,1]
	v_pk_fma_f32 v[238:239], v[212:213], v[82:83], v[238:239] op_sel:[0,1,0]
	v_mov_b32_dpp v231, v230 row_ror:8 row_mask:0xf bank_mask:0xf
	ds_write_b64 v217, v[228:229] offset:7488
	v_pk_fma_f32 v[206:207], v[88:89], v[230:231], v[232:233] op_sel_hi:[0,1,1] neg_lo:[1,0,0] neg_hi:[1,0,0]
	v_pk_fma_f32 v[208:209], v[88:89], v[230:231], v[234:235] op_sel:[1,0,0] neg_lo:[1,0,0] neg_hi:[1,0,0]
	v_pk_fma_f32 v[210:211], v[90:91], v[230:231], v[236:237] op_sel_hi:[0,1,1] neg_lo:[1,0,0] neg_hi:[1,0,0]
	v_pk_fma_f32 v[212:213], v[90:91], v[230:231], v[238:239] op_sel:[1,0,0] neg_lo:[1,0,0] neg_hi:[1,0,0]
	ds_read_b128 v[84:87], v240 offset:13056
	ds_read_b64 v[100:101], v242 offset:47872
	ds_read_b128 v[92:95], v240 offset:30464
	ds_read_b128 v[80:83], v240 offset:4352
	ds_read_b128 v[88:91], v240 offset:21760
	s_waitcnt lgkmcnt(7)
	v_pk_mul_f32 v[226:227], v[206:207], v[106:107] op_sel_hi:[1,0]
	v_pk_mul_f32 v[228:229], v[206:207], v[96:97] op_sel_hi:[1,0]
	v_pk_fma_f32 v[226:227], v[208:209], v[106:107], v[226:227] op_sel:[0,1,0]
	v_pk_fma_f32 v[228:229], v[208:209], v[96:97], v[228:229] op_sel:[0,1,0]
	v_pk_fma_f32 v[226:227], v[210:211], v[108:109], v[226:227] op_sel_hi:[1,0,1]
	v_pk_fma_f32 v[228:229], v[210:211], v[98:99], v[228:229] op_sel_hi:[1,0,1]
	v_pk_fma_f32 v[226:227], v[212:213], v[108:109], v[226:227] op_sel:[0,1,0]
	v_pk_fma_f32 v[228:229], v[212:213], v[98:99], v[228:229] op_sel:[0,1,0]
	v_pk_mul_f32 v[232:233], v[118:119], v[114:115] op_sel_hi:[1,0]
	v_add_f32_dpp v230, v227, v226 row_ror:8 row_mask:0xf bank_mask:0xf
	v_pk_mul_f32 v[234:235], v[118:119], v[114:115] op_sel:[0,1]
	v_pk_mul_f32 v[236:237], v[118:119], v[116:117] op_sel_hi:[1,0]
	v_add_f32_dpp v230, v230, v230 quad_perm:[1,0,3,2] row_mask:0xf bank_mask:0xf
	v_pk_mul_f32 v[238:239], v[118:119], v[116:117] op_sel:[0,1]
	ds_read_b128 v[96:99], v240 offset:39168
	v_add_f32_dpp v230, v230, v230 quad_perm:[2,3,0,1] row_mask:0xf bank_mask:0xf
	v_pk_fma_f32 v[232:233], v[206:207], v[102:103], v[232:233] op_sel_hi:[1,0,1]
	v_pk_fma_f32 v[234:235], v[208:209], v[102:103], v[234:235] op_sel:[0,1,0]
	v_add_f32_dpp v230, v230, v230 row_half_mirror row_mask:0xf bank_mask:0xf
	v_pk_fma_f32 v[236:237], v[210:211], v[104:105], v[236:237] op_sel_hi:[1,0,1]
	v_pk_fma_f32 v[238:239], v[212:213], v[104:105], v[238:239] op_sel:[0,1,0]
	v_mov_b32_dpp v231, v230 row_ror:8 row_mask:0xf bank_mask:0xf
	ds_write_b64 v217, v[228:229] offset:8064
	v_pk_fma_f32 v[206:207], v[110:111], v[230:231], v[232:233] op_sel_hi:[0,1,1] neg_lo:[1,0,0] neg_hi:[1,0,0]
	v_pk_fma_f32 v[208:209], v[110:111], v[230:231], v[234:235] op_sel:[1,0,0] neg_lo:[1,0,0] neg_hi:[1,0,0]
	v_pk_fma_f32 v[210:211], v[112:113], v[230:231], v[236:237] op_sel_hi:[0,1,1] neg_lo:[1,0,0] neg_hi:[1,0,0]
	v_pk_fma_f32 v[212:213], v[112:113], v[230:231], v[238:239] op_sel:[1,0,0] neg_lo:[1,0,0] neg_hi:[1,0,0]
	s_waitcnt lgkmcnt(8)
; __device__ __forceinline__ unsigned f2bf(float f) { unsigned u = __builtin_bit_cast(unsigned, f); return (u + 0x7fffu + ((u >> 16) & 1u)) >> 16; }
; template <int CTRL> __device__ __forceinline__ float dppf(float x) { return __builtin_bit_cast(float, __builtin_amdgcn_update_dpp(0, __builtin_bit_cast(int, x), CTRL, 0xF, 0xF, false)); }
; __device__ __forceinline__ void phase_rwkv_scan(const Fr& F, int jr) {
;     ...
;                 for (int pg = 0; pg < 64; pg += 16) {
; #pragma unroll
;                     for (int pi = 0; pi < 16; ++pi) {
;                         const int p = pg + pi, pn = p < 63 ? p + 1 : 63;
;                         const f32x4 w4n = PW[pn * 16], k4n = PW[1024 + pn * 16], b4n = PW[2048 + pn * 16], d4n = PW[3072 + pn * 16], r4n = PR[pn * 16];
;                         const float vvn = PV[pn * 32];
;                         f32x2 t = S01 * k4.xy; t = S23 * k4.zw + t; float sa = t.x + t.y;
;                         sa += dppf<0x128>(sa);
;                         const f32x2 dv01 = d4.xy * vv, dv23 = d4.zw * vv;
;                         sa += dppf<0x124>(sa);
;                         const f32x2 e01 = S01 * w4.xy + dv01;
;                         sa += dppf<0x122>(sa);
;                         const f32x2 e23 = S23 * w4.zw + dv23;
;                         sa += dppf<0x121>(sa);
;                         S01 = e01 - b4.xy * sa; S23 = e23 - b4.zw * sa;
;                         f32x2 u = S01 * r4.xy; u = S23 * r4.zw + u;
;                         PY[pi * 64] = u.x + u.y;
;                         w4 = w4n; k4 = k4n; b4 = b4n; d4 = d4n; r4 = r4n; vv = vvn;
;                     }
;                     asm volatile("s_waitcnt lgkmcnt(0)" ::: "memory");
;                     {
;                         const int j = lane >> 2, q = lane & 3; const float* yp = Ypw + j * 64 + q * 16;
;                         const f32x4 a0 = *(const f32x4*)yp, a1 = *(const f32x4*)(yp + 4), a2 = *(const f32x4*)(yp + 8), a3 = *(const f32x4*)(yp + 12);
;                         const f32x4 ssum = (a0 + a1) + (a2 + a3); const float yv = (ssum.x + ssum.y) + (ssum.z + ssum.w);
;                         const size_t row = (size_t)b * TB + tokof(s, chunk * 64 + pg + j);
;                         Yb[row * D + h * 64 + 32 * half + 4 * wave + q] = (bf16)f2bf(yv);
;                     }
	v_pk_mul_f32 v[228:229], v[206:207], v[222:223] op_sel_hi:[1,0]
	v_add_u32_e32 v243, s15, v219
	v_pk_fma_f32 v[228:229], v[208:209], v[222:223], v[228:229] op_sel:[0,1,0]
	v_lshl_add_u32 v243, v243, 11, v220
	v_pk_fma_f32 v[228:229], v[210:211], v[224:225], v[228:229] op_sel_hi:[1,0,1]
	v_add_u32_e32 v240, 0x1100, v240
	v_pk_fma_f32 v[228:229], v[212:213], v[224:225], v[228:229] op_sel:[0,1,0]
	v_add_u32_e32 v242, 0x1100, v242
	s_nop 0
	s_waitcnt lgkmcnt(1)
	ds_write_b64 v217, v[228:229] offset:8640
	ds_read_b128 v[102:105], v218 offset:0
	ds_read_b128 v[106:109], v218 offset:16
	ds_read_b128 v[110:113], v218 offset:32
	ds_read_b128 v[114:117], v218 offset:48
	ds_read_b128 v[222:225], v218 offset:64
	ds_read_b128 v[232:235], v218 offset:80
	ds_read_b128 v[236:239], v218 offset:96
	ds_read_b128 v[226:229], v218 offset:112
	s_waitcnt lgkmcnt(6)
	v_pk_add_f32 v[102:103], v[102:103], v[104:105]
	v_pk_add_f32 v[106:107], v[106:107], v[108:109]
	s_waitcnt lgkmcnt(4)
	v_pk_add_f32 v[110:111], v[110:111], v[112:113]
	v_pk_add_f32 v[114:115], v[114:115], v[116:117]
	v_pk_add_f32 v[102:103], v[102:103], v[106:107]
	s_waitcnt lgkmcnt(2)
	v_pk_add_f32 v[222:223], v[222:223], v[224:225]
	v_pk_add_f32 v[232:233], v[232:233], v[234:235]
	v_pk_add_f32 v[110:111], v[110:111], v[114:115]
	s_waitcnt lgkmcnt(0)
	v_pk_add_f32 v[236:237], v[236:237], v[238:239]
	v_pk_add_f32 v[226:227], v[226:227], v[228:229]
	v_pk_add_f32 v[222:223], v[222:223], v[232:233]
	v_pk_add_f32 v[102:103], v[102:103], v[110:111]
	v_pk_add_f32 v[236:237], v[236:237], v[226:227]
	s_add_i32 s15, s15, s19
	v_pk_add_f32 v[222:223], v[222:223], v[236:237]
	s_nop 0
	v_pk_add_f32 v[102:103], v[102:103], v[222:223] op_sel:[0,1] op_sel_hi:[1,0]
	s_nop 0
	v_cvt_pk_bf16_f32 v244, v102, v103
	s_nop 0
	global_store_dword v243, v244, s[20:21]
	s_waitcnt lgkmcnt(0)
	ds_read_b128 v[106:109], v240 offset:8976
	ds_read_b64 v[118:119], v242 offset:43792
	ds_read_b128 v[114:117], v240 offset:26384
	ds_read_b128 v[102:105], v240 offset:272
	ds_read_b128 v[110:113], v240 offset:17680
	v_pk_mul_f32 v[226:227], v[206:207], v[84:85] op_sel_hi:[1,0]
	v_pk_mul_f32 v[232:233], v[100:101], v[92:93] op_sel_hi:[1,0]
	v_pk_fma_f32 v[226:227], v[208:209], v[84:85], v[226:227] op_sel:[0,1,0]
	v_pk_mul_f32 v[234:235], v[100:101], v[92:93] op_sel:[0,1]
	v_pk_fma_f32 v[226:227], v[210:211], v[86:87], v[226:227] op_sel_hi:[1,0,1]
	v_pk_mul_f32 v[236:237], v[100:101], v[94:95] op_sel_hi:[1,0]
	v_pk_fma_f32 v[226:227], v[212:213], v[86:87], v[226:227] op_sel:[0,1,0]
	v_pk_mul_f32 v[238:239], v[100:101], v[94:95] op_sel:[0,1]
	s_nop 0
	v_add_f32_dpp v230, v227, v226 row_ror:8 row_mask:0xf bank_mask:0xf
	v_pk_fma_f32 v[232:233], v[206:207], v[80:81], v[232:233] op_sel_hi:[1,0,1]
	v_pk_fma_f32 v[234:235], v[208:209], v[80:81], v[234:235] op_sel:[0,1,0]
	v_add_f32_dpp v230, v230, v230 quad_perm:[1,0,3,2] row_mask:0xf bank_mask:0xf
	v_pk_fma_f32 v[236:237], v[210:211], v[82:83], v[236:237] op_sel_hi:[1,0,1]
	v_pk_fma_f32 v[238:239], v[212:213], v[82:83], v[238:239] op_sel:[0,1,0]
	v_add_f32_dpp v230, v230, v230 quad_perm:[2,3,0,1] row_mask:0xf bank_mask:0xf
	ds_read_b128 v[222:225], v240 offset:35088
	s_nop 0
	v_add_f32_dpp v230, v230, v230 row_half_mirror row_mask:0xf bank_mask:0xf
	s_nop 1
	v_mov_b32_dpp v231, v230 row_ror:8 row_mask:0xf bank_mask:0xf
	s_nop 0
	v_pk_fma_f32 v[206:207], v[88:89], v[230:231], v[232:233] op_sel_hi:[0,1,1] neg_lo:[1,0,0] neg_hi:[1,0,0]
	v_pk_fma_f32 v[208:209], v[88:89], v[230:231], v[234:235] op_sel:[1,0,0] neg_lo:[1,0,0] neg_hi:[1,0,0]
	v_pk_fma_f32 v[210:211], v[90:91], v[230:231], v[236:237] op_sel_hi:[0,1,1] neg_lo:[1,0,0] neg_hi:[1,0,0]
	v_pk_fma_f32 v[212:213], v[90:91], v[230:231], v[238:239] op_sel:[1,0,0] neg_lo:[1,0,0] neg_hi:[1,0,0]
	ds_read_b128 v[84:87], v240 offset:9248
	ds_read_b64 v[100:101], v242 offset:44064
	ds_read_b128 v[92:95], v240 offset:26656
	ds_read_b128 v[80:83], v240 offset:544
	ds_read_b128 v[88:91], v240 offset:17952
	s_waitcnt lgkmcnt(6)
	v_pk_mul_f32 v[226:227], v[206:207], v[106:107] op_sel_hi:[1,0]
	v_pk_mul_f32 v[228:229], v[206:207], v[96:97] op_sel_hi:[1,0]
	v_pk_fma_f32 v[226:227], v[208:209], v[106:107], v[226:227] op_sel:[0,1,0]
	v_pk_fma_f32 v[228:229], v[208:209], v[96:97], v[228:229] op_sel:[0,1,0]
	v_pk_fma_f32 v[226:227], v[210:211], v[108:109], v[226:227] op_sel_hi:[1,0,1]
	v_pk_fma_f32 v[228:229], v[210:211], v[98:99], v[228:229] op_sel_hi:[1,0,1]
	v_pk_fma_f32 v[226:227], v[212:213], v[108:109], v[226:227] op_sel:[0,1,0]
	v_pk_fma_f32 v[228:229], v[212:213], v[98:99], v[228:229] op_sel:[0,1,0]
	v_pk_mul_f32 v[232:233], v[118:119], v[114:115] op_sel_hi:[1,0]
	v_add_f32_dpp v230, v227, v226 row_ror:8 row_mask:0xf bank_mask:0xf
	v_pk_mul_f32 v[234:235], v[118:119], v[114:115] op_sel:[0,1]
	v_pk_mul_f32 v[236:237], v[118:119], v[116:117] op_sel_hi:[1,0]
	v_add_f32_dpp v230, v230, v230 quad_perm:[1,0,3,2] row_mask:0xf bank_mask:0xf
	v_pk_mul_f32 v[238:239], v[118:119], v[116:117] op_sel:[0,1]
	ds_read_b128 v[96:99], v240 offset:35360
	v_add_f32_dpp v230, v230, v230 quad_perm:[2,3,0,1] row_mask:0xf bank_mask:0xf
	v_pk_fma_f32 v[232:233], v[206:207], v[102:103], v[232:233] op_sel_hi:[1,0,1]
	v_pk_fma_f32 v[234:235], v[208:209], v[102:103], v[234:235] op_sel:[0,1,0]
	v_add_f32_dpp v230, v230, v230 row_half_mirror row_mask:0xf bank_mask:0xf
	v_pk_fma_f32 v[236:237], v[210:211], v[104:105], v[236:237] op_sel_hi:[1,0,1]
	v_pk_fma_f32 v[238:239], v[212:213], v[104:105], v[238:239] op_sel:[0,1,0]
	v_mov_b32_dpp v231, v230 row_ror:8 row_mask:0xf bank_mask:0xf
	ds_write_b64 v217, v[228:229] offset:0
	v_pk_fma_f32 v[206:207], v[110:111], v[230:231], v[232:233] op_sel_hi:[0,1,1] neg_lo:[1,0,0] neg_hi:[1,0,0]
	v_pk_fma_f32 v[208:209], v[110:111], v[230:231], v[234:235] op_sel:[1,0,0] neg_lo:[1,0,0] neg_hi:[1,0,0]
	v_pk_fma_f32 v[210:211], v[112:113], v[230:231], v[236:237] op_sel_hi:[0,1,1] neg_lo:[1,0,0] neg_hi:[1,0,0]
	v_pk_fma_f32 v[212:213], v[112:113], v[230:231], v[238:239] op_sel:[1,0,0] neg_lo:[1,0,0] neg_hi:[1,0,0]
	ds_read_b128 v[106:109], v240 offset:9520
	ds_read_b64 v[118:119], v242 offset:44336
	ds_read_b128 v[114:117], v240 offset:26928
	ds_read_b128 v[102:105], v240 offset:816
	ds_read_b128 v[110:113], v240 offset:18224
	s_waitcnt lgkmcnt(7)
; template <int CTRL> __device__ __forceinline__ float dppf(float x) { return __builtin_bit_cast(float, __builtin_amdgcn_update_dpp(0, __builtin_bit_cast(int, x), CTRL, 0xF, 0xF, false)); }
; __device__ __forceinline__ void phase_rwkv_scan(const Fr& F, int jr) {
;     ...
;                     for (int pi = 0; pi < 16; ++pi) {
;                         const int p = pg + pi, pn = p < 63 ? p + 1 : 63;
;                         const f32x4 w4n = PW[pn * 16], k4n = PW[1024 + pn * 16], b4n = PW[2048 + pn * 16], d4n = PW[3072 + pn * 16], r4n = PR[pn * 16];
;                         const float vvn = PV[pn * 32];
;                         f32x2 t = S01 * k4.xy; t = S23 * k4.zw + t; float sa = t.x + t.y;
;                         sa += dppf<0x128>(sa);
;                         const f32x2 dv01 = d4.xy * vv, dv23 = d4.zw * vv;
;                         sa += dppf<0x124>(sa);
;                         const f32x2 e01 = S01 * w4.xy + dv01;
;                         sa += dppf<0x122>(sa);
;                         const f32x2 e23 = S23 * w4.zw + dv23;
;                         sa += dppf<0x121>(sa);
;                         S01 = e01 - b4.xy * sa; S23 = e23 - b4.zw * sa;
;                         f32x2 u = S01 * r4.xy; u = S23 * r4.zw + u;
;                         PY[pi * 64] = u.x + u.y;
;                         w4 = w4n; k4 = k4n; b4 = b4n; d4 = d4n; r4 = r4n; vv = vvn;
	v_pk_mul_f32 v[226:227], v[206:207], v[84:85] op_sel_hi:[1,0]
	v_pk_mul_f32 v[228:229], v[206:207], v[222:223] op_sel_hi:[1,0]
	v_pk_fma_f32 v[226:227], v[208:209], v[84:85], v[226:227] op_sel:[0,1,0]
	v_pk_fma_f32 v[228:229], v[208:209], v[222:223], v[228:229] op_sel:[0,1,0]
	v_pk_fma_f32 v[226:227], v[210:211], v[86:87], v[226:227] op_sel_hi:[1,0,1]
	v_pk_fma_f32 v[228:229], v[210:211], v[224:225], v[228:229] op_sel_hi:[1,0,1]
	v_pk_fma_f32 v[226:227], v[212:213], v[86:87], v[226:227] op_sel:[0,1,0]
	v_pk_fma_f32 v[228:229], v[212:213], v[224:225], v[228:229] op_sel:[0,1,0]
	v_pk_mul_f32 v[232:233], v[100:101], v[92:93] op_sel_hi:[1,0]
	v_add_f32_dpp v230, v227, v226 row_ror:8 row_mask:0xf bank_mask:0xf
	v_pk_mul_f32 v[234:235], v[100:101], v[92:93] op_sel:[0,1]
	v_pk_mul_f32 v[236:237], v[100:101], v[94:95] op_sel_hi:[1,0]
	v_add_f32_dpp v230, v230, v230 quad_perm:[1,0,3,2] row_mask:0xf bank_mask:0xf
	v_pk_mul_f32 v[238:239], v[100:101], v[94:95] op_sel:[0,1]
	ds_read_b128 v[222:225], v240 offset:35632
	v_add_f32_dpp v230, v230, v230 quad_perm:[2,3,0,1] row_mask:0xf bank_mask:0xf
	v_pk_fma_f32 v[232:233], v[206:207], v[80:81], v[232:233] op_sel_hi:[1,0,1]
	v_pk_fma_f32 v[234:235], v[208:209], v[80:81], v[234:235] op_sel:[0,1,0]
	v_add_f32_dpp v230, v230, v230 row_half_mirror row_mask:0xf bank_mask:0xf
	v_pk_fma_f32 v[236:237], v[210:211], v[82:83], v[236:237] op_sel_hi:[1,0,1]
	v_pk_fma_f32 v[238:239], v[212:213], v[82:83], v[238:239] op_sel:[0,1,0]
	v_mov_b32_dpp v231, v230 row_ror:8 row_mask:0xf bank_mask:0xf
	ds_write_b64 v217, v[228:229] offset:576
	v_pk_fma_f32 v[206:207], v[88:89], v[230:231], v[232:233] op_sel_hi:[0,1,1] neg_lo:[1,0,0] neg_hi:[1,0,0]
	v_pk_fma_f32 v[208:209], v[88:89], v[230:231], v[234:235] op_sel:[1,0,0] neg_lo:[1,0,0] neg_hi:[1,0,0]
	v_pk_fma_f32 v[210:211], v[90:91], v[230:231], v[236:237] op_sel_hi:[0,1,1] neg_lo:[1,0,0] neg_hi:[1,0,0]
	v_pk_fma_f32 v[212:213], v[90:91], v[230:231], v[238:239] op_sel:[1,0,0] neg_lo:[1,0,0] neg_hi:[1,0,0]
	ds_read_b128 v[84:87], v240 offset:9792
	ds_read_b64 v[100:101], v242 offset:44608
	ds_read_b128 v[92:95], v240 offset:27200
	ds_read_b128 v[80:83], v240 offset:1088
	ds_read_b128 v[88:91], v240 offset:18496
	s_waitcnt lgkmcnt(7)
	v_pk_mul_f32 v[226:227], v[206:207], v[106:107] op_sel_hi:[1,0]
	v_pk_mul_f32 v[228:229], v[206:207], v[96:97] op_sel_hi:[1,0]
	v_pk_fma_f32 v[226:227], v[208:209], v[106:107], v[226:227] op_sel:[0,1,0]
	v_pk_fma_f32 v[228:229], v[208:209], v[96:97], v[228:229] op_sel:[0,1,0]
	v_pk_fma_f32 v[226:227], v[210:211], v[108:109], v[226:227] op_sel_hi:[1,0,1]
	v_pk_fma_f32 v[228:229], v[210:211], v[98:99], v[228:229] op_sel_hi:[1,0,1]
	v_pk_fma_f32 v[226:227], v[212:213], v[108:109], v[226:227] op_sel:[0,1,0]
	v_pk_fma_f32 v[228:229], v[212:213], v[98:99], v[228:229] op_sel:[0,1,0]
	v_pk_mul_f32 v[232:233], v[118:119], v[114:115] op_sel_hi:[1,0]
	v_add_f32_dpp v230, v227, v226 row_ror:8 row_mask:0xf bank_mask:0xf
	v_pk_mul_f32 v[234:235], v[118:119], v[114:115] op_sel:[0,1]
	v_pk_mul_f32 v[236:237], v[118:119], v[116:117] op_sel_hi:[1,0]
	v_add_f32_dpp v230, v230, v230 quad_perm:[1,0,3,2] row_mask:0xf bank_mask:0xf
	v_pk_mul_f32 v[238:239], v[118:119], v[116:117] op_sel:[0,1]
	ds_read_b128 v[96:99], v240 offset:35904
	v_add_f32_dpp v230, v230, v230 quad_perm:[2,3,0,1] row_mask:0xf bank_mask:0xf
	v_pk_fma_f32 v[232:233], v[206:207], v[102:103], v[232:233] op_sel_hi:[1,0,1]
	v_pk_fma_f32 v[234:235], v[208:209], v[102:103], v[234:235] op_sel:[0,1,0]
	v_add_f32_dpp v230, v230, v230 row_half_mirror row_mask:0xf bank_mask:0xf
	v_pk_fma_f32 v[236:237], v[210:211], v[104:105], v[236:237] op_sel_hi:[1,0,1]
	v_pk_fma_f32 v[238:239], v[212:213], v[104:105], v[238:239] op_sel:[0,1,0]
	v_mov_b32_dpp v231, v230 row_ror:8 row_mask:0xf bank_mask:0xf
	ds_write_b64 v217, v[228:229] offset:1152
	v_pk_fma_f32 v[206:207], v[110:111], v[230:231], v[232:233] op_sel_hi:[0,1,1] neg_lo:[1,0,0] neg_hi:[1,0,0]
	v_pk_fma_f32 v[208:209], v[110:111], v[230:231], v[234:235] op_sel:[1,0,0] neg_lo:[1,0,0] neg_hi:[1,0,0]
	v_pk_fma_f32 v[210:211], v[112:113], v[230:231], v[236:237] op_sel_hi:[0,1,1] neg_lo:[1,0,0] neg_hi:[1,0,0]
	v_pk_fma_f32 v[212:213], v[112:113], v[230:231], v[238:239] op_sel:[1,0,0] neg_lo:[1,0,0] neg_hi:[1,0,0]
	ds_read_b128 v[106:109], v240 offset:10064
	ds_read_b64 v[118:119], v242 offset:44880
	ds_read_b128 v[114:117], v240 offset:27472
	ds_read_b128 v[102:105], v240 offset:1360
	ds_read_b128 v[110:113], v240 offset:18768
	s_waitcnt lgkmcnt(7)
	v_pk_mul_f32 v[226:227], v[206:207], v[84:85] op_sel_hi:[1,0]
	v_pk_mul_f32 v[228:229], v[206:207], v[222:223] op_sel_hi:[1,0]
	v_pk_fma_f32 v[226:227], v[208:209], v[84:85], v[226:227] op_sel:[0,1,0]
	v_pk_fma_f32 v[228:229], v[208:209], v[222:223], v[228:229] op_sel:[0,1,0]
	v_pk_fma_f32 v[226:227], v[210:211], v[86:87], v[226:227] op_sel_hi:[1,0,1]
	v_pk_fma_f32 v[228:229], v[210:211], v[224:225], v[228:229] op_sel_hi:[1,0,1]
	v_pk_fma_f32 v[226:227], v[212:213], v[86:87], v[226:227] op_sel:[0,1,0]
	v_pk_fma_f32 v[228:229], v[212:213], v[224:225], v[228:229] op_sel:[0,1,0]
	v_pk_mul_f32 v[232:233], v[100:101], v[92:93] op_sel_hi:[1,0]
	v_add_f32_dpp v230, v227, v226 row_ror:8 row_mask:0xf bank_mask:0xf
	v_pk_mul_f32 v[234:235], v[100:101], v[92:93] op_sel:[0,1]
	v_pk_mul_f32 v[236:237], v[100:101], v[94:95] op_sel_hi:[1,0]
	v_add_f32_dpp v230, v230, v230 quad_perm:[1,0,3,2] row_mask:0xf bank_mask:0xf
	v_pk_mul_f32 v[238:239], v[100:101], v[94:95] op_sel:[0,1]
	ds_read_b128 v[222:225], v240 offset:36176
	v_add_f32_dpp v230, v230, v230 quad_perm:[2,3,0,1] row_mask:0xf bank_mask:0xf
	v_pk_fma_f32 v[232:233], v[206:207], v[80:81], v[232:233] op_sel_hi:[1,0,1]
	v_pk_fma_f32 v[234:235], v[208:209], v[80:81], v[234:235] op_sel:[0,1,0]
	v_add_f32_dpp v230, v230, v230 row_half_mirror row_mask:0xf bank_mask:0xf
	v_pk_fma_f32 v[236:237], v[210:211], v[82:83], v[236:237] op_sel_hi:[1,0,1]
	v_pk_fma_f32 v[238:239], v[212:213], v[82:83], v[238:239] op_sel:[0,1,0]
	v_mov_b32_dpp v231, v230 row_ror:8 row_mask:0xf bank_mask:0xf
	ds_write_b64 v217, v[228:229] offset:1728
	v_pk_fma_f32 v[206:207], v[88:89], v[230:231], v[232:233] op_sel_hi:[0,1,1] neg_lo:[1,0,0] neg_hi:[1,0,0]
	v_pk_fma_f32 v[208:209], v[88:89], v[230:231], v[234:235] op_sel:[1,0,0] neg_lo:[1,0,0] neg_hi:[1,0,0]
	v_pk_fma_f32 v[210:211], v[90:91], v[230:231], v[236:237] op_sel_hi:[0,1,1] neg_lo:[1,0,0] neg_hi:[1,0,0]
	v_pk_fma_f32 v[212:213], v[90:91], v[230:231], v[238:239] op_sel:[1,0,0] neg_lo:[1,0,0] neg_hi:[1,0,0]
	ds_read_b128 v[84:87], v240 offset:10336
	ds_read_b64 v[100:101], v242 offset:45152
	ds_read_b128 v[92:95], v240 offset:27744
	ds_read_b128 v[80:83], v240 offset:1632
	ds_read_b128 v[88:91], v240 offset:19040
	s_waitcnt lgkmcnt(7)
; template <int CTRL> __device__ __forceinline__ float dppf(float x) { return __builtin_bit_cast(float, __builtin_amdgcn_update_dpp(0, __builtin_bit_cast(int, x), CTRL, 0xF, 0xF, false)); }
; __device__ __forceinline__ void phase_rwkv_scan(const Fr& F, int jr) {
;     ...
;                     for (int pi = 0; pi < 16; ++pi) {
;                         const int p = pg + pi, pn = p < 63 ? p + 1 : 63;
;                         const f32x4 w4n = PW[pn * 16], k4n = PW[1024 + pn * 16], b4n = PW[2048 + pn * 16], d4n = PW[3072 + pn * 16], r4n = PR[pn * 16];
;                         const float vvn = PV[pn * 32];
;                         f32x2 t = S01 * k4.xy; t = S23 * k4.zw + t; float sa = t.x + t.y;
;                         sa += dppf<0x128>(sa);
;                         const f32x2 dv01 = d4.xy * vv, dv23 = d4.zw * vv;
;                         sa += dppf<0x124>(sa);
;                         const f32x2 e01 = S01 * w4.xy + dv01;
;                         sa += dppf<0x122>(sa);
;                         const f32x2 e23 = S23 * w4.zw + dv23;
;                         sa += dppf<0x121>(sa);
;                         S01 = e01 - b4.xy * sa; S23 = e23 - b4.zw * sa;
;                         f32x2 u = S01 * r4.xy; u = S23 * r4.zw + u;
;                         PY[pi * 64] = u.x + u.y;
;                         w4 = w4n; k4 = k4n; b4 = b4n; d4 = d4n; r4 = r4n; vv = vvn;
	v_pk_mul_f32 v[226:227], v[206:207], v[106:107] op_sel_hi:[1,0]
	v_pk_mul_f32 v[228:229], v[206:207], v[96:97] op_sel_hi:[1,0]
	v_pk_fma_f32 v[226:227], v[208:209], v[106:107], v[226:227] op_sel:[0,1,0]
	v_pk_fma_f32 v[228:229], v[208:209], v[96:97], v[228:229] op_sel:[0,1,0]
	v_pk_fma_f32 v[226:227], v[210:211], v[108:109], v[226:227] op_sel_hi:[1,0,1]
	v_pk_fma_f32 v[228:229], v[210:211], v[98:99], v[228:229] op_sel_hi:[1,0,1]
	v_pk_fma_f32 v[226:227], v[212:213], v[108:109], v[226:227] op_sel:[0,1,0]
	v_pk_fma_f32 v[228:229], v[212:213], v[98:99], v[228:229] op_sel:[0,1,0]
	v_pk_mul_f32 v[232:233], v[118:119], v[114:115] op_sel_hi:[1,0]
	v_add_f32_dpp v230, v227, v226 row_ror:8 row_mask:0xf bank_mask:0xf
	v_pk_mul_f32 v[234:235], v[118:119], v[114:115] op_sel:[0,1]
	v_pk_mul_f32 v[236:237], v[118:119], v[116:117] op_sel_hi:[1,0]
	v_add_f32_dpp v230, v230, v230 quad_perm:[1,0,3,2] row_mask:0xf bank_mask:0xf
	v_pk_mul_f32 v[238:239], v[118:119], v[116:117] op_sel:[0,1]
	ds_read_b128 v[96:99], v240 offset:36448
	v_add_f32_dpp v230, v230, v230 quad_perm:[2,3,0,1] row_mask:0xf bank_mask:0xf
	v_pk_fma_f32 v[232:233], v[206:207], v[102:103], v[232:233] op_sel_hi:[1,0,1]
	v_pk_fma_f32 v[234:235], v[208:209], v[102:103], v[234:235] op_sel:[0,1,0]
	v_add_f32_dpp v230, v230, v230 row_half_mirror row_mask:0xf bank_mask:0xf
	v_pk_fma_f32 v[236:237], v[210:211], v[104:105], v[236:237] op_sel_hi:[1,0,1]
	v_pk_fma_f32 v[238:239], v[212:213], v[104:105], v[238:239] op_sel:[0,1,0]
	v_mov_b32_dpp v231, v230 row_ror:8 row_mask:0xf bank_mask:0xf
	ds_write_b64 v217, v[228:229] offset:2304
	v_pk_fma_f32 v[206:207], v[110:111], v[230:231], v[232:233] op_sel_hi:[0,1,1] neg_lo:[1,0,0] neg_hi:[1,0,0]
	v_pk_fma_f32 v[208:209], v[110:111], v[230:231], v[234:235] op_sel:[1,0,0] neg_lo:[1,0,0] neg_hi:[1,0,0]
	v_pk_fma_f32 v[210:211], v[112:113], v[230:231], v[236:237] op_sel_hi:[0,1,1] neg_lo:[1,0,0] neg_hi:[1,0,0]
	v_pk_fma_f32 v[212:213], v[112:113], v[230:231], v[238:239] op_sel:[1,0,0] neg_lo:[1,0,0] neg_hi:[1,0,0]
	ds_read_b128 v[106:109], v240 offset:10608
	ds_read_b64 v[118:119], v242 offset:45424
	ds_read_b128 v[114:117], v240 offset:28016
	ds_read_b128 v[102:105], v240 offset:1904
	ds_read_b128 v[110:113], v240 offset:19312
	s_waitcnt lgkmcnt(7)
	v_pk_mul_f32 v[226:227], v[206:207], v[84:85] op_sel_hi:[1,0]
	v_pk_mul_f32 v[228:229], v[206:207], v[222:223] op_sel_hi:[1,0]
	v_pk_fma_f32 v[226:227], v[208:209], v[84:85], v[226:227] op_sel:[0,1,0]
	v_pk_fma_f32 v[228:229], v[208:209], v[222:223], v[228:229] op_sel:[0,1,0]
	v_pk_fma_f32 v[226:227], v[210:211], v[86:87], v[226:227] op_sel_hi:[1,0,1]
	v_pk_fma_f32 v[228:229], v[210:211], v[224:225], v[228:229] op_sel_hi:[1,0,1]
	v_pk_fma_f32 v[226:227], v[212:213], v[86:87], v[226:227] op_sel:[0,1,0]
	v_pk_fma_f32 v[228:229], v[212:213], v[224:225], v[228:229] op_sel:[0,1,0]
	v_pk_mul_f32 v[232:233], v[100:101], v[92:93] op_sel_hi:[1,0]
	v_add_f32_dpp v230, v227, v226 row_ror:8 row_mask:0xf bank_mask:0xf
	v_pk_mul_f32 v[234:235], v[100:101], v[92:93] op_sel:[0,1]
	v_pk_mul_f32 v[236:237], v[100:101], v[94:95] op_sel_hi:[1,0]
	v_add_f32_dpp v230, v230, v230 quad_perm:[1,0,3,2] row_mask:0xf bank_mask:0xf
	v_pk_mul_f32 v[238:239], v[100:101], v[94:95] op_sel:[0,1]
	ds_read_b128 v[222:225], v240 offset:36720
	v_add_f32_dpp v230, v230, v230 quad_perm:[2,3,0,1] row_mask:0xf bank_mask:0xf
	v_pk_fma_f32 v[232:233], v[206:207], v[80:81], v[232:233] op_sel_hi:[1,0,1]
	v_pk_fma_f32 v[234:235], v[208:209], v[80:81], v[234:235] op_sel:[0,1,0]
	v_add_f32_dpp v230, v230, v230 row_half_mirror row_mask:0xf bank_mask:0xf
	v_pk_fma_f32 v[236:237], v[210:211], v[82:83], v[236:237] op_sel_hi:[1,0,1]
	v_pk_fma_f32 v[238:239], v[212:213], v[82:83], v[238:239] op_sel:[0,1,0]
	v_mov_b32_dpp v231, v230 row_ror:8 row_mask:0xf bank_mask:0xf
	ds_write_b64 v217, v[228:229] offset:2880
	v_pk_fma_f32 v[206:207], v[88:89], v[230:231], v[232:233] op_sel_hi:[0,1,1] neg_lo:[1,0,0] neg_hi:[1,0,0]
	v_pk_fma_f32 v[208:209], v[88:89], v[230:231], v[234:235] op_sel:[1,0,0] neg_lo:[1,0,0] neg_hi:[1,0,0]
	v_pk_fma_f32 v[210:211], v[90:91], v[230:231], v[236:237] op_sel_hi:[0,1,1] neg_lo:[1,0,0] neg_hi:[1,0,0]
	v_pk_fma_f32 v[212:213], v[90:91], v[230:231], v[238:239] op_sel:[1,0,0] neg_lo:[1,0,0] neg_hi:[1,0,0]
	ds_read_b128 v[84:87], v240 offset:10880
	ds_read_b64 v[100:101], v242 offset:45696
	ds_read_b128 v[92:95], v240 offset:28288
	ds_read_b128 v[80:83], v240 offset:2176
	ds_read_b128 v[88:91], v240 offset:19584
	s_waitcnt lgkmcnt(7)
; template <int CTRL> __device__ __forceinline__ float dppf(float x) { return __builtin_bit_cast(float, __builtin_amdgcn_update_dpp(0, __builtin_bit_cast(int, x), CTRL, 0xF, 0xF, false)); }
; __device__ __forceinline__ void phase_rwkv_scan(const Fr& F, int jr) {
;     ...
;                     for (int pi = 0; pi < 16; ++pi) {
;                         const int p = pg + pi, pn = p < 63 ? p + 1 : 63;
;                         const f32x4 w4n = PW[pn * 16], k4n = PW[1024 + pn * 16], b4n = PW[2048 + pn * 16], d4n = PW[3072 + pn * 16], r4n = PR[pn * 16];
;                         const float vvn = PV[pn * 32];
;                         f32x2 t = S01 * k4.xy; t = S23 * k4.zw + t; float sa = t.x + t.y;
;                         sa += dppf<0x128>(sa);
;                         const f32x2 dv01 = d4.xy * vv, dv23 = d4.zw * vv;
;                         sa += dppf<0x124>(sa);
;                         const f32x2 e01 = S01 * w4.xy + dv01;
;                         sa += dppf<0x122>(sa);
;                         const f32x2 e23 = S23 * w4.zw + dv23;
;                         sa += dppf<0x121>(sa);
;                         S01 = e01 - b4.xy * sa; S23 = e23 - b4.zw * sa;
;                         f32x2 u = S01 * r4.xy; u = S23 * r4.zw + u;
;                         PY[pi * 64] = u.x + u.y;
;                         w4 = w4n; k4 = k4n; b4 = b4n; d4 = d4n; r4 = r4n; vv = vvn;
	v_pk_mul_f32 v[226:227], v[206:207], v[106:107] op_sel_hi:[1,0]
	v_pk_mul_f32 v[228:229], v[206:207], v[96:97] op_sel_hi:[1,0]
	v_pk_fma_f32 v[226:227], v[208:209], v[106:107], v[226:227] op_sel:[0,1,0]
	v_pk_fma_f32 v[228:229], v[208:209], v[96:97], v[228:229] op_sel:[0,1,0]
	v_pk_fma_f32 v[226:227], v[210:211], v[108:109], v[226:227] op_sel_hi:[1,0,1]
	v_pk_fma_f32 v[228:229], v[210:211], v[98:99], v[228:229] op_sel_hi:[1,0,1]
	v_pk_fma_f32 v[226:227], v[212:213], v[108:109], v[226:227] op_sel:[0,1,0]
	v_pk_fma_f32 v[228:229], v[212:213], v[98:99], v[228:229] op_sel:[0,1,0]
	v_pk_mul_f32 v[232:233], v[118:119], v[114:115] op_sel_hi:[1,0]
	v_add_f32_dpp v230, v227, v226 row_ror:8 row_mask:0xf bank_mask:0xf
	v_pk_mul_f32 v[234:235], v[118:119], v[114:115] op_sel:[0,1]
	v_pk_mul_f32 v[236:237], v[118:119], v[116:117] op_sel_hi:[1,0]
	v_add_f32_dpp v230, v230, v230 quad_perm:[1,0,3,2] row_mask:0xf bank_mask:0xf
	v_pk_mul_f32 v[238:239], v[118:119], v[116:117] op_sel:[0,1]
	ds_read_b128 v[96:99], v240 offset:36992
	v_add_f32_dpp v230, v230, v230 quad_perm:[2,3,0,1] row_mask:0xf bank_mask:0xf
	v_pk_fma_f32 v[232:233], v[206:207], v[102:103], v[232:233] op_sel_hi:[1,0,1]
	v_pk_fma_f32 v[234:235], v[208:209], v[102:103], v[234:235] op_sel:[0,1,0]
	v_add_f32_dpp v230, v230, v230 row_half_mirror row_mask:0xf bank_mask:0xf
	v_pk_fma_f32 v[236:237], v[210:211], v[104:105], v[236:237] op_sel_hi:[1,0,1]
	v_pk_fma_f32 v[238:239], v[212:213], v[104:105], v[238:239] op_sel:[0,1,0]
	v_mov_b32_dpp v231, v230 row_ror:8 row_mask:0xf bank_mask:0xf
	ds_write_b64 v217, v[228:229] offset:3456
	v_pk_fma_f32 v[206:207], v[110:111], v[230:231], v[232:233] op_sel_hi:[0,1,1] neg_lo:[1,0,0] neg_hi:[1,0,0]
	v_pk_fma_f32 v[208:209], v[110:111], v[230:231], v[234:235] op_sel:[1,0,0] neg_lo:[1,0,0] neg_hi:[1,0,0]
	v_pk_fma_f32 v[210:211], v[112:113], v[230:231], v[236:237] op_sel_hi:[0,1,1] neg_lo:[1,0,0] neg_hi:[1,0,0]
	v_pk_fma_f32 v[212:213], v[112:113], v[230:231], v[238:239] op_sel:[1,0,0] neg_lo:[1,0,0] neg_hi:[1,0,0]
	ds_read_b128 v[106:109], v240 offset:11152
	ds_read_b64 v[118:119], v242 offset:45968
	ds_read_b128 v[114:117], v240 offset:28560
	ds_read_b128 v[102:105], v240 offset:2448
	ds_read_b128 v[110:113], v240 offset:19856
	s_waitcnt lgkmcnt(7)
	v_pk_mul_f32 v[226:227], v[206:207], v[84:85] op_sel_hi:[1,0]
	v_pk_mul_f32 v[228:229], v[206:207], v[222:223] op_sel_hi:[1,0]
	v_pk_fma_f32 v[226:227], v[208:209], v[84:85], v[226:227] op_sel:[0,1,0]
	v_pk_fma_f32 v[228:229], v[208:209], v[222:223], v[228:229] op_sel:[0,1,0]
	v_pk_fma_f32 v[226:227], v[210:211], v[86:87], v[226:227] op_sel_hi:[1,0,1]
	v_pk_fma_f32 v[228:229], v[210:211], v[224:225], v[228:229] op_sel_hi:[1,0,1]
	v_pk_fma_f32 v[226:227], v[212:213], v[86:87], v[226:227] op_sel:[0,1,0]
	v_pk_fma_f32 v[228:229], v[212:213], v[224:225], v[228:229] op_sel:[0,1,0]
	v_pk_mul_f32 v[232:233], v[100:101], v[92:93] op_sel_hi:[1,0]
	v_add_f32_dpp v230, v227, v226 row_ror:8 row_mask:0xf bank_mask:0xf
	v_pk_mul_f32 v[234:235], v[100:101], v[92:93] op_sel:[0,1]
	v_pk_mul_f32 v[236:237], v[100:101], v[94:95] op_sel_hi:[1,0]
	v_add_f32_dpp v230, v230, v230 quad_perm:[1,0,3,2] row_mask:0xf bank_mask:0xf
	v_pk_mul_f32 v[238:239], v[100:101], v[94:95] op_sel:[0,1]
	ds_read_b128 v[222:225], v240 offset:37264
	v_add_f32_dpp v230, v230, v230 quad_perm:[2,3,0,1] row_mask:0xf bank_mask:0xf
	v_pk_fma_f32 v[232:233], v[206:207], v[80:81], v[232:233] op_sel_hi:[1,0,1]
	v_pk_fma_f32 v[234:235], v[208:209], v[80:81], v[234:235] op_sel:[0,1,0]
	v_add_f32_dpp v230, v230, v230 row_half_mirror row_mask:0xf bank_mask:0xf
	v_pk_fma_f32 v[236:237], v[210:211], v[82:83], v[236:237] op_sel_hi:[1,0,1]
	v_pk_fma_f32 v[238:239], v[212:213], v[82:83], v[238:239] op_sel:[0,1,0]
	v_mov_b32_dpp v231, v230 row_ror:8 row_mask:0xf bank_mask:0xf
	ds_write_b64 v217, v[228:229] offset:4032
	v_pk_fma_f32 v[206:207], v[88:89], v[230:231], v[232:233] op_sel_hi:[0,1,1] neg_lo:[1,0,0] neg_hi:[1,0,0]
	v_pk_fma_f32 v[208:209], v[88:89], v[230:231], v[234:235] op_sel:[1,0,0] neg_lo:[1,0,0] neg_hi:[1,0,0]
	v_pk_fma_f32 v[210:211], v[90:91], v[230:231], v[236:237] op_sel_hi:[0,1,1] neg_lo:[1,0,0] neg_hi:[1,0,0]
	v_pk_fma_f32 v[212:213], v[90:91], v[230:231], v[238:239] op_sel:[1,0,0] neg_lo:[1,0,0] neg_hi:[1,0,0]
	ds_read_b128 v[84:87], v240 offset:11424
	ds_read_b64 v[100:101], v242 offset:46240
	ds_read_b128 v[92:95], v240 offset:28832
	ds_read_b128 v[80:83], v240 offset:2720
	ds_read_b128 v[88:91], v240 offset:20128
	s_waitcnt lgkmcnt(7)
; template <int CTRL> __device__ __forceinline__ float dppf(float x) { return __builtin_bit_cast(float, __builtin_amdgcn_update_dpp(0, __builtin_bit_cast(int, x), CTRL, 0xF, 0xF, false)); }
; __device__ __forceinline__ void phase_rwkv_scan(const Fr& F, int jr) {
;     ...
;                     for (int pi = 0; pi < 16; ++pi) {
;                         const int p = pg + pi, pn = p < 63 ? p + 1 : 63;
;                         const f32x4 w4n = PW[pn * 16], k4n = PW[1024 + pn * 16], b4n = PW[2048 + pn * 16], d4n = PW[3072 + pn * 16], r4n = PR[pn * 16];
;                         const float vvn = PV[pn * 32];
;                         f32x2 t = S01 * k4.xy; t = S23 * k4.zw + t; float sa = t.x + t.y;
;                         sa += dppf<0x128>(sa);
;                         const f32x2 dv01 = d4.xy * vv, dv23 = d4.zw * vv;
;                         sa += dppf<0x124>(sa);
;                         const f32x2 e01 = S01 * w4.xy + dv01;
;                         sa += dppf<0x122>(sa);
;                         const f32x2 e23 = S23 * w4.zw + dv23;
;                         sa += dppf<0x121>(sa);
;                         S01 = e01 - b4.xy * sa; S23 = e23 - b4.zw * sa;
;                         f32x2 u = S01 * r4.xy; u = S23 * r4.zw + u;
;                         PY[pi * 64] = u.x + u.y;
;                         w4 = w4n; k4 = k4n; b4 = b4n; d4 = d4n; r4 = r4n; vv = vvn;
	v_pk_mul_f32 v[226:227], v[206:207], v[106:107] op_sel_hi:[1,0]
	v_pk_mul_f32 v[228:229], v[206:207], v[96:97] op_sel_hi:[1,0]
	v_pk_fma_f32 v[226:227], v[208:209], v[106:107], v[226:227] op_sel:[0,1,0]
	v_pk_fma_f32 v[228:229], v[208:209], v[96:97], v[228:229] op_sel:[0,1,0]
	v_pk_fma_f32 v[226:227], v[210:211], v[108:109], v[226:227] op_sel_hi:[1,0,1]
	v_pk_fma_f32 v[228:229], v[210:211], v[98:99], v[228:229] op_sel_hi:[1,0,1]
	v_pk_fma_f32 v[226:227], v[212:213], v[108:109], v[226:227] op_sel:[0,1,0]
	v_pk_fma_f32 v[228:229], v[212:213], v[98:99], v[228:229] op_sel:[0,1,0]
	v_pk_mul_f32 v[232:233], v[118:119], v[114:115] op_sel_hi:[1,0]
	v_add_f32_dpp v230, v227, v226 row_ror:8 row_mask:0xf bank_mask:0xf
	v_pk_mul_f32 v[234:235], v[118:119], v[114:115] op_sel:[0,1]
	v_pk_mul_f32 v[236:237], v[118:119], v[116:117] op_sel_hi:[1,0]
	v_add_f32_dpp v230, v230, v230 quad_perm:[1,0,3,2] row_mask:0xf bank_mask:0xf
	v_pk_mul_f32 v[238:239], v[118:119], v[116:117] op_sel:[0,1]
	ds_read_b128 v[96:99], v240 offset:37536
	v_add_f32_dpp v230, v230, v230 quad_perm:[2,3,0,1] row_mask:0xf bank_mask:0xf
	v_pk_fma_f32 v[232:233], v[206:207], v[102:103], v[232:233] op_sel_hi:[1,0,1]
	v_pk_fma_f32 v[234:235], v[208:209], v[102:103], v[234:235] op_sel:[0,1,0]
	v_add_f32_dpp v230, v230, v230 row_half_mirror row_mask:0xf bank_mask:0xf
	v_pk_fma_f32 v[236:237], v[210:211], v[104:105], v[236:237] op_sel_hi:[1,0,1]
	v_pk_fma_f32 v[238:239], v[212:213], v[104:105], v[238:239] op_sel:[0,1,0]
	v_mov_b32_dpp v231, v230 row_ror:8 row_mask:0xf bank_mask:0xf
	ds_write_b64 v217, v[228:229] offset:4608
	v_pk_fma_f32 v[206:207], v[110:111], v[230:231], v[232:233] op_sel_hi:[0,1,1] neg_lo:[1,0,0] neg_hi:[1,0,0]
	v_pk_fma_f32 v[208:209], v[110:111], v[230:231], v[234:235] op_sel:[1,0,0] neg_lo:[1,0,0] neg_hi:[1,0,0]
	v_pk_fma_f32 v[210:211], v[112:113], v[230:231], v[236:237] op_sel_hi:[0,1,1] neg_lo:[1,0,0] neg_hi:[1,0,0]
	v_pk_fma_f32 v[212:213], v[112:113], v[230:231], v[238:239] op_sel:[1,0,0] neg_lo:[1,0,0] neg_hi:[1,0,0]
	ds_read_b128 v[106:109], v240 offset:11696
	ds_read_b64 v[118:119], v242 offset:46512
	ds_read_b128 v[114:117], v240 offset:29104
	ds_read_b128 v[102:105], v240 offset:2992
	ds_read_b128 v[110:113], v240 offset:20400
	s_waitcnt lgkmcnt(7)
	v_pk_mul_f32 v[226:227], v[206:207], v[84:85] op_sel_hi:[1,0]
	v_pk_mul_f32 v[228:229], v[206:207], v[222:223] op_sel_hi:[1,0]
	v_pk_fma_f32 v[226:227], v[208:209], v[84:85], v[226:227] op_sel:[0,1,0]
	v_pk_fma_f32 v[228:229], v[208:209], v[222:223], v[228:229] op_sel:[0,1,0]
	v_pk_fma_f32 v[226:227], v[210:211], v[86:87], v[226:227] op_sel_hi:[1,0,1]
	v_pk_fma_f32 v[228:229], v[210:211], v[224:225], v[228:229] op_sel_hi:[1,0,1]
	v_pk_fma_f32 v[226:227], v[212:213], v[86:87], v[226:227] op_sel:[0,1,0]
	v_pk_fma_f32 v[228:229], v[212:213], v[224:225], v[228:229] op_sel:[0,1,0]
	v_pk_mul_f32 v[232:233], v[100:101], v[92:93] op_sel_hi:[1,0]
	v_add_f32_dpp v230, v227, v226 row_ror:8 row_mask:0xf bank_mask:0xf
	v_pk_mul_f32 v[234:235], v[100:101], v[92:93] op_sel:[0,1]
	v_pk_mul_f32 v[236:237], v[100:101], v[94:95] op_sel_hi:[1,0]
	v_add_f32_dpp v230, v230, v230 quad_perm:[1,0,3,2] row_mask:0xf bank_mask:0xf
	v_pk_mul_f32 v[238:239], v[100:101], v[94:95] op_sel:[0,1]
	ds_read_b128 v[222:225], v240 offset:37808
	v_add_f32_dpp v230, v230, v230 quad_perm:[2,3,0,1] row_mask:0xf bank_mask:0xf
	v_pk_fma_f32 v[232:233], v[206:207], v[80:81], v[232:233] op_sel_hi:[1,0,1]
	v_pk_fma_f32 v[234:235], v[208:209], v[80:81], v[234:235] op_sel:[0,1,0]
	v_add_f32_dpp v230, v230, v230 row_half_mirror row_mask:0xf bank_mask:0xf
	v_pk_fma_f32 v[236:237], v[210:211], v[82:83], v[236:237] op_sel_hi:[1,0,1]
	v_pk_fma_f32 v[238:239], v[212:213], v[82:83], v[238:239] op_sel:[0,1,0]
	v_mov_b32_dpp v231, v230 row_ror:8 row_mask:0xf bank_mask:0xf
	ds_write_b64 v217, v[228:229] offset:5184
	v_pk_fma_f32 v[206:207], v[88:89], v[230:231], v[232:233] op_sel_hi:[0,1,1] neg_lo:[1,0,0] neg_hi:[1,0,0]
	v_pk_fma_f32 v[208:209], v[88:89], v[230:231], v[234:235] op_sel:[1,0,0] neg_lo:[1,0,0] neg_hi:[1,0,0]
	v_pk_fma_f32 v[210:211], v[90:91], v[230:231], v[236:237] op_sel_hi:[0,1,1] neg_lo:[1,0,0] neg_hi:[1,0,0]
	v_pk_fma_f32 v[212:213], v[90:91], v[230:231], v[238:239] op_sel:[1,0,0] neg_lo:[1,0,0] neg_hi:[1,0,0]
	ds_read_b128 v[84:87], v240 offset:11968
	ds_read_b64 v[100:101], v242 offset:46784
	ds_read_b128 v[92:95], v240 offset:29376
	ds_read_b128 v[80:83], v240 offset:3264
	ds_read_b128 v[88:91], v240 offset:20672
	s_waitcnt lgkmcnt(7)
; template <int CTRL> __device__ __forceinline__ float dppf(float x) { return __builtin_bit_cast(float, __builtin_amdgcn_update_dpp(0, __builtin_bit_cast(int, x), CTRL, 0xF, 0xF, false)); }
; __device__ __forceinline__ void phase_rwkv_scan(const Fr& F, int jr) {
;     ...
;                     for (int pi = 0; pi < 16; ++pi) {
;                         const int p = pg + pi, pn = p < 63 ? p + 1 : 63;
;                         const f32x4 w4n = PW[pn * 16], k4n = PW[1024 + pn * 16], b4n = PW[2048 + pn * 16], d4n = PW[3072 + pn * 16], r4n = PR[pn * 16];
;                         const float vvn = PV[pn * 32];
;                         f32x2 t = S01 * k4.xy; t = S23 * k4.zw + t; float sa = t.x + t.y;
;                         sa += dppf<0x128>(sa);
;                         const f32x2 dv01 = d4.xy * vv, dv23 = d4.zw * vv;
;                         sa += dppf<0x124>(sa);
;                         const f32x2 e01 = S01 * w4.xy + dv01;
;                         sa += dppf<0x122>(sa);
;                         const f32x2 e23 = S23 * w4.zw + dv23;
;                         sa += dppf<0x121>(sa);
;                         S01 = e01 - b4.xy * sa; S23 = e23 - b4.zw * sa;
;                         f32x2 u = S01 * r4.xy; u = S23 * r4.zw + u;
;                         PY[pi * 64] = u.x + u.y;
;                         w4 = w4n; k4 = k4n; b4 = b4n; d4 = d4n; r4 = r4n; vv = vvn;
	v_pk_mul_f32 v[226:227], v[206:207], v[106:107] op_sel_hi:[1,0]
	v_pk_mul_f32 v[228:229], v[206:207], v[96:97] op_sel_hi:[1,0]
	v_pk_fma_f32 v[226:227], v[208:209], v[106:107], v[226:227] op_sel:[0,1,0]
	v_pk_fma_f32 v[228:229], v[208:209], v[96:97], v[228:229] op_sel:[0,1,0]
	v_pk_fma_f32 v[226:227], v[210:211], v[108:109], v[226:227] op_sel_hi:[1,0,1]
	v_pk_fma_f32 v[228:229], v[210:211], v[98:99], v[228:229] op_sel_hi:[1,0,1]
	v_pk_fma_f32 v[226:227], v[212:213], v[108:109], v[226:227] op_sel:[0,1,0]
	v_pk_fma_f32 v[228:229], v[212:213], v[98:99], v[228:229] op_sel:[0,1,0]
	v_pk_mul_f32 v[232:233], v[118:119], v[114:115] op_sel_hi:[1,0]
	v_add_f32_dpp v230, v227, v226 row_ror:8 row_mask:0xf bank_mask:0xf
	v_pk_mul_f32 v[234:235], v[118:119], v[114:115] op_sel:[0,1]
	v_pk_mul_f32 v[236:237], v[118:119], v[116:117] op_sel_hi:[1,0]
	v_add_f32_dpp v230, v230, v230 quad_perm:[1,0,3,2] row_mask:0xf bank_mask:0xf
	v_pk_mul_f32 v[238:239], v[118:119], v[116:117] op_sel:[0,1]
	ds_read_b128 v[96:99], v240 offset:38080
	v_add_f32_dpp v230, v230, v230 quad_perm:[2,3,0,1] row_mask:0xf bank_mask:0xf
	v_pk_fma_f32 v[232:233], v[206:207], v[102:103], v[232:233] op_sel_hi:[1,0,1]
	v_pk_fma_f32 v[234:235], v[208:209], v[102:103], v[234:235] op_sel:[0,1,0]
	v_add_f32_dpp v230, v230, v230 row_half_mirror row_mask:0xf bank_mask:0xf
	v_pk_fma_f32 v[236:237], v[210:211], v[104:105], v[236:237] op_sel_hi:[1,0,1]
	v_pk_fma_f32 v[238:239], v[212:213], v[104:105], v[238:239] op_sel:[0,1,0]
	v_mov_b32_dpp v231, v230 row_ror:8 row_mask:0xf bank_mask:0xf
	ds_write_b64 v217, v[228:229] offset:5760
	v_pk_fma_f32 v[206:207], v[110:111], v[230:231], v[232:233] op_sel_hi:[0,1,1] neg_lo:[1,0,0] neg_hi:[1,0,0]
	v_pk_fma_f32 v[208:209], v[110:111], v[230:231], v[234:235] op_sel:[1,0,0] neg_lo:[1,0,0] neg_hi:[1,0,0]
	v_pk_fma_f32 v[210:211], v[112:113], v[230:231], v[236:237] op_sel_hi:[0,1,1] neg_lo:[1,0,0] neg_hi:[1,0,0]
	v_pk_fma_f32 v[212:213], v[112:113], v[230:231], v[238:239] op_sel:[1,0,0] neg_lo:[1,0,0] neg_hi:[1,0,0]
	ds_read_b128 v[106:109], v240 offset:12240
	ds_read_b64 v[118:119], v242 offset:47056
	ds_read_b128 v[114:117], v240 offset:29648
	ds_read_b128 v[102:105], v240 offset:3536
	ds_read_b128 v[110:113], v240 offset:20944
	s_waitcnt lgkmcnt(7)
	v_pk_mul_f32 v[226:227], v[206:207], v[84:85] op_sel_hi:[1,0]
	v_pk_mul_f32 v[228:229], v[206:207], v[222:223] op_sel_hi:[1,0]
	v_pk_fma_f32 v[226:227], v[208:209], v[84:85], v[226:227] op_sel:[0,1,0]
	v_pk_fma_f32 v[228:229], v[208:209], v[222:223], v[228:229] op_sel:[0,1,0]
	v_pk_fma_f32 v[226:227], v[210:211], v[86:87], v[226:227] op_sel_hi:[1,0,1]
	v_pk_fma_f32 v[228:229], v[210:211], v[224:225], v[228:229] op_sel_hi:[1,0,1]
	v_pk_fma_f32 v[226:227], v[212:213], v[86:87], v[226:227] op_sel:[0,1,0]
	v_pk_fma_f32 v[228:229], v[212:213], v[224:225], v[228:229] op_sel:[0,1,0]
	v_pk_mul_f32 v[232:233], v[100:101], v[92:93] op_sel_hi:[1,0]
	v_add_f32_dpp v230, v227, v226 row_ror:8 row_mask:0xf bank_mask:0xf
	v_pk_mul_f32 v[234:235], v[100:101], v[92:93] op_sel:[0,1]
	v_pk_mul_f32 v[236:237], v[100:101], v[94:95] op_sel_hi:[1,0]
	v_add_f32_dpp v230, v230, v230 quad_perm:[1,0,3,2] row_mask:0xf bank_mask:0xf
	v_pk_mul_f32 v[238:239], v[100:101], v[94:95] op_sel:[0,1]
	ds_read_b128 v[222:225], v240 offset:38352
	v_add_f32_dpp v230, v230, v230 quad_perm:[2,3,0,1] row_mask:0xf bank_mask:0xf
	v_pk_fma_f32 v[232:233], v[206:207], v[80:81], v[232:233] op_sel_hi:[1,0,1]
	v_pk_fma_f32 v[234:235], v[208:209], v[80:81], v[234:235] op_sel:[0,1,0]
	v_add_f32_dpp v230, v230, v230 row_half_mirror row_mask:0xf bank_mask:0xf
	v_pk_fma_f32 v[236:237], v[210:211], v[82:83], v[236:237] op_sel_hi:[1,0,1]
	v_pk_fma_f32 v[238:239], v[212:213], v[82:83], v[238:239] op_sel:[0,1,0]
	v_mov_b32_dpp v231, v230 row_ror:8 row_mask:0xf bank_mask:0xf
	ds_write_b64 v217, v[228:229] offset:6336
	v_pk_fma_f32 v[206:207], v[88:89], v[230:231], v[232:233] op_sel_hi:[0,1,1] neg_lo:[1,0,0] neg_hi:[1,0,0]
	v_pk_fma_f32 v[208:209], v[88:89], v[230:231], v[234:235] op_sel:[1,0,0] neg_lo:[1,0,0] neg_hi:[1,0,0]
	v_pk_fma_f32 v[210:211], v[90:91], v[230:231], v[236:237] op_sel_hi:[0,1,1] neg_lo:[1,0,0] neg_hi:[1,0,0]
	v_pk_fma_f32 v[212:213], v[90:91], v[230:231], v[238:239] op_sel:[1,0,0] neg_lo:[1,0,0] neg_hi:[1,0,0]
	ds_read_b128 v[84:87], v240 offset:12512
	ds_read_b64 v[100:101], v242 offset:47328
	ds_read_b128 v[92:95], v240 offset:29920
	ds_read_b128 v[80:83], v240 offset:3808
	ds_read_b128 v[88:91], v240 offset:21216
	s_waitcnt lgkmcnt(7)
; template <int CTRL> __device__ __forceinline__ float dppf(float x) { return __builtin_bit_cast(float, __builtin_amdgcn_update_dpp(0, __builtin_bit_cast(int, x), CTRL, 0xF, 0xF, false)); }
; __device__ __forceinline__ void phase_rwkv_scan(const Fr& F, int jr) {
;     ...
;                     for (int pi = 0; pi < 16; ++pi) {
;                         const int p = pg + pi, pn = p < 63 ? p + 1 : 63;
;                         const f32x4 w4n = PW[pn * 16], k4n = PW[1024 + pn * 16], b4n = PW[2048 + pn * 16], d4n = PW[3072 + pn * 16], r4n = PR[pn * 16];
;                         const float vvn = PV[pn * 32];
;                         f32x2 t = S01 * k4.xy; t = S23 * k4.zw + t; float sa = t.x + t.y;
;                         sa += dppf<0x128>(sa);
;                         const f32x2 dv01 = d4.xy * vv, dv23 = d4.zw * vv;
;                         sa += dppf<0x124>(sa);
;                         const f32x2 e01 = S01 * w4.xy + dv01;
;                         sa += dppf<0x122>(sa);
;                         const f32x2 e23 = S23 * w4.zw + dv23;
;                         sa += dppf<0x121>(sa);
;                         S01 = e01 - b4.xy * sa; S23 = e23 - b4.zw * sa;
;                         f32x2 u = S01 * r4.xy; u = S23 * r4.zw + u;
;                         PY[pi * 64] = u.x + u.y;
;                         w4 = w4n; k4 = k4n; b4 = b4n; d4 = d4n; r4 = r4n; vv = vvn;
	v_pk_mul_f32 v[226:227], v[206:207], v[106:107] op_sel_hi:[1,0]
	v_pk_mul_f32 v[228:229], v[206:207], v[96:97] op_sel_hi:[1,0]
	v_pk_fma_f32 v[226:227], v[208:209], v[106:107], v[226:227] op_sel:[0,1,0]
	v_pk_fma_f32 v[228:229], v[208:209], v[96:97], v[228:229] op_sel:[0,1,0]
	v_pk_fma_f32 v[226:227], v[210:211], v[108:109], v[226:227] op_sel_hi:[1,0,1]
	v_pk_fma_f32 v[228:229], v[210:211], v[98:99], v[228:229] op_sel_hi:[1,0,1]
	v_pk_fma_f32 v[226:227], v[212:213], v[108:109], v[226:227] op_sel:[0,1,0]
	v_pk_fma_f32 v[228:229], v[212:213], v[98:99], v[228:229] op_sel:[0,1,0]
	v_pk_mul_f32 v[232:233], v[118:119], v[114:115] op_sel_hi:[1,0]
	v_add_f32_dpp v230, v227, v226 row_ror:8 row_mask:0xf bank_mask:0xf
	v_pk_mul_f32 v[234:235], v[118:119], v[114:115] op_sel:[0,1]
	v_pk_mul_f32 v[236:237], v[118:119], v[116:117] op_sel_hi:[1,0]
	v_add_f32_dpp v230, v230, v230 quad_perm:[1,0,3,2] row_mask:0xf bank_mask:0xf
	v_pk_mul_f32 v[238:239], v[118:119], v[116:117] op_sel:[0,1]
	ds_read_b128 v[96:99], v240 offset:38624
	v_add_f32_dpp v230, v230, v230 quad_perm:[2,3,0,1] row_mask:0xf bank_mask:0xf
	v_pk_fma_f32 v[232:233], v[206:207], v[102:103], v[232:233] op_sel_hi:[1,0,1]
	v_pk_fma_f32 v[234:235], v[208:209], v[102:103], v[234:235] op_sel:[0,1,0]
	v_add_f32_dpp v230, v230, v230 row_half_mirror row_mask:0xf bank_mask:0xf
	v_pk_fma_f32 v[236:237], v[210:211], v[104:105], v[236:237] op_sel_hi:[1,0,1]
	v_pk_fma_f32 v[238:239], v[212:213], v[104:105], v[238:239] op_sel:[0,1,0]
	v_mov_b32_dpp v231, v230 row_ror:8 row_mask:0xf bank_mask:0xf
	ds_write_b64 v217, v[228:229] offset:6912
	v_pk_fma_f32 v[206:207], v[110:111], v[230:231], v[232:233] op_sel_hi:[0,1,1] neg_lo:[1,0,0] neg_hi:[1,0,0]
	v_pk_fma_f32 v[208:209], v[110:111], v[230:231], v[234:235] op_sel:[1,0,0] neg_lo:[1,0,0] neg_hi:[1,0,0]
	v_pk_fma_f32 v[210:211], v[112:113], v[230:231], v[236:237] op_sel_hi:[0,1,1] neg_lo:[1,0,0] neg_hi:[1,0,0]
	v_pk_fma_f32 v[212:213], v[112:113], v[230:231], v[238:239] op_sel:[1,0,0] neg_lo:[1,0,0] neg_hi:[1,0,0]
	ds_read_b128 v[106:109], v240 offset:12784
	ds_read_b64 v[118:119], v242 offset:47600
	ds_read_b128 v[114:117], v240 offset:30192
	ds_read_b128 v[102:105], v240 offset:4080
	ds_read_b128 v[110:113], v240 offset:21488
	s_waitcnt lgkmcnt(7)
	v_pk_mul_f32 v[226:227], v[206:207], v[84:85] op_sel_hi:[1,0]
	v_pk_mul_f32 v[228:229], v[206:207], v[222:223] op_sel_hi:[1,0]
	v_pk_fma_f32 v[226:227], v[208:209], v[84:85], v[226:227] op_sel:[0,1,0]
	v_pk_fma_f32 v[228:229], v[208:209], v[222:223], v[228:229] op_sel:[0,1,0]
	v_pk_fma_f32 v[226:227], v[210:211], v[86:87], v[226:227] op_sel_hi:[1,0,1]
	v_pk_fma_f32 v[228:229], v[210:211], v[224:225], v[228:229] op_sel_hi:[1,0,1]
	v_pk_fma_f32 v[226:227], v[212:213], v[86:87], v[226:227] op_sel:[0,1,0]
	v_pk_fma_f32 v[228:229], v[212:213], v[224:225], v[228:229] op_sel:[0,1,0]
	v_pk_mul_f32 v[232:233], v[100:101], v[92:93] op_sel_hi:[1,0]
	v_add_f32_dpp v230, v227, v226 row_ror:8 row_mask:0xf bank_mask:0xf
	v_pk_mul_f32 v[234:235], v[100:101], v[92:93] op_sel:[0,1]
	v_pk_mul_f32 v[236:237], v[100:101], v[94:95] op_sel_hi:[1,0]
	v_add_f32_dpp v230, v230, v230 quad_perm:[1,0,3,2] row_mask:0xf bank_mask:0xf
	v_pk_mul_f32 v[238:239], v[100:101], v[94:95] op_sel:[0,1]
	ds_read_b128 v[222:225], v240 offset:38896
	v_add_f32_dpp v230, v230, v230 quad_perm:[2,3,0,1] row_mask:0xf bank_mask:0xf
	v_pk_fma_f32 v[232:233], v[206:207], v[80:81], v[232:233] op_sel_hi:[1,0,1]
	v_pk_fma_f32 v[234:235], v[208:209], v[80:81], v[234:235] op_sel:[0,1,0]
	v_add_f32_dpp v230, v230, v230 row_half_mirror row_mask:0xf bank_mask:0xf
	v_pk_fma_f32 v[236:237], v[210:211], v[82:83], v[236:237] op_sel_hi:[1,0,1]
	v_pk_fma_f32 v[238:239], v[212:213], v[82:83], v[238:239] op_sel:[0,1,0]
	v_mov_b32_dpp v231, v230 row_ror:8 row_mask:0xf bank_mask:0xf
	ds_write_b64 v217, v[228:229] offset:7488
	v_pk_fma_f32 v[206:207], v[88:89], v[230:231], v[232:233] op_sel_hi:[0,1,1] neg_lo:[1,0,0] neg_hi:[1,0,0]
	v_pk_fma_f32 v[208:209], v[88:89], v[230:231], v[234:235] op_sel:[1,0,0] neg_lo:[1,0,0] neg_hi:[1,0,0]
	v_pk_fma_f32 v[210:211], v[90:91], v[230:231], v[236:237] op_sel_hi:[0,1,1] neg_lo:[1,0,0] neg_hi:[1,0,0]
	v_pk_fma_f32 v[212:213], v[90:91], v[230:231], v[238:239] op_sel:[1,0,0] neg_lo:[1,0,0] neg_hi:[1,0,0]
	ds_read_b128 v[84:87], v240 offset:13056
	ds_read_b64 v[100:101], v242 offset:47872
	ds_read_b128 v[92:95], v240 offset:30464
	ds_read_b128 v[80:83], v240 offset:4352
	ds_read_b128 v[88:91], v240 offset:21760
	s_waitcnt lgkmcnt(7)
	v_pk_mul_f32 v[226:227], v[206:207], v[106:107] op_sel_hi:[1,0]
	v_pk_mul_f32 v[228:229], v[206:207], v[96:97] op_sel_hi:[1,0]
	v_pk_fma_f32 v[226:227], v[208:209], v[106:107], v[226:227] op_sel:[0,1,0]
	v_pk_fma_f32 v[228:229], v[208:209], v[96:97], v[228:229] op_sel:[0,1,0]
	v_pk_fma_f32 v[226:227], v[210:211], v[108:109], v[226:227] op_sel_hi:[1,0,1]
	v_pk_fma_f32 v[228:229], v[210:211], v[98:99], v[228:229] op_sel_hi:[1,0,1]
	v_pk_fma_f32 v[226:227], v[212:213], v[108:109], v[226:227] op_sel:[0,1,0]
	v_pk_fma_f32 v[228:229], v[212:213], v[98:99], v[228:229] op_sel:[0,1,0]
	v_pk_mul_f32 v[232:233], v[118:119], v[114:115] op_sel_hi:[1,0]
	v_add_f32_dpp v230, v227, v226 row_ror:8 row_mask:0xf bank_mask:0xf
	v_pk_mul_f32 v[234:235], v[118:119], v[114:115] op_sel:[0,1]
	v_pk_mul_f32 v[236:237], v[118:119], v[116:117] op_sel_hi:[1,0]
	v_add_f32_dpp v230, v230, v230 quad_perm:[1,0,3,2] row_mask:0xf bank_mask:0xf
	v_pk_mul_f32 v[238:239], v[118:119], v[116:117] op_sel:[0,1]
	ds_read_b128 v[96:99], v240 offset:39168
	v_add_f32_dpp v230, v230, v230 quad_perm:[2,3,0,1] row_mask:0xf bank_mask:0xf
	v_pk_fma_f32 v[232:233], v[206:207], v[102:103], v[232:233] op_sel_hi:[1,0,1]
	v_pk_fma_f32 v[234:235], v[208:209], v[102:103], v[234:235] op_sel:[0,1,0]
	v_add_f32_dpp v230, v230, v230 row_half_mirror row_mask:0xf bank_mask:0xf
	v_pk_fma_f32 v[236:237], v[210:211], v[104:105], v[236:237] op_sel_hi:[1,0,1]
	v_pk_fma_f32 v[238:239], v[212:213], v[104:105], v[238:239] op_sel:[0,1,0]
	v_mov_b32_dpp v231, v230 row_ror:8 row_mask:0xf bank_mask:0xf
	ds_write_b64 v217, v[228:229] offset:8064
	v_pk_fma_f32 v[206:207], v[110:111], v[230:231], v[232:233] op_sel_hi:[0,1,1] neg_lo:[1,0,0] neg_hi:[1,0,0]
	v_pk_fma_f32 v[208:209], v[110:111], v[230:231], v[234:235] op_sel:[1,0,0] neg_lo:[1,0,0] neg_hi:[1,0,0]
	v_pk_fma_f32 v[210:211], v[112:113], v[230:231], v[236:237] op_sel_hi:[0,1,1] neg_lo:[1,0,0] neg_hi:[1,0,0]
	v_pk_fma_f32 v[212:213], v[112:113], v[230:231], v[238:239] op_sel:[1,0,0] neg_lo:[1,0,0] neg_hi:[1,0,0]
	s_waitcnt lgkmcnt(8)
; __device__ __forceinline__ void phase_rwkv_scan(const Fr& F, int jr) {
;     ...
;     const int bxs = (int)blockIdx.x, bxcd = (gridDim.x == 256) ? (bxs & 7) * 32 + (bxs >> 3) : bxs;
;     for (int task = bxcd; task < 256; task += gridDim.x) {
;         const int half = task & 1, h = (task >> 1) & 15, b = (task >> 5) & 3, s = task >> 7;
;         bf16* Yb = F.R(s);
;         const float* w0 = F.a->in[9] + (size_t)(jr * 2 + s) * D + h * 64; const float* a0 = F.a->in[12] + (size_t)(jr * 2 + s) * D + h * 64;
;         const float* kkw = F.a->in[15] + (size_t)jr * D + h * 64; const float* kaw = F.a->in[16] + (size_t)jr * D + h * 64;
;         f32x2 S01 = {0.f, 0.f}, S23 = {0.f, 0.f};
;         const int ks = 4 * l15, rloc = 4 * wave + lq;
;         const int pt = wave & 3, ht0 = (wave >> 2) * 2;
;         const int p1 = pt * 16 + l15;
;         const int p2 = tid >> 3, j8 = tid & 7, hk0 = 8 * j8;
;         bf16x8 Bw[2][2], Ba[2][2]; float w0v[2], a0v[2];
; #pragma unroll
;         for (int hh = 0; hh < 2; ++hh) { const int hk = (ht0 + hh) * 16 + l15, e = h * 64 + hk; w0v[hh] = w0[hk]; a0v[hh] = a0[hk];
; #pragma unroll
;             for (int kst = 0; kst < 2; ++kst) { Bw[hh][kst] = *(const bf16x8*)(L2T + ((size_t)s * D + e) * 64 + 32 * kst + 8 * lq); Ba[hh][kst] = *(const bf16x8*)(L2T + ((size_t)(2 + s) * D + e) * 64 + 32 * kst + 8 * lq); } }
;         float kkc[8], kac[8], rkc[8];
; #pragma unroll
;         for (int i = 0; i < 8; ++i) { kkc[i] = kkw[hk0 + i]; kac[i] = kaw[hk0 + i]; rkc[i] = F.a->in[17][(size_t)jr * D + h * 64 + hk0 + i]; }
;         float* Bon = (float*)(F.ws + OFF_R0 + 6 * RSZ + 16 * MiB);
;         bf16x8 Aw[2], Aa[2]; u32x4 kw, rw; u32x2 vw;
;         {   const size_t row1 = (size_t)b * TB + tokof(s, p1), row2 = (size_t)b * TB + tokof(s, p2);
; #pragma unroll
;     ...
;                     {
;                         const int j = lane >> 2, q = lane & 3; const float* yp = Ypw + j * 64 + q * 16;
;                         const f32x4 a0 = *(const f32x4*)yp, a1 = *(const f32x4*)(yp + 4), a2 = *(const f32x4*)(yp + 8), a3 = *(const f32x4*)(yp + 12);
;                         const f32x4 ssum = (a0 + a1) + (a2 + a3); const float yv = (ssum.x + ssum.y) + (ssum.z + ssum.w);
;                         const size_t row = (size_t)b * TB + tokof(s, chunk * 64 + pg + j);
;                         Yb[row * D + h * 64 + 32 * half + 4 * wave + q] = (bf16)f2bf(yv);
	v_pk_mul_f32 v[228:229], v[206:207], v[222:223] op_sel_hi:[1,0]
	v_add_u32_e32 v243, s15, v219
	v_pk_fma_f32 v[228:229], v[208:209], v[222:223], v[228:229] op_sel:[0,1,0]
	v_lshl_add_u32 v243, v243, 11, v220
	v_pk_fma_f32 v[228:229], v[210:211], v[224:225], v[228:229] op_sel_hi:[1,0,1]
	v_add_u32_e32 v240, 0x1100, v240
	v_pk_fma_f32 v[228:229], v[212:213], v[224:225], v[228:229] op_sel:[0,1,0]
	v_add_u32_e32 v242, 0x1100, v242
	s_nop 0
	s_waitcnt lgkmcnt(1)
	ds_write_b64 v217, v[228:229] offset:8640
	ds_read_b128 v[102:105], v218 offset:0
	ds_read_b128 v[106:109], v218 offset:16
	ds_read_b128 v[110:113], v218 offset:32
	ds_read_b128 v[114:117], v218 offset:48
	ds_read_b128 v[222:225], v218 offset:64
	ds_read_b128 v[232:235], v218 offset:80
	ds_read_b128 v[236:239], v218 offset:96
	ds_read_b128 v[226:229], v218 offset:112
	s_waitcnt lgkmcnt(6)
	v_pk_add_f32 v[102:103], v[102:103], v[104:105]
	v_pk_add_f32 v[106:107], v[106:107], v[108:109]
	s_waitcnt lgkmcnt(4)
	v_pk_add_f32 v[110:111], v[110:111], v[112:113]
	v_pk_add_f32 v[114:115], v[114:115], v[116:117]
	v_pk_add_f32 v[102:103], v[102:103], v[106:107]
	s_waitcnt lgkmcnt(2)
	v_pk_add_f32 v[222:223], v[222:223], v[224:225]
	v_pk_add_f32 v[232:233], v[232:233], v[234:235]
	v_pk_add_f32 v[110:111], v[110:111], v[114:115]
	s_waitcnt lgkmcnt(0)
	v_pk_add_f32 v[236:237], v[236:237], v[238:239]
	v_pk_add_f32 v[226:227], v[226:227], v[228:229]
	v_pk_add_f32 v[222:223], v[222:223], v[232:233]
	v_pk_add_f32 v[102:103], v[102:103], v[110:111]
	v_pk_add_f32 v[236:237], v[236:237], v[226:227]
	s_add_i32 s15, s15, s19
	v_pk_add_f32 v[222:223], v[222:223], v[236:237]
	s_nop 0
	v_pk_add_f32 v[102:103], v[102:103], v[222:223] op_sel:[0,1] op_sel_hi:[1,0]
	s_nop 0
	v_cvt_pk_bf16_f32 v244, v102, v103
	s_nop 0
	global_store_dword v243, v244, s[20:21]
	s_waitcnt lgkmcnt(0)
	s_add_i32 s10, s10, 1
	s_xor_b32 s11, s11, 0xcc00
	s_barrier
	s_cmp_lt_u32 s10, 136
	s_cbranch_scc1 .Lrw0_shc
	s_setprio 0
	s_branch .Lrw0_end
.Lrw0_helper:
	s_sub_i32 s17, s68, 4
	v_mov_b32_e32 v122, 0xbfb8aa3b
	v_mov_b32_e32 v123, 0xbfb8aa3b
	v_mov_b32_e32 v124, 0xbf1b4598
	v_mov_b32_e32 v125, 0xbf1b4598
	v_mov_b32_e32 v126, 0x3fb8aa3b
	v_mov_b32_e32 v127, 0x3fb8aa3b
	s_and_b32 s14, s17, 1
	s_lshr_b32 s15, s17, 1
	v_and_b32_e32 v196, 15, v130
	v_lshrrev_b32_e32 v217, 4, v130
	s_lshl_b32 s17, s14, 4
	v_add_u32_e32 v216, s17, v196
	v_mov_b32_e32 v218, v216
	s_cmp_eq_u32 s6, 0
	s_cbranch_scc1 .Lrw0_hdir0
	v_sub_u32_e32 v218, 0, v216
.Lrw0_hdir0:
	s_mul_i32 s16, s7, 0x1100
	v_lshlrev_b32_e32 v221, 4, v217
	s_lshl_b32 s17, s15, 6
	v_lshl_add_u32 v219, v217, 3, s17
	s_xor_b32 s18, s17, 64
	v_lshl_add_u32 v220, v217, 3, s18
	s_lshl_b32 s17, s15, 7
	v_mul_u32_u24_e32 v197, 0x110, v216
	v_add_u32_e32 v197, s17, v197
	v_lshl_add_u32 v222, v217, 4, v197
	v_lshl_add_u32 v223, v217, 5, v197
	s_lshl_b32 s17, s6, 7
	s_add_u32 s20, s26, 0xde00000
	s_addc_u32 s21, s27, 0
	s_add_u32 s20, s20, s17
	s_addc_u32 s21, s21, 0
	s_lshl_b32 s17, s8, 7
	s_add_u32 s22, s26, 0xbc00000
	s_addc_u32 s23, s27, 0
	s_add_u32 s22, s22, s17
	s_addc_u32 s23, s23, 0
	s_add_u32 s24, s26, 0x9a00000
	s_addc_u32 s25, s27, 0
	s_add_u32 s24, s24, s17
	s_addc_u32 s25, s25, 0
	s_lshl_b32 s18, s9, 6
	s_add_i32 s17, s17, s18
	s_lshl_b32 s18, s15, 5
	s_add_i32 s17, s17, s18
	s_add_u32 s42, s26, 0x5600000
	s_addc_u32 s43, s27, 0
	s_add_u32 s42, s42, s17
	s_addc_u32 s43, s43, 0
	s_lshl_b32 s17, s8, 2
	s_add_u32 s44, s26, 0xee00000
	s_addc_u32 s45, s27, 0
	s_add_u32 s44, s44, s17
	s_addc_u32 s45, s45, 0
	s_or_b32 s17, s6, s9
	s_or_b32 s17, s17, s15
	s_cmp_eq_u32 s17, 0
	s_cselect_b32 s32, 1, 0
	s_load_dwordx2 s[46:47], s[0:1], 0x48
	s_load_dwordx2 s[48:49], s[0:1], 0x60
	s_load_dwordx2 s[50:51], s[0:1], 0x78
	s_load_dwordx2 s[52:53], s[0:1], 0x80
	s_load_dwordx2 s[54:55], s[0:1], 0x88
	s_lshl_b32 s17, s8, 8
	s_lshl_b32 s18, s15, 7
	s_add_i32 s19, s17, s18
	v_lshl_add_u32 v198, v217, 4, s19
	s_xor_b32 s18, s18, 128
	s_add_i32 s19, s17, s18
	v_lshl_add_u32 v199, v217, 4, s19
	s_waitcnt lgkmcnt(0)
	s_lshl_b32 s17, s6, 12
	s_add_u32 s46, s46, s17
	s_addc_u32 s47, s47, 0
	s_add_u32 s48, s48, s17
	s_addc_u32 s49, s49, 0
	global_load_dwordx4 v[32:35], v198, s[46:47] offset:0
	global_load_dwordx4 v[40:43], v198, s[48:49] offset:0
	global_load_dwordx4 v[64:67], v198, s[52:53] offset:0
	global_load_dwordx4 v[36:39], v198, s[46:47] offset:64
	global_load_dwordx4 v[44:47], v198, s[48:49] offset:64
	global_load_dwordx4 v[68:71], v198, s[52:53] offset:64
	global_load_dwordx4 v[48:51], v198, s[50:51] offset:0
	global_load_dwordx4 v[72:75], v198, s[54:55] offset:0
	global_load_dwordx4 v[52:55], v198, s[50:51] offset:64
	global_load_dwordx4 v[76:79], v198, s[54:55] offset:64
	global_load_dwordx4 v[56:59], v199, s[50:51] offset:0
	global_load_dwordx4 v[80:83], v199, s[54:55] offset:0
	global_load_dwordx4 v[60:63], v199, s[50:51] offset:64
	global_load_dwordx4 v[84:87], v199, s[54:55] offset:64
	s_lshl_b32 s17, s8, 6
	s_lshl_b32 s18, s15, 5
	s_add_i32 s17, s17, s18
	v_add_u32_e32 v200, s17, v196
	v_lshlrev_b32_e32 v200, 7, v200
	v_add_u32_e32 v200, v200, v221
	s_lshl_b32 s17, s6, 17
	s_add_u32 s46, s26, 0x200000
	s_addc_u32 s47, s27, 0
	s_add_u32 s46, s46, s17
	s_addc_u32 s47, s47, 0
	s_add_u32 s48, s46, 0x40000
	s_addc_u32 s49, s47, 0
	global_load_dwordx4 v[0:3], v200, s[46:47] offset:0
	global_load_dwordx4 v[16:19], v200, s[48:49] offset:0
	global_load_dwordx4 v[4:7], v200, s[46:47] offset:64
	global_load_dwordx4 v[20:23], v200, s[48:49] offset:64
	global_load_dwordx4 v[8:11], v200, s[46:47] offset:2048
	global_load_dwordx4 v[24:27], v200, s[48:49] offset:2048
	global_load_dwordx4 v[12:15], v200, s[46:47] offset:2112
	global_load_dwordx4 v[28:31], v200, s[48:49] offset:2112
	s_mov_b32 s10, 0
	s_mov_b32 s11, 0
	s_lshl_b32 s17, s10, 5
	s_cmp_lt_u32 s10, 8
	s_movk_i32 s18, 0x11ff
	s_cselect_b32 s18, 0xff, s18
	s_sub_i32 s18, s18, s17
	s_cmp_eq_u32 s6, 0
	s_cselect_b32 s17, s17, s18
	s_add_i32 s17, s17, s16
	v_add_u32_e32 v231, s17, v218
	v_lshl_add_u32 v226, v231, 9, v221
	v_lshl_add_u32 v227, v231, 11, v219
	v_lshl_add_u32 v228, v231, 11, v220
	v_lshlrev_b32_e32 v229, 3, v217
	v_lshl_add_u32 v229, v231, 11, v229
	v_lshlrev_b32_e32 v230, 6, v231
	global_load_dwordx4 v[88:91], v226, s[20:21]
	global_load_dwordx4 v[92:95], v226, s[20:21] offset:64
	global_load_dwordx4 v[96:99], v226, s[20:21] offset:256
	global_load_dwordx4 v[100:103], v226, s[20:21] offset:320
	global_load_dwordx2 v[104:105], v227, s[22:23] offset:0
	global_load_dwordx2 v[106:107], v227, s[22:23] offset:32
	global_load_dwordx2 v[108:109], v228, s[22:23] offset:0
	global_load_dwordx2 v[110:111], v228, s[22:23] offset:32
	global_load_dwordx2 v[112:113], v227, s[24:25] offset:0
	global_load_dwordx2 v[114:115], v227, s[24:25] offset:32
	global_load_dwordx2 v[116:117], v228, s[24:25] offset:0
	global_load_dwordx2 v[118:119], v228, s[24:25] offset:32
	global_load_dwordx2 v[120:121], v229, s[42:43]
	v_mov_b32_e32 v224, v222
	v_mov_b32_e32 v225, v223
	v_mov_b32_e32 v202, v230
	s_waitcnt vmcnt(0)
; __device__ __forceinline__ float sigm(float x) { return __builtin_amdgcn_rcpf(1.f + __expf(-x)); }
; __device__ __forceinline__ void phase_rwkv_scan(const Fr& F, int jr) {
;     ...
; #pragma unroll
;             for (int hh = 0; hh < 2; ++hh) {
;                 const int hk = (ht0 + hh) * 16 + l15;
;                 f32x4 cw = {0.f, 0.f, 0.f, 0.f}, ca = {0.f, 0.f, 0.f, 0.f};
; #pragma unroll
;                 for (int kst = 0; kst < 2; ++kst) { cw = __builtin_amdgcn_mfma_f32_16x16x32_bf16(Aw[kst], Bw[hh][kst], cw, 0, 0, 0); ca = __builtin_amdgcn_mfma_f32_16x16x32_bf16(Aa[kst], Ba[hh][kst], ca, 0, 0, 0); }
; #pragma unroll
;                 for (int reg = 0; reg < 4; ++reg) { const int pp = pt * 16 + lq * 4 + reg;
;                     Wv[pp * 64 + hk] = __expf(-0.60653066f * sigm(w0v[hh] + cw[reg]));
;                     Av[pp * 64 + hk] = sigm(a0v[hh] + ca[reg]); }
;             }
;             LDS_BAR();
;             {
;                 const float kr[8] = {lo_bf(kw.x), hi_bf(kw.x), lo_bf(kw.y), hi_bf(kw.y), lo_bf(kw.z), hi_bf(kw.z), lo_bf(kw.w), hi_bf(kw.w)};
;                 const float rr[8] = {lo_bf(rw.x), hi_bf(rw.x), lo_bf(rw.y), hi_bf(rw.y), lo_bf(rw.z), hi_bf(rw.z), lo_bf(rw.w), hi_bf(rw.w)};
;                 float kq[8]; float ss = 0.f, bon = 0.f;
; #pragma unroll
;                 for (int i = 0; i < 8; ++i) { kq[i] = kr[i] * kkc[i]; ss += kq[i] * kq[i]; bon += rr[i] * kr[i] * rkc[i]; }
;                 ss += dppf<0xB1>(ss); ss += dppf<0x4E>(ss); ss += dppf<0x141>(ss); bon += dppf<0xB1>(bon); bon += dppf<0x4E>(bon); bon += dppf<0x141>(bon);
;                 if (s == 0 && half == 0 && j8 == 0) Bon[((size_t)b * TB + tokof(s, chunk * 64 + p2)) * 16 + h] = bon;
;                 const float inv = 1.f / fmaxf(sqrtf(ss), 1e-12f);
;                 const f32x4 av0 = *(const f32x4*)(Av + p2 * 64 + hk0), av1 = *(const f32x4*)(Av + p2 * 64 + hk0 + 4);
;                 const float av[8] = {av0.x, av0.y, av0.z, av0.w, av1.x, av1.y, av1.z, av1.w};
;                 float o1[8], o2[8], o3[8];
; #pragma unroll
;                 for (int i = 0; i < 8; ++i) { const float kkv = kq[i] * inv; o1[i] = kkv; o2[i] = kkv * av[i]; o3[i] = kr[i] * (1.f + (av[i] - 1.f) * kac[i]); }
;                 const int o = p2 * 64 + hk0;
;                 *(f32x4*)(KK + o) = (f32x4){o1[0], o1[1], o1[2], o1[3]}; *(f32x4*)(KK + o + 4) = (f32x4){o1[4], o1[5], o1[6], o1[7]};
	v_mfma_f32_16x16x32_bf16 v[136:139], v[0:3], v[88:91], 0
	v_mfma_f32_16x16x32_bf16 v[136:139], v[4:7], v[92:95], v[136:139]
	v_mfma_f32_16x16x32_bf16 v[140:143], v[8:11], v[88:91], 0
	v_mfma_f32_16x16x32_bf16 v[140:143], v[12:15], v[92:95], v[140:143]
	v_mfma_f32_16x16x32_bf16 v[144:147], v[16:19], v[96:99], 0
	v_mfma_f32_16x16x32_bf16 v[144:147], v[20:23], v[100:103], v[144:147]
	v_mfma_f32_16x16x32_bf16 v[148:151], v[24:27], v[96:99], 0
	v_mfma_f32_16x16x32_bf16 v[148:151], v[28:31], v[100:103], v[148:151]
	v_lshlrev_b32_e32 v152, 16, v104
	v_and_b32_e32 v153, 0xffff0000, v104
	v_lshlrev_b32_e32 v154, 16, v105
	v_and_b32_e32 v155, 0xffff0000, v105
	v_lshlrev_b32_e32 v156, 16, v106
	v_and_b32_e32 v157, 0xffff0000, v106
	v_lshlrev_b32_e32 v158, 16, v107
	v_and_b32_e32 v159, 0xffff0000, v107
	v_lshlrev_b32_e32 v160, 16, v108
	v_and_b32_e32 v161, 0xffff0000, v108
	v_lshlrev_b32_e32 v162, 16, v109
	v_and_b32_e32 v163, 0xffff0000, v109
	v_lshlrev_b32_e32 v164, 16, v110
	v_and_b32_e32 v165, 0xffff0000, v110
	v_lshlrev_b32_e32 v166, 16, v111
	v_and_b32_e32 v167, 0xffff0000, v111
	v_lshlrev_b32_e32 v168, 16, v112
	v_and_b32_e32 v169, 0xffff0000, v112
	v_lshlrev_b32_e32 v170, 16, v113
	v_and_b32_e32 v171, 0xffff0000, v113
	v_lshlrev_b32_e32 v172, 16, v114
	v_and_b32_e32 v173, 0xffff0000, v114
	v_lshlrev_b32_e32 v174, 16, v115
	v_and_b32_e32 v175, 0xffff0000, v115
	v_lshlrev_b32_e32 v192, 16, v120
	v_and_b32_e32 v193, 0xffff0000, v120
	v_lshlrev_b32_e32 v194, 16, v121
	v_and_b32_e32 v195, 0xffff0000, v121
	v_pk_mul_f32 v[176:177], v[152:153], v[48:49]
	v_pk_mul_f32 v[178:179], v[154:155], v[50:51]
	v_pk_mul_f32 v[180:181], v[156:157], v[52:53]
	v_pk_mul_f32 v[182:183], v[158:159], v[54:55]
	v_pk_mul_f32 v[184:185], v[160:161], v[56:57]
	v_pk_mul_f32 v[186:187], v[162:163], v[58:59]
	v_pk_mul_f32 v[188:189], v[164:165], v[60:61]
	v_pk_mul_f32 v[190:191], v[166:167], v[62:63]
	v_pk_mul_f32 v[196:197], v[176:177], v[176:177]
	v_pk_mul_f32 v[198:199], v[178:179], v[178:179]
	v_pk_fma_f32 v[196:197], v[180:181], v[180:181], v[196:197]
	v_pk_fma_f32 v[198:199], v[182:183], v[182:183], v[198:199]
	v_pk_fma_f32 v[196:197], v[184:185], v[184:185], v[196:197]
	v_pk_fma_f32 v[198:199], v[186:187], v[186:187], v[198:199]
	v_pk_fma_f32 v[196:197], v[188:189], v[188:189], v[196:197]
	v_pk_fma_f32 v[198:199], v[190:191], v[190:191], v[198:199]
	s_nop 0
	v_pk_add_f32 v[196:197], v[196:197], v[198:199]
	s_cmp_eq_u32 s32, 0
	s_cbranch_scc1 .Lrw0_hnbc0
	v_mul_f32_e32 v208, v168, v152
	v_mul_f32_e32 v209, v169, v153
	v_mul_f32_e32 v210, v170, v154
	v_mul_f32_e32 v211, v171, v155
	v_mul_f32_e32 v234, v72, v208
	v_fmac_f32_e32 v234, v73, v209
	v_fmac_f32_e32 v234, v74, v210
	v_fmac_f32_e32 v234, v75, v211
	v_mul_f32_e32 v208, v172, v156
	v_mul_f32_e32 v209, v173, v157
	v_mul_f32_e32 v210, v174, v158
	v_mul_f32_e32 v211, v175, v159
	v_fmac_f32_e32 v234, v76, v208
	v_fmac_f32_e32 v234, v77, v209
	v_fmac_f32_e32 v234, v78, v210
	v_fmac_f32_e32 v234, v79, v211
	v_lshlrev_b32_e32 v204, 16, v116
	v_and_b32_e32 v205, 0xffff0000, v116
	v_lshlrev_b32_e32 v206, 16, v117
	v_and_b32_e32 v207, 0xffff0000, v117
	v_mul_f32_e32 v208, v204, v160
	v_mul_f32_e32 v209, v205, v161
	v_mul_f32_e32 v210, v206, v162
	v_mul_f32_e32 v211, v207, v163
	v_fmac_f32_e32 v234, v80, v208
	v_fmac_f32_e32 v234, v81, v209
	v_fmac_f32_e32 v234, v82, v210
	v_fmac_f32_e32 v234, v83, v211
	v_lshlrev_b32_e32 v204, 16, v118
	v_and_b32_e32 v205, 0xffff0000, v118
	v_lshlrev_b32_e32 v206, 16, v119
	v_and_b32_e32 v207, 0xffff0000, v119
	v_mul_f32_e32 v208, v204, v164
	v_mul_f32_e32 v209, v205, v165
	v_mul_f32_e32 v210, v206, v166
	v_mul_f32_e32 v211, v207, v167
	v_fmac_f32_e32 v234, v84, v208
	v_fmac_f32_e32 v234, v85, v209
	v_fmac_f32_e32 v234, v86, v210
	v_fmac_f32_e32 v234, v87, v211
.Lrw0_hnbc0:
	v_add_f32_e32 v232, v196, v197
	s_add_i32 s10, s10, 1
	s_cmp_lt_u32 s10, 136
	s_cbranch_scc0 .Lrw0_hnl0
	s_lshl_b32 s17, s10, 5
	s_cmp_lt_u32 s10, 8
	s_movk_i32 s18, 0x11ff
	s_cselect_b32 s18, 0xff, s18
	s_sub_i32 s18, s18, s17
	s_cmp_eq_u32 s6, 0
	s_cselect_b32 s17, s17, s18
	s_add_i32 s17, s17, s16
	v_add_u32_e32 v231, s17, v218
	v_lshl_add_u32 v226, v231, 9, v221
	v_lshl_add_u32 v227, v231, 11, v219
	v_lshl_add_u32 v228, v231, 11, v220
	v_lshlrev_b32_e32 v229, 3, v217
	v_lshl_add_u32 v229, v231, 11, v229
	v_lshlrev_b32_e32 v230, 6, v231
	global_load_dwordx4 v[88:91], v226, s[20:21]
	global_load_dwordx4 v[92:95], v226, s[20:21] offset:64
	global_load_dwordx4 v[96:99], v226, s[20:21] offset:256
	global_load_dwordx4 v[100:103], v226, s[20:21] offset:320
	global_load_dwordx2 v[104:105], v227, s[22:23] offset:0
	global_load_dwordx2 v[106:107], v227, s[22:23] offset:32
	global_load_dwordx2 v[108:109], v228, s[22:23] offset:0
	global_load_dwordx2 v[110:111], v228, s[22:23] offset:32
	global_load_dwordx2 v[112:113], v227, s[24:25] offset:0
	global_load_dwordx2 v[114:115], v227, s[24:25] offset:32
	global_load_dwordx2 v[116:117], v228, s[24:25] offset:0
	global_load_dwordx2 v[118:119], v228, s[24:25] offset:32
	global_load_dwordx2 v[120:121], v229, s[42:43]
; __device__ __forceinline__ void phase_rwkv_scan(const Fr& F, int jr) {
;     ...
;                 for (int kst = 0; kst < 2; ++kst) { cw = __builtin_amdgcn_mfma_f32_16x16x32_bf16(Aw[kst], Bw[hh][kst], cw, 0, 0, 0); ca = __builtin_amdgcn_mfma_f32_16x16x32_bf16(Aa[kst], Ba[hh][kst], ca, 0, 0, 0); }
; #pragma unroll
;                 for (int reg = 0; reg < 4; ++reg) { const int pp = pt * 16 + lq * 4 + reg;
;                     Wv[pp * 64 + hk] = __expf(-0.60653066f * sigm(w0v[hh] + cw[reg]));
;                     Av[pp * 64 + hk] = sigm(a0v[hh] + ca[reg]); }
;             }
;             LDS_BAR();
;             {
;                 const float kr[8] = {lo_bf(kw.x), hi_bf(kw.x), lo_bf(kw.y), hi_bf(kw.y), lo_bf(kw.z), hi_bf(kw.z), lo_bf(kw.w), hi_bf(kw.w)};
;                 const float rr[8] = {lo_bf(rw.x), hi_bf(rw.x), lo_bf(rw.y), hi_bf(rw.y), lo_bf(rw.z), hi_bf(rw.z), lo_bf(rw.w), hi_bf(rw.w)};
;                 float kq[8]; float ss = 0.f, bon = 0.f;
; #pragma unroll
;                 for (int i = 0; i < 8; ++i) { kq[i] = kr[i] * kkc[i]; ss += kq[i] * kq[i]; bon += rr[i] * kr[i] * rkc[i]; }
;                 ss += dppf<0xB1>(ss); ss += dppf<0x4E>(ss); ss += dppf<0x141>(ss); bon += dppf<0xB1>(bon); bon += dppf<0x4E>(bon); bon += dppf<0x141>(bon);
;                 if (s == 0 && half == 0 && j8 == 0) Bon[((size_t)b * TB + tokof(s, chunk * 64 + p2)) * 16 + h] = bon;
;                 const float inv = 1.f / fmaxf(sqrtf(ss), 1e-12f);
;                 const f32x4 av0 = *(const f32x4*)(Av + p2 * 64 + hk0), av1 = *(const f32x4*)(Av + p2 * 64 + hk0 + 4);
;                 const float av[8] = {av0.x, av0.y, av0.z, av0.w, av1.x, av1.y, av1.z, av1.w};
;                 float o1[8], o2[8], o3[8];
; #pragma unroll
;                 for (int i = 0; i < 8; ++i) { const float kkv = kq[i] * inv; o1[i] = kkv; o2[i] = kkv * av[i]; o3[i] = kr[i] * (1.f + (av[i] - 1.f) * kac[i]); }
;                 const int o = p2 * 64 + hk0;
;                 *(f32x4*)(KK + o) = (f32x4){o1[0], o1[1], o1[2], o1[3]}; *(f32x4*)(KK + o + 4) = (f32x4){o1[4], o1[5], o1[6], o1[7]};
;                 *(f32x4*)(Bv + o) = (f32x4){o2[0], o2[1], o2[2], o2[3]}; *(f32x4*)(Bv + o + 4) = (f32x4){o2[4], o2[5], o2[6], o2[7]};
;                 *(f32x4*)(KD + o) = (f32x4){o3[0], o3[1], o3[2], o3[3]}; *(f32x4*)(KD + o + 4) = (f32x4){o3[4], o3[5], o3[6], o3[7]};
.Lrw0_hnl0:
	v_mov_b32_e32 v196, v232
	s_nop 1
	v_permlane16_swap_b32_e32 v232, v196
	s_nop 1
	v_add_f32_e32 v232, v232, v196
	v_mov_b32_e32 v196, v232
	s_nop 1
	v_permlane32_swap_b32_e32 v232, v196
	s_nop 1
	v_add_f32_e32 v232, v232, v196
	v_mul_f32_e32 v197, 0x4f800000, v232
	v_mov_b32_e32 v198, 0xf800000
	v_cmp_gt_f32_e32 vcc, v198, v232
	s_nop 1
	v_cndmask_b32_e32 v196, v232, v197, vcc
	v_sqrt_f32_e32 v197, v196
	s_nop 0
	v_add_u32_e32 v198, -1, v197
	v_fma_f32 v200, -v198, v197, v196
	v_add_u32_e32 v199, 1, v197
	v_cmp_ge_f32_e64 s[56:57], 0, v200
	s_nop 1
	v_cndmask_b32_e64 v198, v197, v198, s[56:57]
	v_fma_f32 v197, -v199, v197, v196
	v_cmp_lt_f32_e64 s[56:57], 0, v197
	s_nop 1
	v_cndmask_b32_e64 v197, v198, v199, s[56:57]
	v_mul_f32_e32 v198, 0x37800000, v197
	v_cndmask_b32_e32 v197, v197, v198, vcc
	v_mov_b32_e32 v198, 0x260
	v_cmp_class_f32_e32 vcc, v196, v198
	s_nop 1
	v_cndmask_b32_e32 v196, v197, v196, vcc
	v_max_f32_e32 v196, 0x2b8cbccc, v196
	v_div_scale_f32 v197, s[56:57], v196, v196, 1.0
	v_rcp_f32_e32 v198, v197
	s_nop 0
	v_fma_f32 v199, -v197, v198, 1.0
	v_fmac_f32_e32 v198, v199, v198
	v_div_scale_f32 v199, vcc, 1.0, v196, 1.0
	v_mul_f32_e32 v200, v199, v198
	v_fma_f32 v201, -v197, v200, v199
	v_fmac_f32_e32 v200, v201, v198
	v_fma_f32 v197, -v197, v200, v199
	s_nop 0
	v_div_fmas_f32 v197, v197, v198, v200
	v_div_fixup_f32 v232, v197, v196, 1.0
	v_pk_add_f32 v[136:137], v[32:33], v[136:137]
	v_pk_add_f32 v[138:139], v[34:35], v[138:139]
	v_pk_add_f32 v[144:145], v[40:41], v[144:145]
	v_pk_add_f32 v[146:147], v[42:43], v[146:147]
	v_pk_add_f32 v[140:141], v[36:37], v[140:141]
	v_pk_add_f32 v[142:143], v[38:39], v[142:143]
	v_pk_add_f32 v[148:149], v[44:45], v[148:149]
	v_pk_add_f32 v[150:151], v[46:47], v[150:151]
	v_pk_mul_f32 v[136:137], v[136:137], v[122:123]
	v_pk_mul_f32 v[138:139], v[138:139], v[122:123]
	v_pk_mul_f32 v[144:145], v[144:145], v[122:123]
	v_pk_mul_f32 v[146:147], v[146:147], v[122:123]
	v_pk_mul_f32 v[140:141], v[140:141], v[122:123]
	v_pk_mul_f32 v[142:143], v[142:143], v[122:123]
	v_pk_mul_f32 v[148:149], v[148:149], v[122:123]
	v_pk_mul_f32 v[150:151], v[150:151], v[122:123]
	v_exp_f32_e32 v136, v136
	v_exp_f32_e32 v137, v137
	v_exp_f32_e32 v138, v138
	v_exp_f32_e32 v139, v139
	v_exp_f32_e32 v144, v144
	v_exp_f32_e32 v145, v145
	v_exp_f32_e32 v146, v146
	v_exp_f32_e32 v147, v147
	v_exp_f32_e32 v140, v140
	v_exp_f32_e32 v141, v141
	v_exp_f32_e32 v142, v142
	v_exp_f32_e32 v143, v143
	v_exp_f32_e32 v148, v148
	v_exp_f32_e32 v149, v149
	v_exp_f32_e32 v150, v150
	v_exp_f32_e32 v151, v151
	v_pk_add_f32 v[136:137], v[136:137], 1.0 op_sel_hi:[1,0]
	v_pk_add_f32 v[138:139], v[138:139], 1.0 op_sel_hi:[1,0]
	v_pk_add_f32 v[144:145], v[144:145], 1.0 op_sel_hi:[1,0]
	v_pk_add_f32 v[146:147], v[146:147], 1.0 op_sel_hi:[1,0]
	v_pk_add_f32 v[140:141], v[140:141], 1.0 op_sel_hi:[1,0]
	v_pk_add_f32 v[142:143], v[142:143], 1.0 op_sel_hi:[1,0]
	v_pk_add_f32 v[148:149], v[148:149], 1.0 op_sel_hi:[1,0]
	v_pk_add_f32 v[150:151], v[150:151], 1.0 op_sel_hi:[1,0]
	v_rcp_f32_e32 v136, v136
	v_rcp_f32_e32 v137, v137
	v_rcp_f32_e32 v138, v138
	v_rcp_f32_e32 v139, v139
	v_rcp_f32_e32 v144, v144
	v_rcp_f32_e32 v145, v145
	v_rcp_f32_e32 v146, v146
	v_rcp_f32_e32 v147, v147
	v_rcp_f32_e32 v140, v140
	v_rcp_f32_e32 v141, v141
	v_rcp_f32_e32 v142, v142
	v_rcp_f32_e32 v143, v143
	v_rcp_f32_e32 v148, v148
	v_rcp_f32_e32 v149, v149
	v_rcp_f32_e32 v150, v150
	v_rcp_f32_e32 v151, v151
	v_pk_mul_f32 v[136:137], v[136:137], v[124:125]
	v_pk_mul_f32 v[138:139], v[138:139], v[124:125]
	v_pk_mul_f32 v[140:141], v[140:141], v[124:125]
	v_pk_mul_f32 v[142:143], v[142:143], v[124:125]
	v_pk_mul_f32 v[136:137], v[136:137], v[126:127]
	v_pk_mul_f32 v[138:139], v[138:139], v[126:127]
	v_pk_mul_f32 v[140:141], v[140:141], v[126:127]
	v_pk_mul_f32 v[142:143], v[142:143], v[126:127]
	v_exp_f32_e32 v136, v136
	v_exp_f32_e32 v137, v137
	v_exp_f32_e32 v138, v138
	v_exp_f32_e32 v139, v139
	v_exp_f32_e32 v140, v140
	v_exp_f32_e32 v141, v141
	v_exp_f32_e32 v142, v142
	v_exp_f32_e32 v143, v143
	v_pk_mul_f32 v[204:205], v[176:177], v[232:233] op_sel_hi:[1,0]
	v_pk_mul_f32 v[206:207], v[178:179], v[232:233] op_sel_hi:[1,0]
	v_pk_add_f32 v[212:213], v[144:145], -1.0 op_sel_hi:[1,0]
	v_pk_add_f32 v[214:215], v[146:147], -1.0 op_sel_hi:[1,0]
	v_pk_mul_f32 v[208:209], v[204:205], v[144:145]
	v_pk_mul_f32 v[210:211], v[206:207], v[146:147]
	v_pk_fma_f32 v[212:213], v[64:65], v[212:213], 1.0 op_sel_hi:[1,1,0]
	v_pk_fma_f32 v[214:215], v[66:67], v[214:215], 1.0 op_sel_hi:[1,1,0]
	ds_write_b128 v224, v[136:139] offset:0
	ds_write_b128 v224, v[204:207] offset:8704
	v_pk_mul_f32 v[212:213], v[212:213], v[152:153]
	v_pk_mul_f32 v[214:215], v[214:215], v[154:155]
	ds_write_b128 v224, v[208:211] offset:17408
	ds_write_b128 v224, v[168:171] offset:34816
	ds_write_b128 v224, v[212:215] offset:26112
	v_pk_mul_f32 v[204:205], v[180:181], v[232:233] op_sel_hi:[1,0]
	v_pk_mul_f32 v[206:207], v[182:183], v[232:233] op_sel_hi:[1,0]
	v_pk_add_f32 v[212:213], v[148:149], -1.0 op_sel_hi:[1,0]
	v_pk_add_f32 v[214:215], v[150:151], -1.0 op_sel_hi:[1,0]
	v_pk_mul_f32 v[208:209], v[204:205], v[148:149]
	v_pk_mul_f32 v[210:211], v[206:207], v[150:151]
	v_pk_fma_f32 v[212:213], v[68:69], v[212:213], 1.0 op_sel_hi:[1,1,0]
	v_pk_fma_f32 v[214:215], v[70:71], v[214:215], 1.0 op_sel_hi:[1,1,0]
	ds_write_b128 v224, v[140:143] offset:64
	ds_write_b128 v224, v[204:207] offset:8768
	v_pk_mul_f32 v[212:213], v[212:213], v[156:157]
	v_pk_mul_f32 v[214:215], v[214:215], v[158:159]
	ds_write_b128 v224, v[208:211] offset:17472
	ds_write_b128 v224, v[172:175] offset:34880
	ds_write_b128 v224, v[212:215] offset:26176
	v_mov_b32_e32 v204, v192
	v_mov_b32_e32 v205, v193
	v_mov_b32_e32 v206, v193
	v_mov_b32_e32 v207, v192
	v_mov_b32_e32 v208, v194
	v_mov_b32_e32 v209, v195
	v_mov_b32_e32 v210, v195
	v_mov_b32_e32 v211, v194
	ds_write_b128 v225, v[204:207] offset:43520
	ds_write_b128 v225, v[208:211] offset:43536
	s_cmp_eq_u32 s32, 0
	s_cbranch_scc1 .Lrw0_hnb0
	v_mov_b32_e32 v196, v234
	s_nop 1
	v_permlane16_swap_b32_e32 v234, v196
	s_nop 1
	v_add_f32_e32 v234, v234, v196
	v_mov_b32_e32 v196, v234
	s_nop 1
	v_permlane32_swap_b32_e32 v234, v196
	s_nop 1
	v_add_f32_e32 v234, v234, v196
	v_cmp_gt_u32_e32 vcc, 16, v130
	s_and_saveexec_b64 s[56:57], vcc
	global_store_dword v202, v234, s[44:45]
	s_mov_b64 exec, s[56:57]

; __device__ __forceinline__ float sigm(float x) { return __builtin_amdgcn_rcpf(1.f + __expf(-x)); }
; #define LDS_BAR() asm volatile("s_waitcnt lgkmcnt(0)\n\ts_barrier" ::: "memory")
; __device__ __forceinline__ void phase_rwkv_scan(const Fr& F, int jr) {
;     ...
;         for (int chunk = 0; chunk < TB / 64; ++chunk) {
; #pragma unroll
;             for (int hh = 0; hh < 2; ++hh) {
;                 const int hk = (ht0 + hh) * 16 + l15;
;                 f32x4 cw = {0.f, 0.f, 0.f, 0.f}, ca = {0.f, 0.f, 0.f, 0.f};
; #pragma unroll
;                 for (int kst = 0; kst < 2; ++kst) { cw = __builtin_amdgcn_mfma_f32_16x16x32_bf16(Aw[kst], Bw[hh][kst], cw, 0, 0, 0); ca = __builtin_amdgcn_mfma_f32_16x16x32_bf16(Aa[kst], Ba[hh][kst], ca, 0, 0, 0); }
; #pragma unroll
;                 for (int reg = 0; reg < 4; ++reg) { const int pp = pt * 16 + lq * 4 + reg;
;                     Wv[pp * 64 + hk] = __expf(-0.60653066f * sigm(w0v[hh] + cw[reg]));
;                     Av[pp * 64 + hk] = sigm(a0v[hh] + ca[reg]); }
;             }
;             LDS_BAR();
;             {
;                 const float kr[8] = {lo_bf(kw.x), hi_bf(kw.x), lo_bf(kw.y), hi_bf(kw.y), lo_bf(kw.z), hi_bf(kw.z), lo_bf(kw.w), hi_bf(kw.w)};
;                 const float rr[8] = {lo_bf(rw.x), hi_bf(rw.x), lo_bf(rw.y), hi_bf(rw.y), lo_bf(rw.z), hi_bf(rw.z), lo_bf(rw.w), hi_bf(rw.w)};
;                 float kq[8]; float ss = 0.f, bon = 0.f;
; #pragma unroll
;                 for (int i = 0; i < 8; ++i) { kq[i] = kr[i] * kkc[i]; ss += kq[i] * kq[i]; bon += rr[i] * kr[i] * rkc[i]; }
.Lrw0_hhc:
	s_cmp_lt_u32 s10, 136
	s_cbranch_scc0 .Lrw0_hlast
	s_xor_b32 s11, s11, 0xcc00
	v_add_u32_e32 v224, s11, v222
	v_add_u32_e32 v225, s11, v223
	v_mov_b32_e32 v202, v230
	s_waitcnt vmcnt(0)
	v_mfma_f32_16x16x32_bf16 v[136:139], v[0:3], v[88:91], 0
	v_mfma_f32_16x16x32_bf16 v[136:139], v[4:7], v[92:95], v[136:139]
	v_mfma_f32_16x16x32_bf16 v[140:143], v[8:11], v[88:91], 0
	v_mfma_f32_16x16x32_bf16 v[140:143], v[12:15], v[92:95], v[140:143]
	v_mfma_f32_16x16x32_bf16 v[144:147], v[16:19], v[96:99], 0
	v_mfma_f32_16x16x32_bf16 v[144:147], v[20:23], v[100:103], v[144:147]
	v_mfma_f32_16x16x32_bf16 v[148:151], v[24:27], v[96:99], 0
	v_mfma_f32_16x16x32_bf16 v[148:151], v[28:31], v[100:103], v[148:151]
	v_lshlrev_b32_e32 v152, 16, v104
	v_and_b32_e32 v153, 0xffff0000, v104
	v_lshlrev_b32_e32 v154, 16, v105
	v_and_b32_e32 v155, 0xffff0000, v105
	v_lshlrev_b32_e32 v156, 16, v106
	v_and_b32_e32 v157, 0xffff0000, v106
	v_lshlrev_b32_e32 v158, 16, v107
	v_and_b32_e32 v159, 0xffff0000, v107
	v_lshlrev_b32_e32 v160, 16, v108
	v_and_b32_e32 v161, 0xffff0000, v108
	v_lshlrev_b32_e32 v162, 16, v109
	v_and_b32_e32 v163, 0xffff0000, v109
	v_lshlrev_b32_e32 v164, 16, v110
	v_and_b32_e32 v165, 0xffff0000, v110
	v_lshlrev_b32_e32 v166, 16, v111
	v_and_b32_e32 v167, 0xffff0000, v111
	v_lshlrev_b32_e32 v168, 16, v112
	v_and_b32_e32 v169, 0xffff0000, v112
	v_lshlrev_b32_e32 v170, 16, v113
	v_and_b32_e32 v171, 0xffff0000, v113
	v_lshlrev_b32_e32 v172, 16, v114
	v_and_b32_e32 v173, 0xffff0000, v114
	v_lshlrev_b32_e32 v174, 16, v115
	v_and_b32_e32 v175, 0xffff0000, v115
	v_lshlrev_b32_e32 v192, 16, v120
	v_and_b32_e32 v193, 0xffff0000, v120
	v_lshlrev_b32_e32 v194, 16, v121
	v_and_b32_e32 v195, 0xffff0000, v121
	v_pk_mul_f32 v[176:177], v[152:153], v[48:49]
	v_pk_mul_f32 v[178:179], v[154:155], v[50:51]
	v_pk_mul_f32 v[180:181], v[156:157], v[52:53]
	v_pk_mul_f32 v[182:183], v[158:159], v[54:55]
	v_pk_mul_f32 v[184:185], v[160:161], v[56:57]
	v_pk_mul_f32 v[186:187], v[162:163], v[58:59]
	v_pk_mul_f32 v[188:189], v[164:165], v[60:61]
	v_pk_mul_f32 v[190:191], v[166:167], v[62:63]
	v_pk_mul_f32 v[196:197], v[176:177], v[176:177]
	v_pk_mul_f32 v[198:199], v[178:179], v[178:179]
	v_pk_fma_f32 v[196:197], v[180:181], v[180:181], v[196:197]
	v_pk_fma_f32 v[198:199], v[182:183], v[182:183], v[198:199]
	v_pk_fma_f32 v[196:197], v[184:185], v[184:185], v[196:197]
	v_pk_fma_f32 v[198:199], v[186:187], v[186:187], v[198:199]
	v_pk_fma_f32 v[196:197], v[188:189], v[188:189], v[196:197]
	v_pk_fma_f32 v[198:199], v[190:191], v[190:191], v[198:199]
	s_nop 0
	v_pk_add_f32 v[196:197], v[196:197], v[198:199]
	s_cmp_eq_u32 s32, 0
	s_cbranch_scc1 .Lrw0_hnbc1
	v_mul_f32_e32 v208, v168, v152
	v_mul_f32_e32 v209, v169, v153
	v_mul_f32_e32 v210, v170, v154
	v_mul_f32_e32 v211, v171, v155
	v_mul_f32_e32 v234, v72, v208
	v_fmac_f32_e32 v234, v73, v209
	v_fmac_f32_e32 v234, v74, v210
	v_fmac_f32_e32 v234, v75, v211
	v_mul_f32_e32 v208, v172, v156
	v_mul_f32_e32 v209, v173, v157
	v_mul_f32_e32 v210, v174, v158
	v_mul_f32_e32 v211, v175, v159
	v_fmac_f32_e32 v234, v76, v208
	v_fmac_f32_e32 v234, v77, v209
	v_fmac_f32_e32 v234, v78, v210
	v_fmac_f32_e32 v234, v79, v211
	v_lshlrev_b32_e32 v204, 16, v116
	v_and_b32_e32 v205, 0xffff0000, v116
	v_lshlrev_b32_e32 v206, 16, v117
	v_and_b32_e32 v207, 0xffff0000, v117
	v_mul_f32_e32 v208, v204, v160
	v_mul_f32_e32 v209, v205, v161
	v_mul_f32_e32 v210, v206, v162
	v_mul_f32_e32 v211, v207, v163
	v_fmac_f32_e32 v234, v80, v208
	v_fmac_f32_e32 v234, v81, v209
	v_fmac_f32_e32 v234, v82, v210
	v_fmac_f32_e32 v234, v83, v211
	v_lshlrev_b32_e32 v204, 16, v118
	v_and_b32_e32 v205, 0xffff0000, v118
	v_lshlrev_b32_e32 v206, 16, v119
	v_and_b32_e32 v207, 0xffff0000, v119
	v_mul_f32_e32 v208, v204, v164
	v_mul_f32_e32 v209, v205, v165
	v_mul_f32_e32 v210, v206, v166
	v_mul_f32_e32 v211, v207, v167
	v_fmac_f32_e32 v234, v84, v208
	v_fmac_f32_e32 v234, v85, v209
	v_fmac_f32_e32 v234, v86, v210
	v_fmac_f32_e32 v234, v87, v211

; __device__ __forceinline__ unsigned xb_ld(unsigned* p)              { return __hip_atomic_load(p, __ATOMIC_RELAXED, __HIP_MEMORY_SCOPE_AGENT); }
; __device__ __forceinline__ unsigned xb_add(unsigned* p, unsigned v) { return __hip_atomic_fetch_add(p, v, __ATOMIC_RELAXED, __HIP_MEMORY_SCOPE_AGENT); }
; #define XB_SPIN(cond, bar) do { unsigned _sp = 0; while (cond) { __builtin_amdgcn_s_sleep(1); \
;     if ((++_sp & 255u) == 0u) { if (xb_ld(&(bar)[XB_TMO])) break; if (_sp > XB_SPIN_CAP) { atomicAdd(&(bar)[XB_TMO], 1u); break; } } } } while (0)
; __device__ __forceinline__ void xcd_barrier(const XcdBarrier& b) {
;     asm volatile("s_waitcnt vmcnt(0)" ::: "memory");
;     __syncthreads();
;     if (threadIdx.x == 0) {
;         unsigned* bar = b.bar;
;         __builtin_amdgcn_s_waitcnt(0);
;         unsigned nloc = b.st[0], nx = b.st[1];
;         if (nloc == 0u) { xcd_barrier_complete(bar, b.x, nloc, nx); b.st[0] = nloc; b.st[1] = nx; }
;         const unsigned old = xb_add(&bar[XB_XSUB(b.x)], 1u);
;         const unsigned gen = old / nloc;
;         if (old + 1u == (gen + 1u) * nloc) {
;             __builtin_amdgcn_fence(__ATOMIC_RELEASE, "agent");
;             asm volatile("s_waitcnt vmcnt(0)" ::: "memory");
;             const unsigned og = xb_add(&bar[XB_TOP], 1u);
;             const unsigned tg = og / nx;
;             if (og + 1u == (tg + 1u) * nx) xb_add(&bar[XB_TOPGEN], 1u);
;             else XB_SPIN(xb_ld(&bar[XB_TOPGEN]) == tg, bar);
;             __builtin_amdgcn_fence(__ATOMIC_ACQUIRE, "agent");
;             xb_add(&bar[XB_XGEN(b.x)], 1u);
;             asm volatile("s_waitcnt vmcnt(0)" ::: "memory");
;         } else {
;             XB_SPIN(xb_ld(&bar[XB_XGEN(b.x)]) == gen, bar);
;             __builtin_amdgcn_fence(__ATOMIC_ACQUIRE, "agent");
;             asm volatile("s_waitcnt vmcnt(0)" ::: "memory");
;         }
;     }
;     __syncthreads();
; }
.Lrw0_hnb1:
	s_waitcnt lgkmcnt(0)
	s_barrier
	s_branch .Lrw0_hhc
.Lrw0_hlast:
	s_barrier
.Lrw0_end:
	v_mov_b32_e32 v1, s34
	v_mov_b32_e32 v2, s35
.LBB0_565:
	s_or_b64 exec, exec, s[12:13]
	v_cmp_gt_i32_e32 vcc, 6, v1
	v_cmp_lt_i32_e64 s[6:7], 6, v2
	s_and_b64 s[8:9], vcc, s[6:7]
	s_and_saveexec_b64 s[6:7], s[8:9]
	s_cbranch_execz .LBB0_619
	s_waitcnt vmcnt(0)
	s_waitcnt vmcnt(0) lgkmcnt(0)
	s_barrier
	s_and_saveexec_b64 s[8:9], s[4:5]
	s_cbranch_execz .LBB0_618
	s_add_i32 s3, 0, 0x20400
	v_mov_b32_e32 v0, s3
	s_waitcnt vmcnt(0) expcnt(0) lgkmcnt(0)
	ds_read_b32 v2, v0
	s_add_i32 s3, 0, 0x20404
	v_mov_b32_e32 v0, s3
	ds_read_b32 v0, v0
	s_waitcnt lgkmcnt(1)
	v_cmp_ne_u32_e32 vcc, 0, v2
	s_cbranch_vccnz .LBB0_582
	s_add_u32 s10, s26, 0x80200
	s_addc_u32 s11, s27, 0
	s_add_u32 s12, s26, 0x80400
	s_addc_u32 s13, s27, 0
	s_add_u32 s14, s26, 0x80500
	s_addc_u32 s15, s27, 0
	s_add_u32 s16, s26, 0x80600
	s_addc_u32 s17, s27, 0
	s_add_u32 s18, s26, 0x80700
	s_addc_u32 s19, s27, 0
	s_add_u32 s20, s26, 0x80800
	s_addc_u32 s21, s27, 0
	s_add_u32 s22, s26, 0x80900
	s_addc_u32 s23, s27, 0
	s_add_u32 s24, s26, 0x80a00
	s_addc_u32 s25, s27, 0
	s_add_u32 s40, s26, 0x80b00
	s_addc_u32 s41, s27, 0
	s_add_u32 s42, s26, 0x80c00
	s_addc_u32 s43, s27, 0
	s_add_u32 s44, s26, 0x80d00
	s_addc_u32 s45, s27, 0
	s_add_u32 s46, s26, 0x80e00
	s_addc_u32 s47, s27, 0
	s_add_u32 s48, s26, 0x80f00
	s_addc_u32 s49, s27, 0
	s_add_u32 s50, s26, 0x81000
	s_addc_u32 s51, s27, 0
	s_add_u32 s52, s26, 0x81100
	s_addc_u32 s53, s27, 0
	s_add_u32 s54, s26, 0x81200
	s_addc_u32 s55, s27, 0
	s_mul_i32 s3, s31, s66
	s_add_u32 s56, s26, 0x81300
	s_mul_i32 s3, s3, s30
	s_addc_u32 s57, s27, 0
	s_mov_b32 s37, 1
	v_mov_b32_e32 v16, 0
	s_branch .LBB0_570

;     __device__ __forceinline__ bf16* R(int i) const { return (bf16*)(ws + OFF_R0 + (size_t)i * RSZ); }
; __device__ __forceinline__ void phase_rwkv_scan(const Fr& F, int jr) {
;     ...
;     const int bxs = (int)blockIdx.x, bxcd = (gridDim.x == 256) ? (bxs & 7) * 32 + (bxs >> 3) : bxs;
;     for (int task = bxcd; task < 256; task += gridDim.x) {
;         const int half = task & 1, h = (task >> 1) & 15, b = (task >> 5) & 3, s = task >> 7;
;         bf16* Yb = F.R(s);
;         const float* w0 = F.a->in[9] + (size_t)(jr * 2 + s) * D + h * 64; const float* a0 = F.a->in[12] + (size_t)(jr * 2 + s) * D + h * 64;
;         const float* kkw = F.a->in[15] + (size_t)jr * D + h * 64; const float* kaw = F.a->in[16] + (size_t)jr * D + h * 64;
;         f32x2 S01 = {0.f, 0.f}, S23 = {0.f, 0.f};
;         const int ks = 4 * l15, rloc = 4 * wave + lq;
;         const int pt = wave & 3, ht0 = (wave >> 2) * 2;
;         const int p1 = pt * 16 + l15;
;     ...
;             {
;                 float* Ypw = Yp + wave * 1024;
;                 unsigned a1 = (unsigned)(size_t)(__attribute__((address_space(3))) float*)(Wv + ks), a2 = (unsigned)(size_t)(__attribute__((address_space(3))) float*)(Rr + ks),
;                          a3 = (unsigned)(size_t)(__attribute__((address_space(3))) float*)(Vv + rloc), a4 = (unsigned)(size_t)(__attribute__((address_space(3))) float*)(Ypw + lane);
;                 asm volatile("" : "+v"(a1), "+v"(a2), "+v"(a3), "+v"(a4));
;                 typedef const __attribute__((address_space(3))) f32x4* lp4; typedef const __attribute__((address_space(3))) float* lp1; typedef __attribute__((address_space(3))) float* lw1;
;                 const lp4 PW = (lp4)a1, PR = (lp4)a2; const lp1 PV = (lp1)a3; const lw1 PY = (lw1)a4;
;                 f32x4 w4 = PW[0], k4 = PW[1024], b4 = PW[2048], d4 = PW[3072], r4 = PR[0];
;                 float vv = PV[0];
.LBB0_2530:
	s_cmp_lt_i32 s34, 26
	s_cselect_b64 s[6:7], -1, 0
	s_cmp_gt_i32 s35, 25
	s_cselect_b64 s[8:9], -1, 0
	s_and_b64 s[6:7], s[6:7], s[8:9]
	s_andn2_b64 vcc, exec, s[6:7]
	s_cbranch_vccnz .LBB0_2542
	s_and_b32 s3, s2, 7
	s_lshl_b32 s3, s3, 5
	s_lshr_b32 s6, s2, 3
	s_add_i32 s3, s3, s6
	s_lshr_b32 s6, s3, 7
	s_bfe_u32 s7, s3, 0x20005
	s_bfe_u32 s8, s3, 0x40001
	s_and_b32 s9, s3, 1
	s_cmp_gt_u32 s68, 3
	s_cbranch_scc1 .Lrw3_helper
	s_setprio 3
	v_mov_b32_e32 v206, 0
	v_mov_b32_e32 v207, 0
	v_mov_b32_e32 v208, 0
	v_mov_b32_e32 v209, 0
	v_mov_b32_e32 v210, 0
	v_mov_b32_e32 v211, 0
	v_mov_b32_e32 v212, 0
	v_mov_b32_e32 v213, 0
	v_and_b32_e32 v243, 15, v130
	v_lshlrev_b32_e32 v214, 4, v243
	v_lshrrev_b32_e32 v244, 4, v130
	v_lshrrev_b32_e32 v245, 3, v243
	v_lshl_add_u32 v245, v244, 1, v245
	s_lshl_b32 s16, s68, 3
	v_add_u32_e32 v245, s16, v245
	v_lshlrev_b32_e32 v216, 3, v245
	s_mul_i32 s16, s68, 0x2400
	s_add_i32 s16, s16, 0x19800
	s_cmp_eq_u32 s68, 3
	s_cselect_b32 s16, 0x20800, s16
	v_mul_u32_u24_e32 v218, 0x90, v130
	v_add_u32_e32 v218, s16, v218
	v_mul_u32_u24_e32 v244, 0x90, v244
	v_lshl_add_u32 v244, v243, 3, v244
	v_add_u32_e32 v217, s16, v244
	v_lshrrev_b32_e32 v219, 2, v130
	s_cmp_eq_u32 s6, 0
	s_cbranch_scc1 .Lrw3_sdir0
	v_sub_u32_e32 v219, 0, v219

;     __device__ __forceinline__ bf16* R(int i) const { return (bf16*)(ws + OFF_R0 + (size_t)i * RSZ); }
; __device__ __forceinline__ void phase_rwkv_scan(const Fr& F, int jr) {
;     ...
;     const int bxs = (int)blockIdx.x, bxcd = (gridDim.x == 256) ? (bxs & 7) * 32 + (bxs >> 3) : bxs;
;     for (int task = bxcd; task < 256; task += gridDim.x) {
;         const int half = task & 1, h = (task >> 1) & 15, b = (task >> 5) & 3, s = task >> 7;
;         bf16* Yb = F.R(s);
;         const float* w0 = F.a->in[9] + (size_t)(jr * 2 + s) * D + h * 64; const float* a0 = F.a->in[12] + (size_t)(jr * 2 + s) * D + h * 64;
;         const float* kkw = F.a->in[15] + (size_t)jr * D + h * 64; const float* kaw = F.a->in[16] + (size_t)jr * D + h * 64;
;         f32x2 S01 = {0.f, 0.f}, S23 = {0.f, 0.f};
;         const int ks = 4 * l15, rloc = 4 * wave + lq;
;         const int pt = wave & 3, ht0 = (wave >> 2) * 2;
;         const int p1 = pt * 16 + l15;
;         const int p2 = tid >> 3, j8 = tid & 7, hk0 = 8 * j8;
;         bf16x8 Bw[2][2], Ba[2][2]; float w0v[2], a0v[2];
; #pragma unroll
;         for (int hh = 0; hh < 2; ++hh) { const int hk = (ht0 + hh) * 16 + l15, e = h * 64 + hk; w0v[hh] = w0[hk]; a0v[hh] = a0[hk];
; #pragma unroll
;             for (int kst = 0; kst < 2; ++kst) { Bw[hh][kst] = *(const bf16x8*)(L2T + ((size_t)s * D + e) * 64 + 32 * kst + 8 * lq); Ba[hh][kst] = *(const bf16x8*)(L2T + ((size_t)(2 + s) * D + e) * 64 + 32 * kst + 8 * lq); } }
;         float kkc[8], kac[8], rkc[8];
; #pragma unroll
;         for (int i = 0; i < 8; ++i) { kkc[i] = kkw[hk0 + i]; kac[i] = kaw[hk0 + i]; rkc[i] = F.a->in[17][(size_t)jr * D + h * 64 + hk0 + i]; }
;         float* Bon = (float*)(F.ws + OFF_R0 + 6 * RSZ + 16 * MiB);
;         bf16x8 Aw[2], Aa[2]; u32x4 kw, rw; u32x2 vw;
;         {   const size_t row1 = (size_t)b * TB + tokof(s, p1), row2 = (size_t)b * TB + tokof(s, p2);
; #pragma unroll
;             for (int kst = 0; kst < 2; ++kst) { Aw[kst] = *(const bf16x8*)(LM + row1 * 256 + 64 * s + 32 * kst + 8 * lq); Aa[kst] = *(const bf16x8*)(LM + row1 * 256 + 128 + 64 * s + 32 * kst + 8 * lq); }
;             kw = *(const u32x4*)(Kb + row2 * D + h * 64 + hk0); rw = *(const u32x4*)(Rb + row2 * D + h * 64 + hk0); vw = *(const u32x2*)(Vb + row2 * D + h * 64 + 32 * half + 4 * j8); }
.Lrw3_hdir0:
	s_mul_i32 s16, s7, 0x1100
	v_lshlrev_b32_e32 v221, 4, v217
	s_lshl_b32 s17, s15, 6
	v_lshl_add_u32 v219, v217, 3, s17
	s_xor_b32 s18, s17, 64
	v_lshl_add_u32 v220, v217, 3, s18
	s_lshl_b32 s17, s15, 7
	v_mul_u32_u24_e32 v197, 0x110, v216
	v_add_u32_e32 v197, s17, v197
	v_lshl_add_u32 v222, v217, 4, v197
	v_lshl_add_u32 v223, v217, 5, v197
	s_lshl_b32 s17, s6, 7
	s_add_u32 s20, s26, 0xde00000
	s_addc_u32 s21, s27, 0
	s_add_u32 s20, s20, s17
	s_addc_u32 s21, s21, 0
	s_lshl_b32 s17, s8, 7
	s_add_u32 s22, s26, 0xbc00000
	s_addc_u32 s23, s27, 0
	s_add_u32 s22, s22, s17
	s_addc_u32 s23, s23, 0
	s_add_u32 s24, s26, 0x9a00000
	s_addc_u32 s25, s27, 0
	s_add_u32 s24, s24, s17
	s_addc_u32 s25, s25, 0
	s_lshl_b32 s18, s9, 6
	s_add_i32 s17, s17, s18
	s_lshl_b32 s18, s15, 5
	s_add_i32 s17, s17, s18
	s_add_u32 s42, s26, 0x5600000
	s_addc_u32 s43, s27, 0
	s_add_u32 s42, s42, s17
	s_addc_u32 s43, s43, 0
	s_lshl_b32 s17, s8, 2
	s_add_u32 s44, s26, 0xee00000
	s_addc_u32 s45, s27, 0
	s_add_u32 s44, s44, s17
	s_addc_u32 s45, s45, 0
	s_or_b32 s17, s6, s9
	s_or_b32 s17, s17, s15
	s_cmp_eq_u32 s17, 0
	s_cselect_b32 s32, 1, 0
	s_load_dwordx2 s[46:47], s[0:1], 0x48
	s_load_dwordx2 s[48:49], s[0:1], 0x60
	s_load_dwordx2 s[50:51], s[0:1], 0x78
	s_load_dwordx2 s[52:53], s[0:1], 0x80
	s_load_dwordx2 s[54:55], s[0:1], 0x88
	s_lshl_b32 s17, s8, 8
	s_lshl_b32 s18, s15, 7
	s_add_i32 s19, s17, s18
	v_lshl_add_u32 v198, v217, 4, s19
	s_xor_b32 s18, s18, 128
	s_add_i32 s19, s17, s18
	v_lshl_add_u32 v199, v217, 4, s19
	s_waitcnt lgkmcnt(0)
	s_lshl_b32 s17, s6, 12
	s_add_u32 s46, s46, s17
	s_addc_u32 s47, s47, 0
	s_add_u32 s48, s48, s17
	s_addc_u32 s49, s49, 0
	s_add_u32 s46, s46, 0x2000
	s_addc_u32 s47, s47, 0
	s_add_u32 s48, s48, 0x2000
	s_addc_u32 s49, s49, 0
	s_add_u32 s50, s50, 0x1000
	s_addc_u32 s51, s51, 0
	s_add_u32 s52, s52, 0x1000
	s_addc_u32 s53, s53, 0
	s_add_u32 s54, s54, 0x1000
	s_addc_u32 s55, s55, 0
	global_load_dwordx4 v[32:35], v198, s[46:47] offset:0
	global_load_dwordx4 v[40:43], v198, s[48:49] offset:0
	global_load_dwordx4 v[64:67], v198, s[52:53] offset:0
	global_load_dwordx4 v[36:39], v198, s[46:47] offset:64
	global_load_dwordx4 v[44:47], v198, s[48:49] offset:64
	global_load_dwordx4 v[68:71], v198, s[52:53] offset:64
	global_load_dwordx4 v[48:51], v198, s[50:51] offset:0
	global_load_dwordx4 v[72:75], v198, s[54:55] offset:0
	global_load_dwordx4 v[52:55], v198, s[50:51] offset:64
	global_load_dwordx4 v[76:79], v198, s[54:55] offset:64
	global_load_dwordx4 v[56:59], v199, s[50:51] offset:0
	global_load_dwordx4 v[80:83], v199, s[54:55] offset:0
	global_load_dwordx4 v[60:63], v199, s[50:51] offset:64
	global_load_dwordx4 v[84:87], v199, s[54:55] offset:64
	s_lshl_b32 s17, s8, 6
	s_lshl_b32 s18, s15, 5
	s_add_i32 s17, s17, s18
	v_add_u32_e32 v200, s17, v196
	v_lshlrev_b32_e32 v200, 7, v200
	v_add_u32_e32 v200, v200, v221
	s_lshl_b32 s17, s6, 17
	s_add_u32 s46, s26, 0x200000
	s_addc_u32 s47, s27, 0
	s_add_u32 s46, s46, s17
	s_addc_u32 s47, s47, 0
	s_add_u32 s48, s46, 0x40000
	s_addc_u32 s49, s47, 0
	global_load_dwordx4 v[0:3], v200, s[46:47] offset:0
	global_load_dwordx4 v[16:19], v200, s[48:49] offset:0
	global_load_dwordx4 v[4:7], v200, s[46:47] offset:64
	global_load_dwordx4 v[20:23], v200, s[48:49] offset:64
	global_load_dwordx4 v[8:11], v200, s[46:47] offset:2048
	global_load_dwordx4 v[24:27], v200, s[48:49] offset:2048
	global_load_dwordx4 v[12:15], v200, s[46:47] offset:2112
	global_load_dwordx4 v[28:31], v200, s[48:49] offset:2112
	s_mov_b32 s10, 0
	s_mov_b32 s11, 0
	s_lshl_b32 s17, s10, 5
	s_cmp_lt_u32 s10, 8
	s_movk_i32 s18, 0x11ff
	s_cselect_b32 s18, 0xff, s18
	s_sub_i32 s18, s18, s17
	s_cmp_eq_u32 s6, 0
	s_cselect_b32 s17, s17, s18
	s_add_i32 s17, s17, s16
	v_add_u32_e32 v231, s17, v218
	v_lshl_add_u32 v226, v231, 9, v221
	v_lshl_add_u32 v227, v231, 11, v219
	v_lshl_add_u32 v228, v231, 11, v220
	v_lshlrev_b32_e32 v229, 3, v217
	v_lshl_add_u32 v229, v231, 11, v229
	v_lshlrev_b32_e32 v230, 6, v231
	global_load_dwordx4 v[88:91], v226, s[20:21]
	global_load_dwordx4 v[92:95], v226, s[20:21] offset:64
	global_load_dwordx4 v[96:99], v226, s[20:21] offset:256
	global_load_dwordx4 v[100:103], v226, s[20:21] offset:320
	global_load_dwordx2 v[104:105], v227, s[22:23] offset:0
	global_load_dwordx2 v[106:107], v227, s[22:23] offset:32
	global_load_dwordx2 v[108:109], v228, s[22:23] offset:0
	global_load_dwordx2 v[110:111], v228, s[22:23] offset:32
	global_load_dwordx2 v[112:113], v227, s[24:25] offset:0
	global_load_dwordx2 v[114:115], v227, s[24:25] offset:32
	global_load_dwordx2 v[116:117], v228, s[24:25] offset:0
	global_load_dwordx2 v[118:119], v228, s[24:25] offset:32
	global_load_dwordx2 v[120:121], v229, s[42:43]
	v_mov_b32_e32 v224, v222
	v_mov_b32_e32 v225, v223
	v_mov_b32_e32 v202, v230
	s_waitcnt vmcnt(0)
; __device__ __forceinline__ float sigm(float x) { return __builtin_amdgcn_rcpf(1.f + __expf(-x)); }
; #define LDS_BAR() asm volatile("s_waitcnt lgkmcnt(0)\n\ts_barrier" ::: "memory")
; __device__ __forceinline__ void phase_rwkv_scan(const Fr& F, int jr) {
;     ...
; #pragma unroll
;             for (int hh = 0; hh < 2; ++hh) {
;                 const int hk = (ht0 + hh) * 16 + l15;
;                 f32x4 cw = {0.f, 0.f, 0.f, 0.f}, ca = {0.f, 0.f, 0.f, 0.f};
; #pragma unroll
;                 for (int kst = 0; kst < 2; ++kst) { cw = __builtin_amdgcn_mfma_f32_16x16x32_bf16(Aw[kst], Bw[hh][kst], cw, 0, 0, 0); ca = __builtin_amdgcn_mfma_f32_16x16x32_bf16(Aa[kst], Ba[hh][kst], ca, 0, 0, 0); }
; #pragma unroll
;                 for (int reg = 0; reg < 4; ++reg) { const int pp = pt * 16 + lq * 4 + reg;
;                     Wv[pp * 64 + hk] = __expf(-0.60653066f * sigm(w0v[hh] + cw[reg]));
;                     Av[pp * 64 + hk] = sigm(a0v[hh] + ca[reg]); }
;             }
;             LDS_BAR();
;             {
;                 const float kr[8] = {lo_bf(kw.x), hi_bf(kw.x), lo_bf(kw.y), hi_bf(kw.y), lo_bf(kw.z), hi_bf(kw.z), lo_bf(kw.w), hi_bf(kw.w)};
;                 const float rr[8] = {lo_bf(rw.x), hi_bf(rw.x), lo_bf(rw.y), hi_bf(rw.y), lo_bf(rw.z), hi_bf(rw.z), lo_bf(rw.w), hi_bf(rw.w)};
;                 float kq[8]; float ss = 0.f, bon = 0.f;
; #pragma unroll
;                 for (int i = 0; i < 8; ++i) { kq[i] = kr[i] * kkc[i]; ss += kq[i] * kq[i]; bon += rr[i] * kr[i] * rkc[i]; }
	v_mfma_f32_16x16x32_bf16 v[136:139], v[0:3], v[88:91], 0
	v_mfma_f32_16x16x32_bf16 v[136:139], v[4:7], v[92:95], v[136:139]
	v_mfma_f32_16x16x32_bf16 v[140:143], v[8:11], v[88:91], 0
	v_mfma_f32_16x16x32_bf16 v[140:143], v[12:15], v[92:95], v[140:143]
	v_mfma_f32_16x16x32_bf16 v[144:147], v[16:19], v[96:99], 0
	v_mfma_f32_16x16x32_bf16 v[144:147], v[20:23], v[100:103], v[144:147]
	v_mfma_f32_16x16x32_bf16 v[148:151], v[24:27], v[96:99], 0
	v_mfma_f32_16x16x32_bf16 v[148:151], v[28:31], v[100:103], v[148:151]
	v_lshlrev_b32_e32 v152, 16, v104
	v_and_b32_e32 v153, 0xffff0000, v104
	v_lshlrev_b32_e32 v154, 16, v105
	v_and_b32_e32 v155, 0xffff0000, v105
	v_lshlrev_b32_e32 v156, 16, v106
	v_and_b32_e32 v157, 0xffff0000, v106
	v_lshlrev_b32_e32 v158, 16, v107
	v_and_b32_e32 v159, 0xffff0000, v107
	v_lshlrev_b32_e32 v160, 16, v108
	v_and_b32_e32 v161, 0xffff0000, v108
	v_lshlrev_b32_e32 v162, 16, v109
	v_and_b32_e32 v163, 0xffff0000, v109
	v_lshlrev_b32_e32 v164, 16, v110
	v_and_b32_e32 v165, 0xffff0000, v110
	v_lshlrev_b32_e32 v166, 16, v111
	v_and_b32_e32 v167, 0xffff0000, v111
	v_lshlrev_b32_e32 v168, 16, v112
	v_and_b32_e32 v169, 0xffff0000, v112
	v_lshlrev_b32_e32 v170, 16, v113
	v_and_b32_e32 v171, 0xffff0000, v113
	v_lshlrev_b32_e32 v172, 16, v114
	v_and_b32_e32 v173, 0xffff0000, v114
	v_lshlrev_b32_e32 v174, 16, v115
	v_and_b32_e32 v175, 0xffff0000, v115
	v_lshlrev_b32_e32 v192, 16, v120
	v_and_b32_e32 v193, 0xffff0000, v120
	v_lshlrev_b32_e32 v194, 16, v121
	v_and_b32_e32 v195, 0xffff0000, v121
	v_pk_mul_f32 v[176:177], v[152:153], v[48:49]
	v_pk_mul_f32 v[178:179], v[154:155], v[50:51]
	v_pk_mul_f32 v[180:181], v[156:157], v[52:53]
	v_pk_mul_f32 v[182:183], v[158:159], v[54:55]
	v_pk_mul_f32 v[184:185], v[160:161], v[56:57]
	v_pk_mul_f32 v[186:187], v[162:163], v[58:59]
	v_pk_mul_f32 v[188:189], v[164:165], v[60:61]
	v_pk_mul_f32 v[190:191], v[166:167], v[62:63]
	v_pk_mul_f32 v[196:197], v[176:177], v[176:177]
	v_pk_mul_f32 v[198:199], v[178:179], v[178:179]
	v_pk_fma_f32 v[196:197], v[180:181], v[180:181], v[196:197]
	v_pk_fma_f32 v[198:199], v[182:183], v[182:183], v[198:199]
	v_pk_fma_f32 v[196:197], v[184:185], v[184:185], v[196:197]
	v_pk_fma_f32 v[198:199], v[186:187], v[186:187], v[198:199]
	v_pk_fma_f32 v[196:197], v[188:189], v[188:189], v[196:197]
	v_pk_fma_f32 v[198:199], v[190:191], v[190:191], v[198:199]
	s_nop 0
	v_pk_add_f32 v[196:197], v[196:197], v[198:199]
	s_cmp_eq_u32 s32, 0
	s_cbranch_scc1 .Lrw3_hnbc0
	v_mul_f32_e32 v208, v168, v152
	v_mul_f32_e32 v209, v169, v153
	v_mul_f32_e32 v210, v170, v154
	v_mul_f32_e32 v211, v171, v155
	v_mul_f32_e32 v234, v72, v208
	v_fmac_f32_e32 v234, v73, v209
	v_fmac_f32_e32 v234, v74, v210
	v_fmac_f32_e32 v234, v75, v211
	v_mul_f32_e32 v208, v172, v156
	v_mul_f32_e32 v209, v173, v157
	v_mul_f32_e32 v210, v174, v158
	v_mul_f32_e32 v211, v175, v159
	v_fmac_f32_e32 v234, v76, v208
	v_fmac_f32_e32 v234, v77, v209
	v_fmac_f32_e32 v234, v78, v210
	v_fmac_f32_e32 v234, v79, v211
	v_lshlrev_b32_e32 v204, 16, v116
	v_and_b32_e32 v205, 0xffff0000, v116
	v_lshlrev_b32_e32 v206, 16, v117
	v_and_b32_e32 v207, 0xffff0000, v117
	v_mul_f32_e32 v208, v204, v160
	v_mul_f32_e32 v209, v205, v161
	v_mul_f32_e32 v210, v206, v162
	v_mul_f32_e32 v211, v207, v163
	v_fmac_f32_e32 v234, v80, v208
	v_fmac_f32_e32 v234, v81, v209
	v_fmac_f32_e32 v234, v82, v210
	v_fmac_f32_e32 v234, v83, v211
	v_lshlrev_b32_e32 v204, 16, v118
	v_and_b32_e32 v205, 0xffff0000, v118
	v_lshlrev_b32_e32 v206, 16, v119
	v_and_b32_e32 v207, 0xffff0000, v119
	v_mul_f32_e32 v208, v204, v164
	v_mul_f32_e32 v209, v205, v165
	v_mul_f32_e32 v210, v206, v166
	v_mul_f32_e32 v211, v207, v167
	v_fmac_f32_e32 v234, v84, v208
	v_fmac_f32_e32 v234, v85, v209
	v_fmac_f32_e32 v234, v86, v210
	v_fmac_f32_e32 v234, v87, v211

; __device__ __forceinline__ unsigned xb_ld(unsigned* p)              { return __hip_atomic_load(p, __ATOMIC_RELAXED, __HIP_MEMORY_SCOPE_AGENT); }
; __device__ __forceinline__ unsigned xb_add(unsigned* p, unsigned v) { return __hip_atomic_fetch_add(p, v, __ATOMIC_RELAXED, __HIP_MEMORY_SCOPE_AGENT); }
; #define XB_SPIN(cond, bar) do { unsigned _sp = 0; while (cond) { __builtin_amdgcn_s_sleep(1); \
;     if ((++_sp & 255u) == 0u) { if (xb_ld(&(bar)[XB_TMO])) break; if (_sp > XB_SPIN_CAP) { atomicAdd(&(bar)[XB_TMO], 1u); break; } } } } while (0)
; __device__ __forceinline__ void xcd_barrier(const XcdBarrier& b) {
;     asm volatile("s_waitcnt vmcnt(0)" ::: "memory");
;     __syncthreads();
;     if (threadIdx.x == 0) {
;         unsigned* bar = b.bar;
;         __builtin_amdgcn_s_waitcnt(0);
;         unsigned nloc = b.st[0], nx = b.st[1];
;         if (nloc == 0u) { xcd_barrier_complete(bar, b.x, nloc, nx); b.st[0] = nloc; b.st[1] = nx; }
;         const unsigned old = xb_add(&bar[XB_XSUB(b.x)], 1u);
;         const unsigned gen = old / nloc;
;         if (old + 1u == (gen + 1u) * nloc) {
;             __builtin_amdgcn_fence(__ATOMIC_RELEASE, "agent");
;             asm volatile("s_waitcnt vmcnt(0)" ::: "memory");
;             const unsigned og = xb_add(&bar[XB_TOP], 1u);
;             const unsigned tg = og / nx;
;             if (og + 1u == (tg + 1u) * nx) xb_add(&bar[XB_TOPGEN], 1u);
;             else XB_SPIN(xb_ld(&bar[XB_TOPGEN]) == tg, bar);
;             __builtin_amdgcn_fence(__ATOMIC_ACQUIRE, "agent");
;             xb_add(&bar[XB_XGEN(b.x)], 1u);
;             asm volatile("s_waitcnt vmcnt(0)" ::: "memory");
;         } else {
;             XB_SPIN(xb_ld(&bar[XB_XGEN(b.x)]) == gen, bar);
;             __builtin_amdgcn_fence(__ATOMIC_ACQUIRE, "agent");
;             asm volatile("s_waitcnt vmcnt(0)" ::: "memory");
;         }
;     }
;     __syncthreads();
; }
.Lrw3_end:
.LBB0_2542:
	s_cmp_lt_i32 s34, 26
	s_cselect_b64 s[6:7], -1, 0
	s_cmp_gt_i32 s35, 26
	s_cselect_b64 s[8:9], -1, 0
	s_and_b64 s[6:7], s[6:7], s[8:9]
	s_andn2_b64 vcc, exec, s[6:7]
	s_cbranch_vccnz .LBB0_2596
	s_waitcnt vmcnt(0)
	s_waitcnt vmcnt(0) lgkmcnt(0)
	s_barrier
	s_and_saveexec_b64 s[6:7], s[4:5]
	s_cbranch_execz .LBB0_2595
	s_add_i32 s3, 0, 0x20400
	v_mov_b32_e32 v0, s3
	s_waitcnt vmcnt(0) expcnt(0) lgkmcnt(0)
	ds_read_b32 v2, v0
	s_add_i32 s3, 0, 0x20404
	v_mov_b32_e32 v0, s3
	ds_read_b32 v0, v0
	s_waitcnt lgkmcnt(1)
	v_cmp_ne_u32_e32 vcc, 0, v2
	s_cbranch_vccnz .LBB0_2559
	s_add_u32 s8, s26, 0x80200
	s_addc_u32 s9, s27, 0
	s_add_u32 s10, s26, 0x80400
	s_addc_u32 s11, s27, 0
	s_add_u32 s12, s26, 0x80500
	s_addc_u32 s13, s27, 0
	s_add_u32 s14, s26, 0x80600
	s_addc_u32 s15, s27, 0
	s_add_u32 s16, s26, 0x80700
	s_addc_u32 s17, s27, 0
	s_add_u32 s18, s26, 0x80800
	s_addc_u32 s19, s27, 0
	s_add_u32 s20, s26, 0x80900
	s_addc_u32 s21, s27, 0
	s_add_u32 s22, s26, 0x80a00
	s_addc_u32 s23, s27, 0
	s_add_u32 s24, s26, 0x80b00
	s_addc_u32 s25, s27, 0
	s_add_u32 s38, s26, 0x80c00
	s_addc_u32 s39, s27, 0
	s_add_u32 s42, s26, 0x80d00
	s_addc_u32 s43, s27, 0
	s_add_u32 s44, s26, 0x80e00
	s_addc_u32 s45, s27, 0
	s_add_u32 s46, s26, 0x80f00
	s_addc_u32 s47, s27, 0
	s_add_u32 s48, s26, 0x81000
	s_addc_u32 s49, s27, 0
	s_add_u32 s50, s26, 0x81100
	s_addc_u32 s51, s27, 0
	s_add_u32 s52, s26, 0x81200
	s_addc_u32 s53, s27, 0
	s_mul_i32 s3, s31, s66
	s_add_u32 s54, s26, 0x81300
	s_mul_i32 s3, s3, s30
	s_addc_u32 s55, s27, 0
	s_mov_b32 s37, 1
	v_mov_b32_e32 v16, 0
	s_branch .LBB0_2547
